# v96 + PLE epilogue phase 8: bf16 output copy stored as 16-byte stores via v_permlane16_swap (single staging set), prefetch vmcnt counts lowered accordingly
# speedup vs baseline: 1.0172x; 1.0029x over previous
.LBB0_621:
	s_mul_i32 s57, s9, 0x6000
	s_add_i32 s58, s57, 0xffffa000
	s_cmp_lg_u32 s9, 0
	s_cselect_b32 s58, s58, 0xc000
	v_add_u32_e32 v143, s58, v138
	v_lshl_add_u64 v[144:145], v[132:133], 0, s[6:7]
	v_readfirstlane_b32 s58, v143
	v_add_u32_e32 v148, 0x1000, v143
	v_lshl_add_u64 v[146:147], v[144:145], 0, s[44:45]
	s_mov_b32 m0, s58
	v_readfirstlane_b32 s58, v148
	v_add_u32_e32 v148, 0x2000, v143
	s_waitcnt vmcnt(6)
	s_barrier
	global_load_lds_dwordx4 v[146:147], off
	v_lshl_add_u64 v[146:147], v[144:145], 0, s[46:47]
	s_mov_b32 m0, s58
	v_readfirstlane_b32 s58, v148
	global_load_lds_dwordx4 v[146:147], off
	v_lshl_add_u64 v[146:147], v[144:145], 0, s[48:49]
	s_mov_b32 m0, s58
	v_lshl_add_u64 v[144:145], v[144:145], 0, s[50:51]
	global_load_lds_dwordx4 v[146:147], off
	v_add_u32_e32 v146, 0x3000, v143
	v_add_u32_e32 v148, 0x4000, v143
	v_readfirstlane_b32 s58, v146
	s_mov_b32 m0, s58
	v_readfirstlane_b32 s58, v148
	global_load_lds_dwordx4 v[144:145], off
	v_lshl_add_u64 v[144:145], v[130:131], 0, s[6:7]
	v_add_u32_e32 v143, 0x5000, v143
	v_lshl_add_u64 v[146:147], v[144:145], 0, s[52:53]
	s_mov_b32 m0, s58
	v_readfirstlane_b32 s58, v143
	global_load_lds_dwordx4 v[146:147], off
	v_lshl_add_u64 v[144:145], v[144:145], 0, s[54:55]
	s_mov_b32 m0, s58
	s_add_i32 s57, s57, 0
	global_load_lds_dwordx4 v[144:145], off
	v_add3_u32 v143, s57, v140, v142
	ds_read_b128 v[144:147], v143 offset:16384
	ds_read_b128 v[148:151], v143 offset:17408
	ds_read_b128 v[156:159], v143 offset:18432
	ds_read_b128 v[160:163], v143 offset:19456
	v_add3_u32 v143, s57, v141, v142
	ds_read_b128 v[164:167], v143
	ds_read_b128 v[168:171], v143 offset:1024
	ds_read_b128 v[172:175], v143 offset:2048
	ds_read_b128 v[176:179], v143 offset:3072
	s_setprio 1
	s_waitcnt lgkmcnt(0)
	v_mfma_f32_16x16x32_bf16 v[126:129], v[144:147], v[164:167], v[126:129]
	v_mfma_f32_16x16x32_bf16 v[122:125], v[148:151], v[164:167], v[122:125]
	v_mfma_f32_16x16x32_bf16 v[118:121], v[156:159], v[164:167], v[118:121]
	v_mfma_f32_16x16x32_bf16 v[114:117], v[160:163], v[164:167], v[114:117]
	v_mfma_f32_16x16x32_bf16 v[110:113], v[144:147], v[168:171], v[110:113]
	v_mfma_f32_16x16x32_bf16 v[106:109], v[148:151], v[168:171], v[106:109]
	v_mfma_f32_16x16x32_bf16 v[102:105], v[156:159], v[168:171], v[102:105]
	v_mfma_f32_16x16x32_bf16 v[98:101], v[160:163], v[168:171], v[98:101]
	v_mfma_f32_16x16x32_bf16 v[94:97], v[144:147], v[172:175], v[94:97]
	v_mfma_f32_16x16x32_bf16 v[90:93], v[148:151], v[172:175], v[90:93]
	v_mfma_f32_16x16x32_bf16 v[86:89], v[156:159], v[172:175], v[86:89]
	v_mfma_f32_16x16x32_bf16 v[82:85], v[160:163], v[172:175], v[82:85]
	v_mfma_f32_16x16x32_bf16 v[78:81], v[144:147], v[176:179], v[78:81]
	v_mfma_f32_16x16x32_bf16 v[74:77], v[148:151], v[176:179], v[74:77]
	v_mfma_f32_16x16x32_bf16 v[70:73], v[156:159], v[176:179], v[70:73]
	v_mfma_f32_16x16x32_bf16 v[66:69], v[160:163], v[176:179], v[66:69]
	s_setprio 0
	ds_read_b128 v[164:167], v143 offset:4096
	ds_read_b128 v[168:171], v143 offset:5120
	ds_read_b128 v[172:175], v143 offset:6144
	ds_read_b128 v[176:179], v143 offset:7168
	s_setprio 1
	s_waitcnt lgkmcnt(0)
	v_mfma_f32_16x16x32_bf16 v[62:65], v[144:147], v[164:167], v[62:65]
	v_mfma_f32_16x16x32_bf16 v[58:61], v[148:151], v[164:167], v[58:61]
	v_mfma_f32_16x16x32_bf16 v[54:57], v[156:159], v[164:167], v[54:57]
	v_mfma_f32_16x16x32_bf16 v[50:53], v[160:163], v[164:167], v[50:53]
	v_mfma_f32_16x16x32_bf16 v[46:49], v[144:147], v[168:171], v[46:49]
	v_mfma_f32_16x16x32_bf16 v[42:45], v[148:151], v[168:171], v[42:45]
	v_mfma_f32_16x16x32_bf16 v[38:41], v[156:159], v[168:171], v[38:41]
	v_mfma_f32_16x16x32_bf16 v[34:37], v[160:163], v[168:171], v[34:37]
	v_mfma_f32_16x16x32_bf16 v[30:33], v[144:147], v[172:175], v[30:33]
	v_mfma_f32_16x16x32_bf16 v[26:29], v[148:151], v[172:175], v[26:29]
	v_mfma_f32_16x16x32_bf16 v[22:25], v[156:159], v[172:175], v[22:25]
	v_mfma_f32_16x16x32_bf16 v[18:21], v[160:163], v[172:175], v[18:21]
	v_mfma_f32_16x16x32_bf16 v[14:17], v[144:147], v[176:179], v[14:17]
	v_mfma_f32_16x16x32_bf16 v[10:13], v[148:151], v[176:179], v[10:13]
	v_mfma_f32_16x16x32_bf16 v[6:9], v[156:159], v[176:179], v[6:9]
	v_mfma_f32_16x16x32_bf16 v[2:5], v[160:163], v[176:179], v[2:5]
	s_setprio 0
	s_add_i32 s57, s9, 1
	s_cmp_lg_u32 s9, 2
	s_cselect_b32 s9, s57, 0
	s_add_u32 s6, s6, 64
	s_addc_u32 s7, s7, 0
	s_cmpk_eq_i32 s6, 0x780
	s_cbranch_scc0 .LBB0_621
	v_add3_u32 v138, 0, v140, v142
	v_add3_u32 v155, 0, v141, v142
	s_waitcnt vmcnt(6)
	s_barrier
	ds_read_b128 v[130:133], v138 offset:16384
	ds_read_b128 v[144:147], v138 offset:17408
	ds_read_b128 v[148:151], v138 offset:18432
	ds_read_b128 v[156:159], v138 offset:19456
	ds_read_b128 v[140:143], v155
	ds_read_b128 v[160:163], v155 offset:1024
	ds_read_b128 v[164:167], v155 offset:2048
	ds_read_b128 v[168:171], v155 offset:3072
	s_setprio 1
	s_waitcnt lgkmcnt(0)
	v_mfma_f32_16x16x32_bf16 v[126:129], v[130:133], v[140:143], v[126:129]
	v_mfma_f32_16x16x32_bf16 v[114:117], v[156:159], v[140:143], v[114:117]
	v_mfma_f32_16x16x32_bf16 v[110:113], v[130:133], v[160:163], v[110:113]
	v_mfma_f32_16x16x32_bf16 v[106:109], v[144:147], v[160:163], v[106:109]
	v_mfma_f32_16x16x32_bf16 v[102:105], v[148:151], v[160:163], v[102:105]
	v_mfma_f32_16x16x32_bf16 v[98:101], v[156:159], v[160:163], v[98:101]
	v_mfma_f32_16x16x32_bf16 v[94:97], v[130:133], v[164:167], v[94:97]
	v_mfma_f32_16x16x32_bf16 v[90:93], v[144:147], v[164:167], v[90:93]
	v_mfma_f32_16x16x32_bf16 v[86:89], v[148:151], v[164:167], v[86:89]
	v_mfma_f32_16x16x32_bf16 v[82:85], v[156:159], v[164:167], v[82:85]
	v_mfma_f32_16x16x32_bf16 v[78:81], v[130:133], v[168:171], v[78:81]
	v_mfma_f32_16x16x32_bf16 v[74:77], v[144:147], v[168:171], v[74:77]
	v_mfma_f32_16x16x32_bf16 v[70:73], v[148:151], v[168:171], v[70:73]
	v_mfma_f32_16x16x32_bf16 v[66:69], v[156:159], v[168:171], v[66:69]
	v_mfma_f32_16x16x32_bf16 v[122:125], v[144:147], v[140:143], v[122:125]
	v_mfma_f32_16x16x32_bf16 v[118:121], v[148:151], v[140:143], v[118:121]
	s_setprio 0
	ds_read_b128 v[140:143], v155 offset:4096
	ds_read_b128 v[160:163], v155 offset:5120
	ds_read_b128 v[164:167], v155 offset:6144
	ds_read_b128 v[168:171], v155 offset:7168
	s_setprio 1
	s_waitcnt lgkmcnt(0)
	v_mfma_f32_16x16x32_bf16 v[62:65], v[130:133], v[140:143], v[62:65]
	v_mfma_f32_16x16x32_bf16 v[58:61], v[144:147], v[140:143], v[58:61]
	v_mfma_f32_16x16x32_bf16 v[54:57], v[148:151], v[140:143], v[54:57]
	v_mfma_f32_16x16x32_bf16 v[50:53], v[156:159], v[140:143], v[50:53]
	v_mfma_f32_16x16x32_bf16 v[46:49], v[130:133], v[160:163], v[46:49]
	v_mfma_f32_16x16x32_bf16 v[42:45], v[144:147], v[160:163], v[42:45]
	v_mfma_f32_16x16x32_bf16 v[38:41], v[148:151], v[160:163], v[38:41]
	v_mfma_f32_16x16x32_bf16 v[34:37], v[156:159], v[160:163], v[34:37]
	v_mfma_f32_16x16x32_bf16 v[30:33], v[130:133], v[164:167], v[30:33]
	v_mfma_f32_16x16x32_bf16 v[26:29], v[144:147], v[164:167], v[26:29]
	v_mfma_f32_16x16x32_bf16 v[22:25], v[148:151], v[164:167], v[22:25]
	v_mfma_f32_16x16x32_bf16 v[18:21], v[156:159], v[164:167], v[18:21]
	v_mfma_f32_16x16x32_bf16 v[14:17], v[130:133], v[168:171], v[14:17]
	v_mfma_f32_16x16x32_bf16 v[10:13], v[144:147], v[168:171], v[10:13]
	v_mfma_f32_16x16x32_bf16 v[6:9], v[148:151], v[168:171], v[6:9]
	v_mfma_f32_16x16x32_bf16 v[2:5], v[156:159], v[168:171], v[2:5]
	s_setprio 0
	s_waitcnt vmcnt(0)
	s_barrier
	ds_read_b128 v[130:133], v138 offset:40960
	ds_read_b128 v[140:143], v138 offset:41984
	ds_read_b128 v[144:147], v138 offset:43008
	ds_read_b128 v[148:151], v138 offset:44032
	ds_read_b128 v[156:159], v155 offset:24576
	ds_read_b128 v[160:163], v155 offset:25600
	ds_read_b128 v[164:167], v155 offset:26624
	ds_read_b128 v[168:171], v155 offset:27648
	s_lshl_b64 s[4:5], s[4:5], 8
	s_setprio 1
	s_waitcnt lgkmcnt(0)
	v_mfma_f32_16x16x32_bf16 v[172:175], v[130:133], v[156:159], v[126:129]
	v_mfma_f32_16x16x32_bf16 v[126:129], v[140:143], v[156:159], v[122:125]
	v_mfma_f32_16x16x32_bf16 v[114:117], v[148:151], v[156:159], v[114:117]
	v_mfma_f32_16x16x32_bf16 v[110:113], v[130:133], v[160:163], v[110:113]
	v_mfma_f32_16x16x32_bf16 v[106:109], v[140:143], v[160:163], v[106:109]
	v_mfma_f32_16x16x32_bf16 v[102:105], v[144:147], v[160:163], v[102:105]
	v_mfma_f32_16x16x32_bf16 v[98:101], v[148:151], v[160:163], v[98:101]
	v_mfma_f32_16x16x32_bf16 v[94:97], v[130:133], v[164:167], v[94:97]
	v_mfma_f32_16x16x32_bf16 v[90:93], v[140:143], v[164:167], v[90:93]
	v_mfma_f32_16x16x32_bf16 v[86:89], v[144:147], v[164:167], v[86:89]
	v_mfma_f32_16x16x32_bf16 v[82:85], v[148:151], v[164:167], v[82:85]
	v_mfma_f32_16x16x32_bf16 v[78:81], v[130:133], v[168:171], v[78:81]
	v_mfma_f32_16x16x32_bf16 v[74:77], v[140:143], v[168:171], v[74:77]
	v_mfma_f32_16x16x32_bf16 v[70:73], v[144:147], v[168:171], v[70:73]
	v_mfma_f32_16x16x32_bf16 v[66:69], v[148:151], v[168:171], v[66:69]
	v_mfma_f32_16x16x32_bf16 v[122:125], v[144:147], v[156:159], v[118:121]
	s_setprio 0
	s_nop 1
	ds_read_b128 v[118:121], v155 offset:28672
	ds_read_b128 v[156:159], v155 offset:29696
	ds_read_b128 v[160:163], v155 offset:30720
	ds_read_b128 v[164:167], v155 offset:31744
	s_setprio 1
	s_waitcnt lgkmcnt(0)
	v_mfma_f32_16x16x32_bf16 v[62:65], v[130:133], v[118:121], v[62:65]
	v_mfma_f32_16x16x32_bf16 v[58:61], v[140:143], v[118:121], v[58:61]
	v_mfma_f32_16x16x32_bf16 v[54:57], v[144:147], v[118:121], v[54:57]
	v_mfma_f32_16x16x32_bf16 v[50:53], v[148:151], v[118:121], v[50:53]
	v_mfma_f32_16x16x32_bf16 v[46:49], v[130:133], v[156:159], v[46:49]
	v_mfma_f32_16x16x32_bf16 v[42:45], v[140:143], v[156:159], v[42:45]
	v_mfma_f32_16x16x32_bf16 v[38:41], v[144:147], v[156:159], v[38:41]
	v_mfma_f32_16x16x32_bf16 v[34:37], v[148:151], v[156:159], v[34:37]
	v_mfma_f32_16x16x32_bf16 v[30:33], v[130:133], v[160:163], v[30:33]
	v_mfma_f32_16x16x32_bf16 v[26:29], v[140:143], v[160:163], v[26:29]
	v_mfma_f32_16x16x32_bf16 v[22:25], v[144:147], v[160:163], v[22:25]
	v_mfma_f32_16x16x32_bf16 v[18:21], v[148:151], v[160:163], v[18:21]
	v_mfma_f32_16x16x32_bf16 v[14:17], v[130:133], v[164:167], v[14:17]
	v_mfma_f32_16x16x32_bf16 v[10:13], v[140:143], v[164:167], v[10:13]
	v_mfma_f32_16x16x32_bf16 v[6:9], v[144:147], v[164:167], v[6:9]
	v_mfma_f32_16x16x32_bf16 v[2:5], v[148:151], v[164:167], v[2:5]
	s_setprio 0
	v_lshl_add_u64 v[140:141], s[4:5], 0, v[136:137]
	v_lshl_add_u64 v[118:119], v[140:141], 2, s[18:19]
	s_waitcnt vmcnt(0)
	s_barrier
	v_mov_b32_e32 v234, v118
	v_mov_b32_e32 v235, v119
	global_load_dword v228, v[234:235], off
	v_lshl_or_b32 v132, s8, 7, v152
	v_lshlrev_b64 v[118:119], 11, v[140:141]
	v_lshl_add_u64 v[120:121], s[14:15], 0, v[118:119]
	v_lshlrev_b32_e32 v142, 1, v132
	v_mov_b32_e32 v143, v139
	v_lshl_add_u64 v[148:149], v[120:121], 0, v[142:143]
	v_lshlrev_b64 v[120:121], 12, v[140:141]
	v_lshlrev_b32_e32 v138, 2, v132
	v_lshl_add_u64 v[120:121], v[134:135], 0, v[120:121]
	s_nop 0
	v_lshl_add_u64 v[144:145], v[120:121], 0, v[138:139]
	v_lshl_add_u64 v[132:133], s[16:17], 0, v[118:119]
	v_mov_b32_e32 v230, v144
	v_mov_b32_e32 v231, v145
	v_mov_b32_e32 v232, v148
	v_mov_b32_e32 v233, v149
	global_load_dwordx4 v[180:183], v[230:231], off
	global_load_dwordx4 v[184:187], v[230:231], off offset:64
	global_load_dwordx4 v[188:191], v[230:231], off offset:128
	global_load_dwordx4 v[192:195], v[230:231], off offset:192
	global_load_dwordx2 v[196:197], v[232:233], off
	global_load_dwordx2 v[198:199], v[232:233], off offset:32
	global_load_dwordx2 v[200:201], v[232:233], off offset:64
	global_load_dwordx2 v[202:203], v[232:233], off offset:96
	s_mov_b32 s99, 0
	s_mov_b32 s98, 0x10000
	v_lshl_add_u64 v[236:237], v[230:231], 0, s[98:99]
	global_load_dwordx4 v[204:207], v[236:237], off
	global_load_dwordx4 v[208:211], v[236:237], off offset:64
	global_load_dwordx4 v[212:215], v[236:237], off offset:128
	global_load_dwordx4 v[216:219], v[236:237], off offset:192
	s_mov_b32 s98, 0x8000
	v_lshl_add_u64 v[236:237], v[232:233], 0, s[98:99]
	global_load_dwordx2 v[220:221], v[236:237], off
	global_load_dwordx2 v[222:223], v[236:237], off offset:32
	global_load_dwordx2 v[224:225], v[236:237], off offset:64
	global_load_dwordx2 v[226:227], v[236:237], off offset:96
	s_mov_b32 s98, 0x40
	v_lshl_add_u64 v[236:237], v[234:235], 0, s[98:99]
	global_load_dword v229, v[236:237], off
	v_lshl_add_u64 v[146:147], v[132:133], 0, v[142:143]
	s_waitcnt vmcnt(9) lgkmcnt(0)
	v_mov_b32_e32 v150, v228
	v_mov_b32_e32 v130, v196
	v_mov_b32_e32 v131, v197
	v_mov_b32_e32 v118, v180
	v_mov_b32_e32 v119, v181
	v_mov_b32_e32 v120, v182
	v_mov_b32_e32 v121, v183
	v_fmamk_f32 v132, v150, 0x3a800000, v153
	v_mul_f32_e32 v133, 0x4b800000, v132
	v_cmp_gt_f32_e32 vcc, s56, v132
	s_nop 1
	v_cndmask_b32_e32 v132, v132, v133, vcc
	v_rsq_f32_e32 v150, v132
	v_lshlrev_b32_e32 v132, 16, v130
	v_mul_f32_e32 v151, 0x45800000, v150
	v_cndmask_b32_e32 v155, v150, v151, vcc
	v_mul_f32_e32 v150, v172, v155
	v_mul_f32_e32 v151, v173, v155
	v_mul_f32_e32 v150, 0xbfb8aa3b, v150
	v_mul_f32_e32 v151, 0xbfb8aa3b, v151
	v_mul_f32_e32 v156, v174, v155
	v_mul_f32_e32 v157, v175, v155
	v_exp_f32_e32 v150, v150
	v_exp_f32_e32 v151, v151
	v_mul_f32_e32 v156, 0xbfb8aa3b, v156
	v_mul_f32_e32 v157, 0xbfb8aa3b, v157
	v_exp_f32_e32 v156, v156
	v_exp_f32_e32 v157, v157
	v_pk_add_f32 v[150:151], v[150:151], 1.0 op_sel_hi:[1,0]
	v_and_b32_e32 v133, 0xffff0000, v130
	v_div_scale_f32 v158, s[4:5], v151, v151, 1.0
	v_pk_add_f32 v[156:157], v[156:157], 1.0 op_sel_hi:[1,0]
	v_div_scale_f32 v160, s[4:5], v150, v150, 1.0
	v_rcp_f32_e32 v166, v158
	v_div_scale_f32 v162, s[6:7], v157, v157, 1.0
	v_rcp_f32_e32 v167, v160
	v_div_scale_f32 v164, s[8:9], v156, v156, 1.0
	v_rcp_f32_e32 v168, v162
	v_rcp_f32_e32 v169, v164
	v_fma_f32 v170, -v158, v166, 1.0
	v_div_scale_f32 v159, vcc, 1.0, v151, 1.0
	v_fma_f32 v171, -v160, v167, 1.0
	v_fmac_f32_e32 v166, v170, v166
	v_div_scale_f32 v161, s[4:5], 1.0, v150, 1.0
	v_fma_f32 v172, -v162, v168, 1.0
	v_fmac_f32_e32 v167, v171, v167
	v_mul_f32_e32 v170, v159, v166
	v_div_scale_f32 v163, s[6:7], 1.0, v157, 1.0
	v_fma_f32 v173, -v164, v169, 1.0
	v_fmac_f32_e32 v168, v172, v168
	v_mul_f32_e32 v171, v161, v167
	v_fma_f32 v174, -v158, v170, v159
	v_div_scale_f32 v165, s[8:9], 1.0, v156, 1.0
	v_fmac_f32_e32 v169, v173, v169
	v_mul_f32_e32 v172, v163, v168
	v_fma_f32 v175, -v160, v171, v161
	v_fmac_f32_e32 v170, v174, v166
	v_mul_f32_e32 v173, v165, v169
	v_fma_f32 v176, -v162, v172, v163
	v_fmac_f32_e32 v171, v175, v167
	v_fma_f32 v158, -v158, v170, v159
	v_fma_f32 v177, -v164, v173, v165
	v_fmac_f32_e32 v172, v176, v168
	v_fma_f32 v159, -v160, v171, v161
	v_div_fmas_f32 v158, v158, v166, v170
	s_mov_b64 vcc, s[4:5]
	v_fmac_f32_e32 v173, v177, v169
	v_fma_f32 v160, -v162, v172, v163
	v_div_fixup_f32 v151, v158, v151, 1.0
	v_div_fmas_f32 v158, v159, v167, v171
	s_mov_b64 vcc, s[6:7]
	v_fma_f32 v161, -v164, v173, v165
	v_div_fixup_f32 v150, v158, v150, 1.0
	v_div_fmas_f32 v158, v160, v168, v172
	s_mov_b64 vcc, s[8:9]
	v_pk_fma_f32 v[118:119], v[150:151], v[132:133], v[118:119]
	v_div_fmas_f32 v132, v161, v169, v173
	v_lshlrev_b32_e32 v130, 16, v131
	v_and_b32_e32 v131, 0xffff0000, v131
	v_div_fixup_f32 v133, v158, v157, 1.0
	v_div_fixup_f32 v132, v132, v156, 1.0
	v_pk_fma_f32 v[120:121], v[132:133], v[130:131], v[120:121]
	global_store_dwordx4 v[144:145], v[118:121], off
	v_cvt_pk_bf16_f32 v130, v118, v119
	v_cvt_pk_bf16_f32 v131, v120, v121
	s_nop 0
	v_mul_f32_e32 v126, v126, v155
	v_mov_b32_e32 v238, v130
	v_mov_b32_e32 v239, v131
	s_nop 0
	v_mul_f32_e32 v127, v127, v155
	v_mul_f32_e32 v128, v128, v155
	v_mul_f32_e32 v129, v129, v155
	v_mul_f32_e32 v156, v122, v155
	v_mul_f32_e32 v157, v123, v155
	v_mul_f32_e32 v122, 0xbfb8aa3b, v126
	v_mul_f32_e32 v123, 0xbfb8aa3b, v127
	v_mul_f32_e32 v158, v124, v155
	v_mul_f32_e32 v159, v125, v155
	v_mul_f32_e32 v124, 0xbfb8aa3b, v128
	v_mul_f32_e32 v125, 0xbfb8aa3b, v129
	v_exp_f32_e32 v122, v122
	v_exp_f32_e32 v123, v123
	v_exp_f32_e32 v124, v124
	v_exp_f32_e32 v125, v125
	v_mul_f32_e32 v160, v114, v155
	v_mul_f32_e32 v161, v115, v155
	v_pk_add_f32 v[114:115], v[122:123], 1.0 op_sel_hi:[1,0]
	v_pk_add_f32 v[122:123], v[124:125], 1.0 op_sel_hi:[1,0]
	v_div_scale_f32 v124, s[4:5], v115, v115, 1.0
	v_div_scale_f32 v126, s[4:5], v114, v114, 1.0
	v_rcp_f32_e32 v164, v124
	v_div_scale_f32 v128, s[6:7], v123, v123, 1.0
	v_rcp_f32_e32 v165, v126
	v_div_scale_f32 v162, s[8:9], v122, v122, 1.0
	v_rcp_f32_e32 v166, v128
	v_rcp_f32_e32 v167, v162
	v_fma_f32 v168, -v124, v164, 1.0
	v_div_scale_f32 v125, vcc, 1.0, v115, 1.0
	v_fma_f32 v169, -v126, v165, 1.0
	v_fmac_f32_e32 v164, v168, v164
	v_div_scale_f32 v127, s[4:5], 1.0, v114, 1.0
	v_fma_f32 v170, -v128, v166, 1.0
	v_fmac_f32_e32 v165, v169, v165
	v_mul_f32_e32 v168, v125, v164
	v_div_scale_f32 v129, s[6:7], 1.0, v123, 1.0
	v_fma_f32 v171, -v162, v167, 1.0
	v_fmac_f32_e32 v166, v170, v166
	v_mul_f32_e32 v169, v127, v165
	v_fma_f32 v172, -v124, v168, v125
	v_div_scale_f32 v163, s[8:9], 1.0, v122, 1.0
	v_fmac_f32_e32 v167, v171, v167
	v_mul_f32_e32 v170, v129, v166
	v_fma_f32 v173, -v126, v169, v127
	v_fmac_f32_e32 v168, v172, v164
	v_mul_f32_e32 v171, v163, v167
	v_fma_f32 v174, -v128, v170, v129
	v_fmac_f32_e32 v169, v173, v165
	v_fma_f32 v124, -v124, v168, v125
	v_fma_f32 v175, -v162, v171, v163
	v_fmac_f32_e32 v170, v174, v166
	v_fma_f32 v125, -v126, v169, v127
	v_div_fmas_f32 v124, v124, v164, v168
	s_mov_b64 vcc, s[4:5]
	v_fmac_f32_e32 v171, v175, v167
	v_fma_f32 v126, -v128, v170, v129
	v_div_fixup_f32 v115, v124, v115, 1.0
	v_div_fmas_f32 v124, v125, v165, v169
	s_mov_b64 vcc, s[6:7]
	v_fma_f32 v127, -v162, v171, v163
	v_div_fixup_f32 v114, v124, v114, 1.0
	v_div_fmas_f32 v124, v126, v166, v170
	s_mov_b64 vcc, s[8:9]
	v_div_fixup_f32 v125, v124, v123, 1.0
	v_div_fmas_f32 v123, v127, v167, v171
	v_div_fixup_f32 v124, v123, v122, 1.0
	v_mul_f32_e32 v116, v116, v155
	v_mul_f32_e32 v117, v117, v155
	s_waitcnt lgkmcnt(0)
	v_mov_b32_e32 v150, v198
	v_mov_b32_e32 v151, v199
	v_mov_b32_e32 v130, v184
	v_mov_b32_e32 v131, v185
	v_mov_b32_e32 v132, v186
	v_mov_b32_e32 v133, v187
	v_lshlrev_b32_e32 v122, 16, v150
	v_and_b32_e32 v123, 0xffff0000, v150
	v_lshlrev_b32_e32 v126, 16, v151
	v_and_b32_e32 v127, 0xffff0000, v151
	v_pk_fma_f32 v[122:123], v[114:115], v[122:123], v[130:131]
	v_pk_fma_f32 v[124:125], v[124:125], v[126:127], v[132:133]
	global_store_dwordx4 v[144:145], v[122:125], off offset:64
	v_cvt_pk_bf16_f32 v126, v122, v123
	v_cvt_pk_bf16_f32 v127, v124, v125
	s_nop 0
	v_mul_f32_e32 v130, 0xbfb8aa3b, v156
	v_mov_b32_e32 v240, v126
	v_mov_b32_e32 v241, v127
	v_mbcnt_lo_u32_b32 v242, -1, 0
	v_mbcnt_hi_u32_b32 v242, -1, v242
	v_and_b32_e32 v242, 16, v242
	v_lshrrev_b32_e32 v236, 1, v242
	v_add_u32_e32 v242, v242, v236
	v_mov_b32_e32 v243, 0
	v_lshl_add_u64 v[236:237], v[146:147], 0, v[242:243]
	v_permlane16_swap_b32_e32 v238, v240
	v_permlane16_swap_b32_e32 v239, v241
	global_store_dwordx4 v[236:237], v[238:241], off
	s_nop 0
	v_mul_f32_e32 v131, 0xbfb8aa3b, v157
	v_mul_f32_e32 v150, 0xbfb8aa3b, v160
	v_mul_f32_e32 v155, 0xbfb8aa3b, v116
	v_mul_f32_e32 v160, 0xbfb8aa3b, v117
	v_exp_f32_e32 v116, v130
	v_exp_f32_e32 v117, v131
	v_mul_f32_e32 v132, 0xbfb8aa3b, v158
	v_mul_f32_e32 v133, 0xbfb8aa3b, v159
	v_exp_f32_e32 v130, v132
	v_exp_f32_e32 v131, v133
	v_mul_f32_e32 v151, 0xbfb8aa3b, v161
	v_pk_add_f32 v[116:117], v[116:117], 1.0 op_sel_hi:[1,0]
	v_exp_f32_e32 v133, v151
	v_div_scale_f32 v151, s[4:5], v117, v117, 1.0
	v_pk_add_f32 v[130:131], v[130:131], 1.0 op_sel_hi:[1,0]
	v_div_scale_f32 v156, s[4:5], v116, v116, 1.0
	v_rcp_f32_e32 v163, v151
	v_div_scale_f32 v158, s[6:7], v131, v131, 1.0
	v_rcp_f32_e32 v164, v156
	v_div_scale_f32 v161, s[8:9], v130, v130, 1.0
	v_rcp_f32_e32 v165, v158
	v_rcp_f32_e32 v166, v161
	v_fma_f32 v167, -v151, v163, 1.0
	v_exp_f32_e32 v132, v150
	v_exp_f32_e32 v150, v155
	v_div_scale_f32 v155, vcc, 1.0, v117, 1.0
	v_fma_f32 v168, -v156, v164, 1.0
	v_fmac_f32_e32 v163, v167, v163
	v_div_scale_f32 v157, s[4:5], 1.0, v116, 1.0
	v_fma_f32 v169, -v158, v165, 1.0
	v_fmac_f32_e32 v164, v168, v164
	v_mul_f32_e32 v167, v155, v163
	v_div_scale_f32 v159, s[6:7], 1.0, v131, 1.0
	v_fma_f32 v170, -v161, v166, 1.0
	v_fmac_f32_e32 v165, v169, v165
	v_mul_f32_e32 v168, v157, v164
	v_fma_f32 v171, -v151, v167, v155
	v_div_scale_f32 v162, s[8:9], 1.0, v130, 1.0
	v_fmac_f32_e32 v166, v170, v166
	v_mul_f32_e32 v169, v159, v165
	v_fma_f32 v172, -v156, v168, v157
	v_fmac_f32_e32 v167, v171, v163
	v_mul_f32_e32 v170, v162, v166
	v_fma_f32 v173, -v158, v169, v159
	v_fmac_f32_e32 v168, v172, v164
	v_fma_f32 v151, -v151, v167, v155
	v_fma_f32 v174, -v161, v170, v162
	v_fmac_f32_e32 v169, v173, v165
	v_fma_f32 v155, -v156, v168, v157
	v_div_fmas_f32 v151, v151, v163, v167
	s_mov_b64 vcc, s[4:5]
	v_fmac_f32_e32 v170, v174, v166
	v_fma_f32 v156, -v158, v169, v159
	v_div_fixup_f32 v117, v151, v117, 1.0
	v_div_fmas_f32 v151, v155, v164, v168
	s_mov_b64 vcc, s[6:7]
	v_fma_f32 v157, -v161, v170, v162
	v_div_fixup_f32 v116, v151, v116, 1.0
	v_div_fmas_f32 v151, v156, v165, v169
	s_mov_b64 vcc, s[8:9]
	v_div_fixup_f32 v131, v151, v131, 1.0
	v_div_fmas_f32 v151, v157, v166, v170
	v_div_fixup_f32 v130, v151, v130, 1.0
	v_exp_f32_e32 v151, v160
	v_pk_add_f32 v[132:133], v[132:133], 1.0 op_sel_hi:[1,0]
	v_pk_mul_f32 v[118:119], v[118:119], v[118:119]
	v_div_scale_f32 v155, s[4:5], v132, v132, 1.0
	s_waitcnt lgkmcnt(0)
	v_mov_b32_e32 v114, v200
	v_mov_b32_e32 v115, v201
	v_mov_b32_e32 v126, v188
	v_mov_b32_e32 v127, v189
	v_mov_b32_e32 v128, v190
	v_mov_b32_e32 v129, v191
	v_lshlrev_b32_e32 v156, 16, v114
	v_and_b32_e32 v157, 0xffff0000, v114
	v_lshlrev_b32_e32 v158, 16, v115
	v_and_b32_e32 v159, 0xffff0000, v115
	v_pk_fma_f32 v[114:115], v[116:117], v[156:157], v[126:127]
	v_pk_fma_f32 v[116:117], v[130:131], v[158:159], v[128:129]
	global_store_dwordx4 v[144:145], v[114:117], off offset:128
	v_cvt_pk_bf16_f32 v126, v114, v115
	v_cvt_pk_bf16_f32 v127, v116, v117
	s_nop 0
	v_pk_add_f32 v[148:149], v[150:151], 1.0 op_sel_hi:[1,0]
	v_mov_b32_e32 v238, v126
	v_mov_b32_e32 v239, v127
	s_nop 0
	v_div_scale_f32 v150, s[4:5], v133, v133, 1.0
	v_div_scale_f32 v157, s[6:7], v149, v149, 1.0
	v_rcp_f32_e32 v161, v150
	v_rcp_f32_e32 v162, v155
	v_rcp_f32_e32 v163, v157
	v_div_scale_f32 v159, s[8:9], v148, v148, 1.0
	v_rcp_f32_e32 v164, v159
	v_fma_f32 v165, -v150, v161, 1.0
	v_fma_f32 v166, -v155, v162, 1.0
	v_fma_f32 v167, -v157, v163, 1.0
	v_div_scale_f32 v151, vcc, 1.0, v133, 1.0
	v_div_scale_f32 v156, s[4:5], 1.0, v132, 1.0
	v_div_scale_f32 v158, s[6:7], 1.0, v149, 1.0
	v_fmac_f32_e32 v161, v165, v161
	v_fmac_f32_e32 v162, v166, v162
	v_fmac_f32_e32 v163, v167, v163
	v_mul_f32_e32 v165, v151, v161
	v_mul_f32_e32 v166, v156, v162
	v_mul_f32_e32 v167, v158, v163
	v_fma_f32 v169, -v150, v165, v151
	v_fma_f32 v170, -v155, v166, v156
	v_fma_f32 v171, -v157, v167, v158
	v_fma_f32 v168, -v159, v164, 1.0
	v_fmac_f32_e32 v165, v169, v161
	v_fmac_f32_e32 v166, v170, v162
	v_fmac_f32_e32 v167, v171, v163
	v_div_scale_f32 v160, s[8:9], 1.0, v148, 1.0
	v_fmac_f32_e32 v164, v168, v164
	v_fma_f32 v150, -v150, v165, v151
	v_fma_f32 v151, -v155, v166, v156
	v_fma_f32 v155, -v157, v167, v158
	v_add_f32_e32 v157, v118, v119
	v_pk_mul_f32 v[118:119], v[120:121], v[120:121]
	v_mul_f32_e32 v168, v160, v164
	v_add_f32_e32 v118, v118, v157
	v_fma_f32 v172, -v159, v168, v160
	v_add_f32_e32 v157, v119, v118
	v_div_fmas_f32 v118, v150, v161, v165
	s_mov_b64 vcc, s[4:5]
	v_pk_mul_f32 v[122:123], v[122:123], v[122:123]
	v_fmac_f32_e32 v168, v172, v164
	v_div_fixup_f32 v119, v118, v133, 1.0
	v_div_fmas_f32 v118, v151, v162, v166
	s_mov_b64 vcc, s[6:7]
	v_pk_mul_f32 v[124:125], v[124:125], v[124:125]
	v_add_f32_e32 v122, v122, v123
	v_fma_f32 v156, -v159, v168, v160
	v_div_fmas_f32 v120, v155, v163, v167
	s_mov_b64 vcc, s[8:9]
	v_add_f32_e32 v122, v124, v122
	v_pk_mul_f32 v[114:115], v[114:115], v[114:115]
	v_div_fixup_f32 v118, v118, v132, 1.0
	v_div_fixup_f32 v121, v120, v149, 1.0
	v_div_fmas_f32 v120, v156, v164, v168
	v_add_f32_e32 v122, v125, v122
	v_add_f32_e32 v133, v114, v115
	v_div_fixup_f32 v120, v120, v148, 1.0
	v_add_f32_e32 v132, v157, v122
	v_pk_mul_f32 v[122:123], v[116:117], v[116:117]
	s_waitcnt lgkmcnt(0)
	v_mov_b32_e32 v130, v202
	v_mov_b32_e32 v131, v203
	v_mov_b32_e32 v126, v192
	v_mov_b32_e32 v127, v193
	v_mov_b32_e32 v128, v194
	v_mov_b32_e32 v129, v195
	v_lshlrev_b32_e32 v114, 16, v130
	v_and_b32_e32 v115, 0xffff0000, v130
	v_lshlrev_b32_e32 v124, 16, v131
	v_and_b32_e32 v125, 0xffff0000, v131
	v_pk_fma_f32 v[116:117], v[118:119], v[114:115], v[126:127]
	v_pk_fma_f32 v[118:119], v[120:121], v[124:125], v[128:129]
	v_pk_mul_f32 v[114:115], v[116:117], v[116:117]
	v_pk_mul_f32 v[120:121], v[118:119], v[118:119]
	v_add_f32_e32 v114, v114, v115
	v_add_f32_e32 v114, v120, v114
	v_and_b32_e32 v120, 64, v154
	v_add_f32_e32 v122, v122, v133
	v_xor_b32_e32 v115, 16, v154
	v_add_u32_e32 v120, 64, v120
	v_add_f32_e32 v122, v123, v122
	v_cmp_lt_i32_e32 vcc, v115, v120
	v_add_f32_e32 v122, v132, v122
	v_add_f32_e32 v114, v121, v114
	v_cndmask_b32_e32 v115, v154, v115, vcc
	v_add_f32_e32 v114, v122, v114
	v_lshlrev_b32_e32 v126, 2, v115
	ds_bpermute_b32 v115, v126, v114
	global_store_dwordx4 v[144:145], v[116:119], off offset:192
	s_waitcnt lgkmcnt(0)
	v_add_f32_e32 v114, v114, v115
	v_xor_b32_e32 v115, 32, v154
	v_cmp_lt_i32_e32 vcc, v115, v120
	v_cvt_pk_bf16_f32 v116, v116, v117
	v_cvt_pk_bf16_f32 v117, v118, v119
	v_cndmask_b32_e32 v115, v154, v115, vcc
	v_lshlrev_b32_e32 v127, 2, v115
	ds_bpermute_b32 v115, v127, v114
	v_mov_b32_e32 v240, v116
	v_mov_b32_e32 v241, v117
	s_nop 1
	v_lshl_add_u64 v[236:237], v[146:147], 0, v[242:243]
	v_permlane16_swap_b32_e32 v238, v240
	v_permlane16_swap_b32_e32 v239, v241
	global_store_dwordx4 v[236:237], v[238:241], off offset:64
	s_and_saveexec_b64 s[4:5], s[0:1]
	s_cbranch_execz .LBB0_624
	s_waitcnt lgkmcnt(0)
	v_add_f32_e32 v116, v114, v115
	v_lshl_add_u64 v[114:115], v[140:141], 2, s[20:21]
	global_atomic_add_f32 v[114:115], v116, off
.LBB0_624:
	s_or_b64 exec, exec, s[4:5]
	v_or_b32_e32 v118, 16, v140
	v_mov_b32_e32 v119, v141
	s_waitcnt lgkmcnt(0)
	v_lshl_add_u64 v[114:115], v[118:119], 2, s[18:19]
	s_mov_b32 s99, 0
	s_mov_b32 s98, 0x20000
	v_lshl_add_u64 v[236:237], v[230:231], 0, s[98:99]
	global_load_dwordx4 v[180:183], v[236:237], off
	global_load_dwordx4 v[184:187], v[236:237], off offset:64
	global_load_dwordx4 v[188:191], v[236:237], off offset:128
	global_load_dwordx4 v[192:195], v[236:237], off offset:192
	s_mov_b32 s98, 0x10000
	v_lshl_add_u64 v[236:237], v[232:233], 0, s[98:99]
	global_load_dwordx2 v[196:197], v[236:237], off
	global_load_dwordx2 v[198:199], v[236:237], off offset:32
	global_load_dwordx2 v[200:201], v[236:237], off offset:64
	global_load_dwordx2 v[202:203], v[236:237], off offset:96
	s_mov_b32 s98, 0x80
	v_lshl_add_u64 v[236:237], v[234:235], 0, s[98:99]
	global_load_dword v228, v[236:237], off
	v_lshlrev_b64 v[114:115], 11, v[118:119]
	v_lshl_add_u64 v[116:117], s[14:15], 0, v[114:115]
	v_lshl_add_u64 v[124:125], v[116:117], 0, v[142:143]
	v_lshlrev_b64 v[116:117], 12, v[118:119]
	v_lshl_add_u64 v[116:117], v[134:135], 0, v[116:117]
	s_nop 0
	v_lshl_add_u64 v[114:115], s[16:17], 0, v[114:115]
	v_lshl_add_u64 v[120:121], v[116:117], 0, v[138:139]
	v_lshl_add_u64 v[122:123], v[114:115], 0, v[142:143]
	s_nop 0
	s_waitcnt vmcnt(15) lgkmcnt(0)
	v_mov_b32_e32 v130, v229
	v_mov_b32_e32 v128, v220
	v_mov_b32_e32 v129, v221
	v_mov_b32_e32 v114, v204
	v_mov_b32_e32 v115, v205
	v_mov_b32_e32 v116, v206
	v_mov_b32_e32 v117, v207
	v_fmamk_f32 v130, v130, 0x3a800000, v153
	v_mul_f32_e32 v131, 0x4b800000, v130
	v_cmp_gt_f32_e32 vcc, s56, v130
	s_nop 1
	v_cndmask_b32_e32 v131, v130, v131, vcc
	v_rsq_f32_e32 v132, v131
	v_lshlrev_b32_e32 v130, 16, v128
	v_and_b32_e32 v131, 0xffff0000, v128
	v_lshlrev_b32_e32 v128, 16, v129
	v_mul_f32_e32 v133, 0x45800000, v132
	v_cndmask_b32_e32 v132, v132, v133, vcc
	v_mul_f32_e32 v110, v110, v132
	v_mul_f32_e32 v111, v111, v132
	v_mul_f32_e32 v110, 0xbfb8aa3b, v110
	v_mul_f32_e32 v111, 0xbfb8aa3b, v111
	v_mul_f32_e32 v112, v112, v132
	v_mul_f32_e32 v113, v113, v132
	v_exp_f32_e32 v110, v110
	v_exp_f32_e32 v111, v111
	v_mul_f32_e32 v112, 0xbfb8aa3b, v112
	v_mul_f32_e32 v113, 0xbfb8aa3b, v113
	v_exp_f32_e32 v112, v112
	v_exp_f32_e32 v113, v113
	v_mul_f32_e32 v133, v106, v132
	v_mul_f32_e32 v143, v107, v132
	v_pk_add_f32 v[106:107], v[110:111], 1.0 op_sel_hi:[1,0]
	v_pk_add_f32 v[112:113], v[112:113], 1.0 op_sel_hi:[1,0]
	v_div_scale_f32 v110, s[4:5], v107, v107, 1.0
	v_div_scale_f32 v144, s[4:5], v106, v106, 1.0
	v_rcp_f32_e32 v150, v110
	v_div_scale_f32 v146, s[6:7], v113, v113, 1.0
	v_rcp_f32_e32 v151, v144
	v_div_scale_f32 v148, s[8:9], v112, v112, 1.0
	v_rcp_f32_e32 v155, v146
	v_rcp_f32_e32 v156, v148
	v_fma_f32 v157, -v110, v150, 1.0
	v_div_scale_f32 v111, vcc, 1.0, v107, 1.0
	v_fma_f32 v158, -v144, v151, 1.0
	v_fmac_f32_e32 v150, v157, v150
	v_div_scale_f32 v145, s[4:5], 1.0, v106, 1.0
	v_fma_f32 v159, -v146, v155, 1.0
	v_fmac_f32_e32 v151, v158, v151
	v_mul_f32_e32 v157, v111, v150
	v_div_scale_f32 v147, s[6:7], 1.0, v113, 1.0
	v_fma_f32 v160, -v148, v156, 1.0
	v_fmac_f32_e32 v155, v159, v155
	v_mul_f32_e32 v158, v145, v151
	v_fma_f32 v161, -v110, v157, v111
	v_div_scale_f32 v149, s[8:9], 1.0, v112, 1.0
	v_fmac_f32_e32 v156, v160, v156
	v_mul_f32_e32 v159, v147, v155
	v_fma_f32 v162, -v144, v158, v145
	v_fmac_f32_e32 v157, v161, v150
	v_mul_f32_e32 v160, v149, v156
	v_fma_f32 v163, -v146, v159, v147
	v_fmac_f32_e32 v158, v162, v151
	v_fma_f32 v110, -v110, v157, v111
	v_fma_f32 v164, -v148, v160, v149
	v_fmac_f32_e32 v159, v163, v155
	v_fma_f32 v111, -v144, v158, v145
	v_div_fmas_f32 v110, v110, v150, v157
	s_mov_b64 vcc, s[4:5]
	v_fmac_f32_e32 v160, v164, v156
	v_fma_f32 v144, -v146, v159, v147
	v_div_fixup_f32 v107, v110, v107, 1.0
	v_div_fmas_f32 v110, v111, v151, v158
	s_mov_b64 vcc, s[6:7]
	v_fma_f32 v145, -v148, v160, v149
	v_div_fixup_f32 v106, v110, v106, 1.0
	v_div_fmas_f32 v144, v144, v155, v159
	s_mov_b64 vcc, s[8:9]
	v_pk_fma_f32 v[110:111], v[106:107], v[130:131], v[114:115]
	v_div_fmas_f32 v106, v145, v156, v160
	v_and_b32_e32 v129, 0xffff0000, v129
	v_div_fixup_f32 v107, v144, v113, 1.0
	v_div_fixup_f32 v106, v106, v112, 1.0
	v_pk_fma_f32 v[112:113], v[106:107], v[128:129], v[116:117]
	global_store_dwordx4 v[120:121], v[110:113], off
	v_cvt_pk_bf16_f32 v114, v110, v111
	v_cvt_pk_bf16_f32 v115, v112, v113
	s_nop 0
	v_mul_f32_e32 v108, v108, v132
	v_mov_b32_e32 v238, v114
	v_mov_b32_e32 v239, v115
	s_nop 0
	v_mul_f32_e32 v109, v109, v132
	v_mul_f32_e32 v129, v103, v132
	v_mul_f32_e32 v144, v98, v132
	v_mul_f32_e32 v98, 0xbfb8aa3b, v133
	v_mul_f32_e32 v103, 0xbfb8aa3b, v143
	v_mul_f32_e32 v128, v102, v132
	v_mul_f32_e32 v130, v104, v132
	v_mul_f32_e32 v131, v105, v132
	v_mul_f32_e32 v104, 0xbfb8aa3b, v108
	v_mul_f32_e32 v105, 0xbfb8aa3b, v109
	v_exp_f32_e32 v102, v98
	v_exp_f32_e32 v103, v103
	v_exp_f32_e32 v104, v104
	v_exp_f32_e32 v105, v105
	v_mul_f32_e32 v133, v99, v132
	v_pk_add_f32 v[98:99], v[102:103], 1.0 op_sel_hi:[1,0]
	v_mul_f32_e32 v100, v100, v132
	v_pk_add_f32 v[102:103], v[104:105], 1.0 op_sel_hi:[1,0]
	v_div_scale_f32 v104, s[4:5], v99, v99, 1.0
	v_div_scale_f32 v108, s[4:5], v98, v98, 1.0
	v_rcp_f32_e32 v148, v104
	v_div_scale_f32 v143, s[6:7], v103, v103, 1.0
	v_rcp_f32_e32 v149, v108
	v_div_scale_f32 v146, s[8:9], v102, v102, 1.0
	v_rcp_f32_e32 v150, v143
	v_rcp_f32_e32 v151, v146
	v_fma_f32 v155, -v104, v148, 1.0
	v_div_scale_f32 v105, vcc, 1.0, v99, 1.0
	v_fma_f32 v156, -v108, v149, 1.0
	v_fmac_f32_e32 v148, v155, v148
	v_div_scale_f32 v109, s[4:5], 1.0, v98, 1.0
	v_fma_f32 v157, -v143, v150, 1.0
	v_fmac_f32_e32 v149, v156, v149
	v_mul_f32_e32 v155, v105, v148
	v_div_scale_f32 v145, s[6:7], 1.0, v103, 1.0
	v_fma_f32 v158, -v146, v151, 1.0
	v_fmac_f32_e32 v150, v157, v150
	v_mul_f32_e32 v156, v109, v149
	v_fma_f32 v159, -v104, v155, v105
	v_div_scale_f32 v147, s[8:9], 1.0, v102, 1.0
	v_fmac_f32_e32 v151, v158, v151
	v_mul_f32_e32 v157, v145, v150
	v_fma_f32 v160, -v108, v156, v109
	v_fmac_f32_e32 v155, v159, v148
	v_mul_f32_e32 v158, v147, v151
	v_fma_f32 v161, -v143, v157, v145
	v_fmac_f32_e32 v156, v160, v149
	v_fma_f32 v104, -v104, v155, v105
	v_fma_f32 v162, -v146, v158, v147
	v_fmac_f32_e32 v157, v161, v150
	v_fma_f32 v105, -v108, v156, v109
	v_div_fmas_f32 v104, v104, v148, v155
	s_mov_b64 vcc, s[4:5]
	v_fmac_f32_e32 v158, v162, v151
	v_fma_f32 v108, -v143, v157, v145
	v_div_fixup_f32 v99, v104, v99, 1.0
	v_div_fmas_f32 v104, v105, v149, v156
	s_mov_b64 vcc, s[6:7]
	v_fma_f32 v109, -v146, v158, v147
	v_div_fixup_f32 v98, v104, v98, 1.0
	v_div_fmas_f32 v104, v108, v150, v157
	s_mov_b64 vcc, s[8:9]
	v_div_fixup_f32 v105, v104, v103, 1.0
	v_div_fmas_f32 v103, v109, v151, v158
	v_div_fixup_f32 v104, v103, v102, 1.0
	v_mul_f32_e32 v101, v101, v132
	v_pk_mul_f32 v[110:111], v[110:111], v[110:111]
	s_waitcnt lgkmcnt(0)
	v_mov_b32_e32 v106, v222
	v_mov_b32_e32 v107, v223
	v_mov_b32_e32 v114, v208
	v_mov_b32_e32 v115, v209
	v_mov_b32_e32 v116, v210
	v_mov_b32_e32 v117, v211
	v_lshlrev_b32_e32 v102, 16, v106
	v_and_b32_e32 v103, 0xffff0000, v106
	v_lshlrev_b32_e32 v106, 16, v107
	v_and_b32_e32 v107, 0xffff0000, v107
	v_pk_fma_f32 v[102:103], v[98:99], v[102:103], v[114:115]
	v_pk_fma_f32 v[104:105], v[104:105], v[106:107], v[116:117]
	global_store_dwordx4 v[120:121], v[102:105], off offset:64
	v_cvt_pk_bf16_f32 v106, v102, v103
	v_cvt_pk_bf16_f32 v107, v104, v105
	s_nop 0
	v_mul_f32_e32 v114, 0xbfb8aa3b, v128
	v_mov_b32_e32 v240, v106
	v_mov_b32_e32 v241, v107
	v_mbcnt_lo_u32_b32 v242, -1, 0
	v_mbcnt_hi_u32_b32 v242, -1, v242
	v_and_b32_e32 v242, 16, v242
	v_lshrrev_b32_e32 v236, 1, v242
	v_add_u32_e32 v242, v242, v236
	v_mov_b32_e32 v243, 0
	v_lshl_add_u64 v[236:237], v[122:123], 0, v[242:243]
	v_permlane16_swap_b32_e32 v238, v240
	v_permlane16_swap_b32_e32 v239, v241
	global_store_dwordx4 v[236:237], v[238:241], off
	s_nop 0
	v_mul_f32_e32 v115, 0xbfb8aa3b, v129
	v_mul_f32_e32 v116, 0xbfb8aa3b, v130
	v_mul_f32_e32 v117, 0xbfb8aa3b, v131
	v_mul_f32_e32 v130, 0xbfb8aa3b, v100
	v_mul_f32_e32 v131, 0xbfb8aa3b, v101
	v_exp_f32_e32 v100, v114
	v_exp_f32_e32 v101, v115
	v_exp_f32_e32 v114, v116
	v_exp_f32_e32 v115, v117
	v_mul_f32_e32 v128, 0xbfb8aa3b, v144
	v_pk_add_f32 v[100:101], v[100:101], 1.0 op_sel_hi:[1,0]
	v_exp_f32_e32 v116, v128
	v_exp_f32_e32 v128, v130
	v_div_scale_f32 v130, s[4:5], v101, v101, 1.0
	v_pk_add_f32 v[114:115], v[114:115], 1.0 op_sel_hi:[1,0]
	v_div_scale_f32 v132, s[4:5], v100, v100, 1.0
	v_rcp_f32_e32 v147, v130
	v_div_scale_f32 v143, s[6:7], v115, v115, 1.0
	v_rcp_f32_e32 v148, v132
	v_div_scale_f32 v145, s[8:9], v114, v114, 1.0
	v_rcp_f32_e32 v149, v143
	v_rcp_f32_e32 v150, v145
	v_mul_f32_e32 v129, 0xbfb8aa3b, v133
	v_fma_f32 v151, -v130, v147, 1.0
	v_exp_f32_e32 v117, v129
	v_exp_f32_e32 v129, v131
	v_div_scale_f32 v131, vcc, 1.0, v101, 1.0
	v_fma_f32 v155, -v132, v148, 1.0
	v_fmac_f32_e32 v147, v151, v147
	v_div_scale_f32 v133, s[4:5], 1.0, v100, 1.0
	v_fma_f32 v156, -v143, v149, 1.0
	v_fmac_f32_e32 v148, v155, v148
	v_mul_f32_e32 v151, v131, v147
	v_div_scale_f32 v144, s[6:7], 1.0, v115, 1.0
	v_fma_f32 v157, -v145, v150, 1.0
	v_fmac_f32_e32 v149, v156, v149
	v_mul_f32_e32 v155, v133, v148
	v_fma_f32 v158, -v130, v151, v131
	v_div_scale_f32 v146, s[8:9], 1.0, v114, 1.0
	v_fmac_f32_e32 v150, v157, v150
	v_mul_f32_e32 v156, v144, v149
	v_fma_f32 v159, -v132, v155, v133
	v_fmac_f32_e32 v151, v158, v147
	v_mul_f32_e32 v157, v146, v150
	v_fma_f32 v160, -v143, v156, v144
	v_fmac_f32_e32 v155, v159, v148
	v_fma_f32 v130, -v130, v151, v131
	v_fma_f32 v161, -v145, v157, v146
	v_fmac_f32_e32 v156, v160, v149
	v_fma_f32 v131, -v132, v155, v133
	v_div_fmas_f32 v130, v130, v147, v151
	s_mov_b64 vcc, s[4:5]
	v_fmac_f32_e32 v157, v161, v150
	v_fma_f32 v132, -v143, v156, v144
	v_div_fixup_f32 v101, v130, v101, 1.0
	v_div_fmas_f32 v130, v131, v148, v155
	s_mov_b64 vcc, s[6:7]
	v_fma_f32 v133, -v145, v157, v146
	v_div_fixup_f32 v100, v130, v100, 1.0
	v_div_fmas_f32 v130, v132, v149, v156
	s_mov_b64 vcc, s[8:9]
	v_div_fixup_f32 v115, v130, v115, 1.0
	v_div_fmas_f32 v130, v133, v150, v157
	v_div_fixup_f32 v114, v130, v114, 1.0
	v_pk_add_f32 v[116:117], v[116:117], 1.0 op_sel_hi:[1,0]
	v_pk_mul_f32 v[102:103], v[102:103], v[102:103]
	v_pk_mul_f32 v[104:105], v[104:105], v[104:105]
	v_add_f32_e32 v102, v102, v103
	s_waitcnt lgkmcnt(0)
	v_mov_b32_e32 v98, v224
	v_mov_b32_e32 v99, v225
	v_mov_b32_e32 v106, v212
	v_mov_b32_e32 v107, v213
	v_mov_b32_e32 v108, v214
	v_mov_b32_e32 v109, v215
	v_lshlrev_b32_e32 v130, 16, v98
	v_and_b32_e32 v131, 0xffff0000, v98
	v_lshlrev_b32_e32 v132, 16, v99
	v_and_b32_e32 v133, 0xffff0000, v99
	v_pk_fma_f32 v[98:99], v[100:101], v[130:131], v[106:107]
	v_pk_fma_f32 v[100:101], v[114:115], v[132:133], v[108:109]
	global_store_dwordx4 v[120:121], v[98:101], off offset:128
	v_cvt_pk_bf16_f32 v106, v98, v99
	v_cvt_pk_bf16_f32 v107, v100, v101
	s_nop 0
	v_pk_add_f32 v[124:125], v[128:129], 1.0 op_sel_hi:[1,0]
	v_mov_b32_e32 v238, v106
	v_mov_b32_e32 v239, v107
	s_nop 0
	v_div_scale_f32 v128, s[4:5], v117, v117, 1.0
	v_div_scale_f32 v130, s[4:5], v116, v116, 1.0
	v_div_scale_f32 v132, s[6:7], v125, v125, 1.0
	v_rcp_f32_e32 v145, v128
	v_rcp_f32_e32 v146, v130
	v_rcp_f32_e32 v147, v132
	v_div_scale_f32 v143, s[8:9], v124, v124, 1.0
	v_rcp_f32_e32 v148, v143
	v_fma_f32 v149, -v128, v145, 1.0
	v_fma_f32 v150, -v130, v146, 1.0
	v_fma_f32 v151, -v132, v147, 1.0
	v_div_scale_f32 v129, vcc, 1.0, v117, 1.0
	v_div_scale_f32 v131, s[4:5], 1.0, v116, 1.0
	v_div_scale_f32 v133, s[6:7], 1.0, v125, 1.0
	v_fmac_f32_e32 v145, v149, v145
	v_fmac_f32_e32 v146, v150, v146
	v_fmac_f32_e32 v147, v151, v147
	v_mul_f32_e32 v149, v129, v145
	v_mul_f32_e32 v150, v131, v146
	v_mul_f32_e32 v151, v133, v147
	v_fma_f32 v156, -v128, v149, v129
	v_fma_f32 v157, -v130, v150, v131
	v_fma_f32 v158, -v132, v151, v133
	v_fma_f32 v155, -v143, v148, 1.0
	v_fmac_f32_e32 v149, v156, v145
	v_fmac_f32_e32 v150, v157, v146
	v_fmac_f32_e32 v151, v158, v147
	v_div_scale_f32 v144, s[8:9], 1.0, v124, 1.0
	v_fmac_f32_e32 v148, v155, v148
	v_fma_f32 v128, -v128, v149, v129
	v_fma_f32 v129, -v130, v150, v131
	v_fma_f32 v130, -v132, v151, v133
	v_add_f32_e32 v132, v110, v111
	v_pk_mul_f32 v[110:111], v[112:113], v[112:113]
	v_mul_f32_e32 v155, v144, v148
	v_add_f32_e32 v110, v110, v132
	v_fma_f32 v159, -v143, v155, v144
	v_add_f32_e32 v132, v111, v110
	v_div_fmas_f32 v110, v128, v145, v149
	s_mov_b64 vcc, s[4:5]
	v_pk_mul_f32 v[98:99], v[98:99], v[98:99]
	v_fmac_f32_e32 v155, v159, v148
	v_div_fixup_f32 v111, v110, v117, 1.0
	v_div_fmas_f32 v110, v129, v146, v150
	s_mov_b64 vcc, s[6:7]
	v_pk_mul_f32 v[100:101], v[100:101], v[100:101]
	v_add_f32_e32 v98, v98, v99
	v_fma_f32 v131, -v143, v155, v144
	v_div_fmas_f32 v112, v130, v147, v151
	s_mov_b64 vcc, s[8:9]
	v_add_f32_e32 v102, v104, v102
	v_add_f32_e32 v98, v100, v98
	v_div_fixup_f32 v110, v110, v116, 1.0
	v_div_fixup_f32 v113, v112, v125, 1.0
	v_div_fmas_f32 v112, v131, v148, v155
	v_add_f32_e32 v102, v105, v102
	v_add_f32_e32 v117, v101, v98
	v_div_fixup_f32 v112, v112, v124, 1.0
	v_add_f32_e32 v116, v132, v102
	s_waitcnt lgkmcnt(0)
	v_mov_b32_e32 v114, v226
	v_mov_b32_e32 v115, v227
	v_mov_b32_e32 v106, v216
	v_mov_b32_e32 v107, v217
	v_mov_b32_e32 v108, v218
	v_mov_b32_e32 v109, v219
	v_lshlrev_b32_e32 v98, 16, v114
	v_and_b32_e32 v99, 0xffff0000, v114
	v_lshlrev_b32_e32 v102, 16, v115
	v_and_b32_e32 v103, 0xffff0000, v115
	v_pk_fma_f32 v[100:101], v[110:111], v[98:99], v[106:107]
	v_pk_fma_f32 v[102:103], v[112:113], v[102:103], v[108:109]
	v_pk_mul_f32 v[98:99], v[100:101], v[100:101]
	v_pk_mul_f32 v[104:105], v[102:103], v[102:103]
	v_add_f32_e32 v98, v98, v99
	v_add_f32_e32 v98, v104, v98
	v_add_f32_e32 v106, v116, v117
	v_add_f32_e32 v98, v105, v98
	v_add_f32_e32 v98, v106, v98
	ds_bpermute_b32 v99, v126, v98
	global_store_dwordx4 v[120:121], v[100:103], off offset:192
	s_waitcnt lgkmcnt(0)
	v_add_f32_e32 v98, v98, v99
	ds_bpermute_b32 v99, v127, v98
	v_cvt_pk_bf16_f32 v100, v100, v101
	v_cvt_pk_bf16_f32 v101, v102, v103
	v_mov_b32_e32 v240, v100
	v_mov_b32_e32 v241, v101
	s_nop 1
	v_lshl_add_u64 v[236:237], v[122:123], 0, v[242:243]
	v_permlane16_swap_b32_e32 v238, v240
	v_permlane16_swap_b32_e32 v239, v241
	global_store_dwordx4 v[236:237], v[238:241], off offset:64
	s_and_saveexec_b64 s[4:5], s[0:1]
	s_cbranch_execz .LBB0_626
	s_waitcnt lgkmcnt(0)
	v_add_f32_e32 v100, v98, v99
	v_lshl_add_u64 v[98:99], v[118:119], 2, s[20:21]
	global_atomic_add_f32 v[98:99], v100, off
.LBB0_626:
	s_or_b64 exec, exec, s[4:5]
	v_or_b32_e32 v102, 32, v140
	v_mov_b32_e32 v103, v141
	s_waitcnt lgkmcnt(0)
	v_lshl_add_u64 v[98:99], v[102:103], 2, s[18:19]
	s_mov_b32 s99, 0
	s_mov_b32 s98, 0x30000
	v_lshl_add_u64 v[236:237], v[230:231], 0, s[98:99]
	global_load_dwordx4 v[204:207], v[236:237], off
	global_load_dwordx4 v[208:211], v[236:237], off offset:64
	global_load_dwordx4 v[212:215], v[236:237], off offset:128
	global_load_dwordx4 v[216:219], v[236:237], off offset:192
	s_mov_b32 s98, 0x18000
	v_lshl_add_u64 v[236:237], v[232:233], 0, s[98:99]
	global_load_dwordx2 v[220:221], v[236:237], off
	global_load_dwordx2 v[222:223], v[236:237], off offset:32
	global_load_dwordx2 v[224:225], v[236:237], off offset:64
	global_load_dwordx2 v[226:227], v[236:237], off offset:96
	s_mov_b32 s98, 0xc0
	v_lshl_add_u64 v[236:237], v[234:235], 0, s[98:99]
	global_load_dword v229, v[236:237], off
	v_lshlrev_b64 v[98:99], 11, v[102:103]
	v_lshl_add_u64 v[100:101], s[14:15], 0, v[98:99]
	v_mov_b32_e32 v143, v139
	v_lshl_add_u64 v[108:109], v[100:101], 0, v[142:143]
	v_lshlrev_b64 v[100:101], 12, v[102:103]
	v_lshl_add_u64 v[100:101], v[134:135], 0, v[100:101]
	s_nop 0
	v_lshl_add_u64 v[98:99], s[16:17], 0, v[98:99]
	v_lshl_add_u64 v[104:105], v[100:101], 0, v[138:139]
	v_lshl_add_u64 v[106:107], v[98:99], 0, v[142:143]
	s_nop 0
	s_waitcnt vmcnt(15) lgkmcnt(0)
	v_mov_b32_e32 v112, v228
	v_mov_b32_e32 v110, v196
	v_mov_b32_e32 v111, v197
	v_mov_b32_e32 v98, v180
	v_mov_b32_e32 v99, v181
	v_mov_b32_e32 v100, v182
	v_mov_b32_e32 v101, v183
	v_fmamk_f32 v112, v112, 0x3a800000, v153
	v_mul_f32_e32 v113, 0x4b800000, v112
	v_cmp_gt_f32_e32 vcc, s56, v112
	s_nop 1
	v_cndmask_b32_e32 v113, v112, v113, vcc
	v_rsq_f32_e32 v114, v113
	v_lshlrev_b32_e32 v112, 16, v110
	v_and_b32_e32 v113, 0xffff0000, v110
	v_lshlrev_b32_e32 v110, 16, v111
	v_mul_f32_e32 v115, 0x45800000, v114
	v_cndmask_b32_e32 v114, v114, v115, vcc
	v_mul_f32_e32 v94, v94, v114
	v_mul_f32_e32 v95, v95, v114
	v_mul_f32_e32 v94, 0xbfb8aa3b, v94
	v_mul_f32_e32 v95, 0xbfb8aa3b, v95
	v_mul_f32_e32 v96, v96, v114
	v_mul_f32_e32 v97, v97, v114
	v_exp_f32_e32 v94, v94
	v_exp_f32_e32 v95, v95
	v_mul_f32_e32 v96, 0xbfb8aa3b, v96
	v_mul_f32_e32 v97, 0xbfb8aa3b, v97
	v_exp_f32_e32 v96, v96
	v_exp_f32_e32 v97, v97
	v_mul_f32_e32 v115, v90, v114
	v_mul_f32_e32 v116, v91, v114
	v_pk_add_f32 v[90:91], v[94:95], 1.0 op_sel_hi:[1,0]
	v_pk_add_f32 v[96:97], v[96:97], 1.0 op_sel_hi:[1,0]
	v_div_scale_f32 v94, s[4:5], v91, v91, 1.0
	v_div_scale_f32 v117, s[4:5], v90, v90, 1.0
	v_rcp_f32_e32 v123, v94
	v_div_scale_f32 v119, s[6:7], v97, v97, 1.0
	v_rcp_f32_e32 v124, v117
	v_div_scale_f32 v121, s[8:9], v96, v96, 1.0
	v_rcp_f32_e32 v125, v119
	v_rcp_f32_e32 v128, v121
	v_fma_f32 v129, -v94, v123, 1.0
	v_div_scale_f32 v95, vcc, 1.0, v91, 1.0
	v_fma_f32 v130, -v117, v124, 1.0
	v_fmac_f32_e32 v123, v129, v123
	v_div_scale_f32 v118, s[4:5], 1.0, v90, 1.0
	v_fma_f32 v131, -v119, v125, 1.0
	v_fmac_f32_e32 v124, v130, v124
	v_mul_f32_e32 v129, v95, v123
	v_div_scale_f32 v120, s[6:7], 1.0, v97, 1.0
	v_fma_f32 v132, -v121, v128, 1.0
	v_fmac_f32_e32 v125, v131, v125
	v_mul_f32_e32 v130, v118, v124
	v_fma_f32 v133, -v94, v129, v95
	v_div_scale_f32 v122, s[8:9], 1.0, v96, 1.0
	v_fmac_f32_e32 v128, v132, v128
	v_mul_f32_e32 v131, v120, v125
	v_fma_f32 v144, -v117, v130, v118
	v_fmac_f32_e32 v129, v133, v123
	v_mul_f32_e32 v132, v122, v128
	v_fma_f32 v145, -v119, v131, v120
	v_fmac_f32_e32 v130, v144, v124
	v_fma_f32 v94, -v94, v129, v95
	v_fma_f32 v146, -v121, v132, v122
	v_fmac_f32_e32 v131, v145, v125
	v_fma_f32 v95, -v117, v130, v118
	v_div_fmas_f32 v94, v94, v123, v129
	s_mov_b64 vcc, s[4:5]
	v_fmac_f32_e32 v132, v146, v128
	v_fma_f32 v117, -v119, v131, v120
	v_div_fixup_f32 v91, v94, v91, 1.0
	v_div_fmas_f32 v94, v95, v124, v130
	s_mov_b64 vcc, s[6:7]
	v_fma_f32 v118, -v121, v132, v122
	v_div_fixup_f32 v90, v94, v90, 1.0
	v_div_fmas_f32 v117, v117, v125, v131
	s_mov_b64 vcc, s[8:9]
	v_pk_fma_f32 v[94:95], v[90:91], v[112:113], v[98:99]
	v_div_fmas_f32 v90, v118, v128, v132
	v_and_b32_e32 v111, 0xffff0000, v111
	v_div_fixup_f32 v91, v117, v97, 1.0
	v_div_fixup_f32 v90, v90, v96, 1.0
	v_pk_fma_f32 v[96:97], v[90:91], v[110:111], v[100:101]
	global_store_dwordx4 v[104:105], v[94:97], off
	v_cvt_pk_bf16_f32 v98, v94, v95
	v_cvt_pk_bf16_f32 v99, v96, v97
	s_nop 0
	v_mul_f32_e32 v92, v92, v114
	v_mov_b32_e32 v238, v98
	v_mov_b32_e32 v239, v99
	s_nop 0
	v_mul_f32_e32 v93, v93, v114
	v_mul_f32_e32 v111, v87, v114
	v_mul_f32_e32 v117, v82, v114
	v_mul_f32_e32 v82, 0xbfb8aa3b, v115
	v_mul_f32_e32 v87, 0xbfb8aa3b, v116
	v_mul_f32_e32 v110, v86, v114
	v_mul_f32_e32 v112, v88, v114
	v_mul_f32_e32 v113, v89, v114
	v_mul_f32_e32 v88, 0xbfb8aa3b, v92
	v_mul_f32_e32 v89, 0xbfb8aa3b, v93
	v_exp_f32_e32 v86, v82
	v_exp_f32_e32 v87, v87
	v_exp_f32_e32 v88, v88
	v_exp_f32_e32 v89, v89
	v_mul_f32_e32 v115, v83, v114
	v_pk_add_f32 v[82:83], v[86:87], 1.0 op_sel_hi:[1,0]
	v_mul_f32_e32 v84, v84, v114
	v_pk_add_f32 v[86:87], v[88:89], 1.0 op_sel_hi:[1,0]
	v_div_scale_f32 v88, s[4:5], v83, v83, 1.0
	v_div_scale_f32 v92, s[4:5], v82, v82, 1.0
	v_rcp_f32_e32 v121, v88
	v_div_scale_f32 v116, s[6:7], v87, v87, 1.0
	v_rcp_f32_e32 v122, v92
	v_div_scale_f32 v119, s[8:9], v86, v86, 1.0
	v_rcp_f32_e32 v123, v116
	v_rcp_f32_e32 v124, v119
	v_fma_f32 v125, -v88, v121, 1.0
	v_div_scale_f32 v89, vcc, 1.0, v83, 1.0
	v_fma_f32 v128, -v92, v122, 1.0
	v_fmac_f32_e32 v121, v125, v121
	v_div_scale_f32 v93, s[4:5], 1.0, v82, 1.0
	v_fma_f32 v129, -v116, v123, 1.0
	v_fmac_f32_e32 v122, v128, v122
	v_mul_f32_e32 v125, v89, v121
	v_div_scale_f32 v118, s[6:7], 1.0, v87, 1.0
	v_fma_f32 v130, -v119, v124, 1.0
	v_fmac_f32_e32 v123, v129, v123
	v_mul_f32_e32 v128, v93, v122
	v_fma_f32 v131, -v88, v125, v89
	v_div_scale_f32 v120, s[8:9], 1.0, v86, 1.0
	v_fmac_f32_e32 v124, v130, v124
	v_mul_f32_e32 v129, v118, v123
	v_fma_f32 v132, -v92, v128, v93
	v_fmac_f32_e32 v125, v131, v121
	v_mul_f32_e32 v130, v120, v124
	v_fma_f32 v133, -v116, v129, v118
	v_fmac_f32_e32 v128, v132, v122
	v_fma_f32 v88, -v88, v125, v89
	v_fma_f32 v144, -v119, v130, v120
	v_fmac_f32_e32 v129, v133, v123
	v_fma_f32 v89, -v92, v128, v93
	v_div_fmas_f32 v88, v88, v121, v125
	s_mov_b64 vcc, s[4:5]
	v_fmac_f32_e32 v130, v144, v124
	v_fma_f32 v92, -v116, v129, v118
	v_div_fixup_f32 v83, v88, v83, 1.0
	v_div_fmas_f32 v88, v89, v122, v128
	s_mov_b64 vcc, s[6:7]
	v_fma_f32 v93, -v119, v130, v120
	v_div_fixup_f32 v82, v88, v82, 1.0
	v_div_fmas_f32 v88, v92, v123, v129
	s_mov_b64 vcc, s[8:9]
	v_div_fixup_f32 v89, v88, v87, 1.0
	v_div_fmas_f32 v87, v93, v124, v130
	v_div_fixup_f32 v88, v87, v86, 1.0
	v_mul_f32_e32 v85, v85, v114
	v_pk_mul_f32 v[94:95], v[94:95], v[94:95]
	s_waitcnt lgkmcnt(0)
	v_mov_b32_e32 v90, v198
	v_mov_b32_e32 v91, v199
	v_mov_b32_e32 v98, v184
	v_mov_b32_e32 v99, v185
	v_mov_b32_e32 v100, v186
	v_mov_b32_e32 v101, v187
	v_lshlrev_b32_e32 v86, 16, v90
	v_and_b32_e32 v87, 0xffff0000, v90
	v_lshlrev_b32_e32 v90, 16, v91
	v_and_b32_e32 v91, 0xffff0000, v91
	v_pk_fma_f32 v[86:87], v[82:83], v[86:87], v[98:99]
	v_pk_fma_f32 v[88:89], v[88:89], v[90:91], v[100:101]
	global_store_dwordx4 v[104:105], v[86:89], off offset:64
	v_cvt_pk_bf16_f32 v90, v86, v87
	v_cvt_pk_bf16_f32 v91, v88, v89
	s_nop 0
	v_mul_f32_e32 v98, 0xbfb8aa3b, v110
	v_mov_b32_e32 v240, v90
	v_mov_b32_e32 v241, v91
	v_mbcnt_lo_u32_b32 v242, -1, 0
	v_mbcnt_hi_u32_b32 v242, -1, v242
	v_and_b32_e32 v242, 16, v242
	v_lshrrev_b32_e32 v236, 1, v242
	v_add_u32_e32 v242, v242, v236
	v_mov_b32_e32 v243, 0
	v_lshl_add_u64 v[236:237], v[106:107], 0, v[242:243]
	v_permlane16_swap_b32_e32 v238, v240
	v_permlane16_swap_b32_e32 v239, v241
	global_store_dwordx4 v[236:237], v[238:241], off
	s_nop 0
	v_mul_f32_e32 v99, 0xbfb8aa3b, v111
	v_mul_f32_e32 v100, 0xbfb8aa3b, v112
	v_mul_f32_e32 v101, 0xbfb8aa3b, v113
	v_mul_f32_e32 v112, 0xbfb8aa3b, v84
	v_mul_f32_e32 v113, 0xbfb8aa3b, v85
	v_exp_f32_e32 v84, v98
	v_exp_f32_e32 v85, v99
	v_exp_f32_e32 v98, v100
	v_exp_f32_e32 v99, v101
	v_mul_f32_e32 v110, 0xbfb8aa3b, v117
	v_pk_add_f32 v[84:85], v[84:85], 1.0 op_sel_hi:[1,0]
	v_exp_f32_e32 v100, v110
	v_exp_f32_e32 v110, v112
	v_div_scale_f32 v112, s[4:5], v85, v85, 1.0
	v_pk_add_f32 v[98:99], v[98:99], 1.0 op_sel_hi:[1,0]
	v_div_scale_f32 v114, s[4:5], v84, v84, 1.0
	v_rcp_f32_e32 v120, v112
	v_div_scale_f32 v116, s[6:7], v99, v99, 1.0
	v_rcp_f32_e32 v121, v114
	v_div_scale_f32 v118, s[8:9], v98, v98, 1.0
	v_rcp_f32_e32 v122, v116
	v_rcp_f32_e32 v123, v118
	v_mul_f32_e32 v111, 0xbfb8aa3b, v115
	v_fma_f32 v124, -v112, v120, 1.0
	v_exp_f32_e32 v101, v111
	v_exp_f32_e32 v111, v113
	v_div_scale_f32 v113, vcc, 1.0, v85, 1.0
	v_fma_f32 v125, -v114, v121, 1.0
	v_fmac_f32_e32 v120, v124, v120
	v_div_scale_f32 v115, s[4:5], 1.0, v84, 1.0
	v_fma_f32 v128, -v116, v122, 1.0
	v_fmac_f32_e32 v121, v125, v121
	v_mul_f32_e32 v124, v113, v120
	v_div_scale_f32 v117, s[6:7], 1.0, v99, 1.0
	v_fma_f32 v129, -v118, v123, 1.0
	v_fmac_f32_e32 v122, v128, v122
	v_mul_f32_e32 v125, v115, v121
	v_fma_f32 v130, -v112, v124, v113
	v_div_scale_f32 v119, s[8:9], 1.0, v98, 1.0
	v_fmac_f32_e32 v123, v129, v123
	v_mul_f32_e32 v128, v117, v122
	v_fma_f32 v131, -v114, v125, v115
	v_fmac_f32_e32 v124, v130, v120
	v_mul_f32_e32 v129, v119, v123
	v_fma_f32 v132, -v116, v128, v117
	v_fmac_f32_e32 v125, v131, v121
	v_fma_f32 v112, -v112, v124, v113
	v_fma_f32 v133, -v118, v129, v119
	v_fmac_f32_e32 v128, v132, v122
	v_fma_f32 v113, -v114, v125, v115
	v_div_fmas_f32 v112, v112, v120, v124
	s_mov_b64 vcc, s[4:5]
	v_fmac_f32_e32 v129, v133, v123
	v_fma_f32 v114, -v116, v128, v117
	v_div_fixup_f32 v85, v112, v85, 1.0
	v_div_fmas_f32 v112, v113, v121, v125
	s_mov_b64 vcc, s[6:7]
	v_fma_f32 v115, -v118, v129, v119
	v_div_fixup_f32 v84, v112, v84, 1.0
	v_div_fmas_f32 v112, v114, v122, v128
	s_mov_b64 vcc, s[8:9]
	v_div_fixup_f32 v99, v112, v99, 1.0
	v_div_fmas_f32 v112, v115, v123, v129
	v_div_fixup_f32 v98, v112, v98, 1.0
	v_pk_add_f32 v[100:101], v[100:101], 1.0 op_sel_hi:[1,0]
	v_pk_mul_f32 v[86:87], v[86:87], v[86:87]
	v_pk_mul_f32 v[88:89], v[88:89], v[88:89]
	v_add_f32_e32 v86, v86, v87
	s_waitcnt lgkmcnt(0)
	v_mov_b32_e32 v82, v200
	v_mov_b32_e32 v83, v201
	v_mov_b32_e32 v90, v188
	v_mov_b32_e32 v91, v189
	v_mov_b32_e32 v92, v190
	v_mov_b32_e32 v93, v191
	v_lshlrev_b32_e32 v112, 16, v82
	v_and_b32_e32 v113, 0xffff0000, v82
	v_lshlrev_b32_e32 v114, 16, v83
	v_and_b32_e32 v115, 0xffff0000, v83
	v_pk_fma_f32 v[82:83], v[84:85], v[112:113], v[90:91]
	v_pk_fma_f32 v[84:85], v[98:99], v[114:115], v[92:93]
	global_store_dwordx4 v[104:105], v[82:85], off offset:128
	v_cvt_pk_bf16_f32 v90, v82, v83
	v_cvt_pk_bf16_f32 v91, v84, v85
	s_nop 0
	v_pk_add_f32 v[108:109], v[110:111], 1.0 op_sel_hi:[1,0]
	v_mov_b32_e32 v238, v90
	v_mov_b32_e32 v239, v91
	s_nop 0
	v_div_scale_f32 v110, s[4:5], v101, v101, 1.0
	v_div_scale_f32 v112, s[4:5], v100, v100, 1.0
	v_div_scale_f32 v114, s[6:7], v109, v109, 1.0
	v_rcp_f32_e32 v118, v110
	v_rcp_f32_e32 v119, v112
	v_rcp_f32_e32 v120, v114
	v_div_scale_f32 v116, s[8:9], v108, v108, 1.0
	v_rcp_f32_e32 v121, v116
	v_fma_f32 v122, -v110, v118, 1.0
	v_fma_f32 v123, -v112, v119, 1.0
	v_fma_f32 v124, -v114, v120, 1.0
	v_div_scale_f32 v111, vcc, 1.0, v101, 1.0
	v_div_scale_f32 v113, s[4:5], 1.0, v100, 1.0
	v_div_scale_f32 v115, s[6:7], 1.0, v109, 1.0
	v_fmac_f32_e32 v118, v122, v118
	v_fmac_f32_e32 v119, v123, v119
	v_fmac_f32_e32 v120, v124, v120
	v_mul_f32_e32 v122, v111, v118
	v_mul_f32_e32 v123, v113, v119
	v_mul_f32_e32 v124, v115, v120
	v_fma_f32 v128, -v110, v122, v111
	v_fma_f32 v129, -v112, v123, v113
	v_fma_f32 v130, -v114, v124, v115
	v_fma_f32 v125, -v116, v121, 1.0
	v_fmac_f32_e32 v122, v128, v118
	v_fmac_f32_e32 v123, v129, v119
	v_fmac_f32_e32 v124, v130, v120
	v_div_scale_f32 v117, s[8:9], 1.0, v108, 1.0
	v_fmac_f32_e32 v121, v125, v121
	v_fma_f32 v110, -v110, v122, v111
	v_fma_f32 v111, -v112, v123, v113
	v_fma_f32 v112, -v114, v124, v115
	v_add_f32_e32 v114, v94, v95
	v_pk_mul_f32 v[94:95], v[96:97], v[96:97]
	v_mul_f32_e32 v125, v117, v121
	v_add_f32_e32 v94, v94, v114
	v_fma_f32 v131, -v116, v125, v117
	v_add_f32_e32 v114, v95, v94
	v_div_fmas_f32 v94, v110, v118, v122
	s_mov_b64 vcc, s[4:5]
	v_pk_mul_f32 v[82:83], v[82:83], v[82:83]
	v_fmac_f32_e32 v125, v131, v121
	v_div_fixup_f32 v95, v94, v101, 1.0
	v_div_fmas_f32 v94, v111, v119, v123
	s_mov_b64 vcc, s[6:7]
	v_pk_mul_f32 v[84:85], v[84:85], v[84:85]
	v_add_f32_e32 v82, v82, v83
	v_fma_f32 v113, -v116, v125, v117
	v_div_fmas_f32 v96, v112, v120, v124
	s_mov_b64 vcc, s[8:9]
	v_add_f32_e32 v86, v88, v86
	v_add_f32_e32 v82, v84, v82
	v_div_fixup_f32 v94, v94, v100, 1.0
	v_div_fixup_f32 v97, v96, v109, 1.0
	v_div_fmas_f32 v96, v113, v121, v125
	v_add_f32_e32 v86, v89, v86
	v_add_f32_e32 v101, v85, v82
	v_div_fixup_f32 v96, v96, v108, 1.0
	v_add_f32_e32 v100, v114, v86
	s_waitcnt lgkmcnt(0)
	v_mov_b32_e32 v98, v202
	v_mov_b32_e32 v99, v203
	v_mov_b32_e32 v90, v192
	v_mov_b32_e32 v91, v193
	v_mov_b32_e32 v92, v194
	v_mov_b32_e32 v93, v195
	v_lshlrev_b32_e32 v82, 16, v98
	v_and_b32_e32 v83, 0xffff0000, v98
	v_lshlrev_b32_e32 v86, 16, v99
	v_and_b32_e32 v87, 0xffff0000, v99
	v_pk_fma_f32 v[84:85], v[94:95], v[82:83], v[90:91]
	v_pk_fma_f32 v[86:87], v[96:97], v[86:87], v[92:93]
	v_pk_mul_f32 v[82:83], v[84:85], v[84:85]
	v_pk_mul_f32 v[88:89], v[86:87], v[86:87]
	v_add_f32_e32 v82, v82, v83
	v_add_f32_e32 v82, v88, v82
	v_add_f32_e32 v90, v100, v101
	v_add_f32_e32 v82, v89, v82
	v_add_f32_e32 v82, v90, v82
	ds_bpermute_b32 v83, v126, v82
	global_store_dwordx4 v[104:105], v[84:87], off offset:192
	s_waitcnt lgkmcnt(0)
	v_add_f32_e32 v82, v82, v83
	ds_bpermute_b32 v83, v127, v82
	v_cvt_pk_bf16_f32 v84, v84, v85
	v_cvt_pk_bf16_f32 v85, v86, v87
	v_mov_b32_e32 v240, v84
	v_mov_b32_e32 v241, v85
	s_nop 1
	v_lshl_add_u64 v[236:237], v[106:107], 0, v[242:243]
	v_permlane16_swap_b32_e32 v238, v240
	v_permlane16_swap_b32_e32 v239, v241
	global_store_dwordx4 v[236:237], v[238:241], off offset:64
	s_and_saveexec_b64 s[4:5], s[0:1]
	s_cbranch_execz .LBB0_628
	s_waitcnt lgkmcnt(0)
	v_add_f32_e32 v84, v82, v83
	v_lshl_add_u64 v[82:83], v[102:103], 2, s[20:21]
	global_atomic_add_f32 v[82:83], v84, off
.LBB0_628:
	s_or_b64 exec, exec, s[4:5]
	v_or_b32_e32 v86, 48, v140
	v_mov_b32_e32 v87, v141
	s_waitcnt lgkmcnt(0)
	v_lshl_add_u64 v[82:83], v[86:87], 2, s[18:19]
	s_mov_b32 s99, 0
	s_mov_b32 s98, 0x40000
	v_lshl_add_u64 v[236:237], v[230:231], 0, s[98:99]
	global_load_dwordx4 v[180:183], v[236:237], off
	global_load_dwordx4 v[184:187], v[236:237], off offset:64
	global_load_dwordx4 v[188:191], v[236:237], off offset:128
	global_load_dwordx4 v[192:195], v[236:237], off offset:192
	s_mov_b32 s98, 0x20000
	v_lshl_add_u64 v[236:237], v[232:233], 0, s[98:99]
	global_load_dwordx2 v[196:197], v[236:237], off
	global_load_dwordx2 v[198:199], v[236:237], off offset:32
	global_load_dwordx2 v[200:201], v[236:237], off offset:64
	global_load_dwordx2 v[202:203], v[236:237], off offset:96
	s_mov_b32 s98, 0x100
	v_lshl_add_u64 v[236:237], v[234:235], 0, s[98:99]
	global_load_dword v228, v[236:237], off
	v_lshlrev_b64 v[82:83], 11, v[86:87]
	v_lshl_add_u64 v[84:85], s[14:15], 0, v[82:83]
	v_lshl_add_u64 v[92:93], v[84:85], 0, v[142:143]
	v_lshlrev_b64 v[84:85], 12, v[86:87]
	v_lshl_add_u64 v[84:85], v[134:135], 0, v[84:85]
	s_nop 0
	v_lshl_add_u64 v[82:83], s[16:17], 0, v[82:83]
	v_lshl_add_u64 v[88:89], v[84:85], 0, v[138:139]
	v_lshl_add_u64 v[90:91], v[82:83], 0, v[142:143]
	s_nop 0
	s_waitcnt vmcnt(15) lgkmcnt(0)
	v_mov_b32_e32 v96, v229
	v_mov_b32_e32 v94, v220
	v_mov_b32_e32 v95, v221
	v_mov_b32_e32 v82, v204
	v_mov_b32_e32 v83, v205
	v_mov_b32_e32 v84, v206
	v_mov_b32_e32 v85, v207
	v_fmamk_f32 v96, v96, 0x3a800000, v153
	v_mul_f32_e32 v97, 0x4b800000, v96
	v_cmp_gt_f32_e32 vcc, s56, v96
	s_nop 1
	v_cndmask_b32_e32 v97, v96, v97, vcc
	v_rsq_f32_e32 v98, v97
	v_lshlrev_b32_e32 v96, 16, v94
	v_and_b32_e32 v97, 0xffff0000, v94
	v_lshlrev_b32_e32 v94, 16, v95
	v_mul_f32_e32 v99, 0x45800000, v98
	v_cndmask_b32_e32 v98, v98, v99, vcc
	v_mul_f32_e32 v78, v78, v98
	v_mul_f32_e32 v79, v79, v98
	v_mul_f32_e32 v78, 0xbfb8aa3b, v78
	v_mul_f32_e32 v79, 0xbfb8aa3b, v79
	v_mul_f32_e32 v80, v80, v98
	v_mul_f32_e32 v81, v81, v98
	v_exp_f32_e32 v78, v78
	v_exp_f32_e32 v79, v79
	v_mul_f32_e32 v80, 0xbfb8aa3b, v80
	v_mul_f32_e32 v81, 0xbfb8aa3b, v81
	v_exp_f32_e32 v80, v80
	v_exp_f32_e32 v81, v81
	v_mul_f32_e32 v99, v74, v98
	v_mul_f32_e32 v100, v75, v98
	v_pk_add_f32 v[74:75], v[78:79], 1.0 op_sel_hi:[1,0]
	v_pk_add_f32 v[80:81], v[80:81], 1.0 op_sel_hi:[1,0]
	v_div_scale_f32 v78, s[4:5], v75, v75, 1.0
	v_div_scale_f32 v101, s[4:5], v74, v74, 1.0
	v_rcp_f32_e32 v107, v78
	v_div_scale_f32 v103, s[6:7], v81, v81, 1.0
	v_rcp_f32_e32 v108, v101
	v_div_scale_f32 v105, s[8:9], v80, v80, 1.0
	v_rcp_f32_e32 v109, v103
	v_rcp_f32_e32 v110, v105
	v_fma_f32 v111, -v78, v107, 1.0
	v_div_scale_f32 v79, vcc, 1.0, v75, 1.0
	v_fma_f32 v112, -v101, v108, 1.0
	v_fmac_f32_e32 v107, v111, v107
	v_div_scale_f32 v102, s[4:5], 1.0, v74, 1.0
	v_fma_f32 v113, -v103, v109, 1.0
	v_fmac_f32_e32 v108, v112, v108
	v_mul_f32_e32 v111, v79, v107
	v_div_scale_f32 v104, s[6:7], 1.0, v81, 1.0
	v_fma_f32 v114, -v105, v110, 1.0
	v_fmac_f32_e32 v109, v113, v109
	v_mul_f32_e32 v112, v102, v108
	v_fma_f32 v115, -v78, v111, v79
	v_div_scale_f32 v106, s[8:9], 1.0, v80, 1.0
	v_fmac_f32_e32 v110, v114, v110
	v_mul_f32_e32 v113, v104, v109
	v_fma_f32 v116, -v101, v112, v102
	v_fmac_f32_e32 v111, v115, v107
	v_mul_f32_e32 v114, v106, v110
	v_fma_f32 v117, -v103, v113, v104
	v_fmac_f32_e32 v112, v116, v108
	v_fma_f32 v78, -v78, v111, v79
	v_fma_f32 v118, -v105, v114, v106
	v_fmac_f32_e32 v113, v117, v109
	v_fma_f32 v79, -v101, v112, v102
	v_div_fmas_f32 v78, v78, v107, v111
	s_mov_b64 vcc, s[4:5]
	v_fmac_f32_e32 v114, v118, v110
	v_fma_f32 v101, -v103, v113, v104
	v_div_fixup_f32 v75, v78, v75, 1.0
	v_div_fmas_f32 v78, v79, v108, v112
	s_mov_b64 vcc, s[6:7]
	v_fma_f32 v102, -v105, v114, v106
	v_div_fixup_f32 v74, v78, v74, 1.0
	v_div_fmas_f32 v101, v101, v109, v113
	s_mov_b64 vcc, s[8:9]
	v_pk_fma_f32 v[78:79], v[74:75], v[96:97], v[82:83]
	v_div_fmas_f32 v74, v102, v110, v114
	v_and_b32_e32 v95, 0xffff0000, v95
	v_div_fixup_f32 v75, v101, v81, 1.0
	v_div_fixup_f32 v74, v74, v80, 1.0
	v_pk_fma_f32 v[80:81], v[74:75], v[94:95], v[84:85]
	global_store_dwordx4 v[88:89], v[78:81], off
	v_cvt_pk_bf16_f32 v82, v78, v79
	v_cvt_pk_bf16_f32 v83, v80, v81
	s_nop 0
	v_mul_f32_e32 v76, v76, v98
	v_mov_b32_e32 v238, v82
	v_mov_b32_e32 v239, v83
	s_nop 0
	v_mul_f32_e32 v77, v77, v98
	v_mul_f32_e32 v95, v71, v98
	v_mul_f32_e32 v101, v66, v98
	v_mul_f32_e32 v66, 0xbfb8aa3b, v99
	v_mul_f32_e32 v71, 0xbfb8aa3b, v100
	v_mul_f32_e32 v94, v70, v98
	v_mul_f32_e32 v96, v72, v98
	v_mul_f32_e32 v97, v73, v98
	v_mul_f32_e32 v72, 0xbfb8aa3b, v76
	v_mul_f32_e32 v73, 0xbfb8aa3b, v77
	v_exp_f32_e32 v70, v66
	v_exp_f32_e32 v71, v71
	v_exp_f32_e32 v72, v72
	v_exp_f32_e32 v73, v73
	v_mul_f32_e32 v99, v67, v98
	v_pk_add_f32 v[66:67], v[70:71], 1.0 op_sel_hi:[1,0]
	v_mul_f32_e32 v68, v68, v98
	v_pk_add_f32 v[70:71], v[72:73], 1.0 op_sel_hi:[1,0]
	v_div_scale_f32 v72, s[4:5], v67, v67, 1.0
	v_div_scale_f32 v76, s[4:5], v66, v66, 1.0
	v_rcp_f32_e32 v105, v72
	v_div_scale_f32 v100, s[6:7], v71, v71, 1.0
	v_rcp_f32_e32 v106, v76
	v_div_scale_f32 v103, s[8:9], v70, v70, 1.0
	v_rcp_f32_e32 v107, v100
	v_rcp_f32_e32 v108, v103
	v_fma_f32 v109, -v72, v105, 1.0
	v_div_scale_f32 v73, vcc, 1.0, v67, 1.0
	v_fma_f32 v110, -v76, v106, 1.0
	v_fmac_f32_e32 v105, v109, v105
	v_div_scale_f32 v77, s[4:5], 1.0, v66, 1.0
	v_fma_f32 v111, -v100, v107, 1.0
	v_fmac_f32_e32 v106, v110, v106
	v_mul_f32_e32 v109, v73, v105
	v_div_scale_f32 v102, s[6:7], 1.0, v71, 1.0
	v_fma_f32 v112, -v103, v108, 1.0
	v_fmac_f32_e32 v107, v111, v107
	v_mul_f32_e32 v110, v77, v106
	v_fma_f32 v113, -v72, v109, v73
	v_div_scale_f32 v104, s[8:9], 1.0, v70, 1.0
	v_fmac_f32_e32 v108, v112, v108
	v_mul_f32_e32 v111, v102, v107
	v_fma_f32 v114, -v76, v110, v77
	v_fmac_f32_e32 v109, v113, v105
	v_mul_f32_e32 v112, v104, v108
	v_fma_f32 v115, -v100, v111, v102
	v_fmac_f32_e32 v110, v114, v106
	v_fma_f32 v72, -v72, v109, v73
	v_fma_f32 v116, -v103, v112, v104
	v_fmac_f32_e32 v111, v115, v107
	v_fma_f32 v73, -v76, v110, v77
	v_div_fmas_f32 v72, v72, v105, v109
	s_mov_b64 vcc, s[4:5]
	v_fmac_f32_e32 v112, v116, v108
	v_fma_f32 v76, -v100, v111, v102
	v_div_fixup_f32 v67, v72, v67, 1.0
	v_div_fmas_f32 v72, v73, v106, v110
	s_mov_b64 vcc, s[6:7]
	v_fma_f32 v77, -v103, v112, v104
	v_div_fixup_f32 v66, v72, v66, 1.0
	v_div_fmas_f32 v72, v76, v107, v111
	s_mov_b64 vcc, s[8:9]
	v_div_fixup_f32 v73, v72, v71, 1.0
	v_div_fmas_f32 v71, v77, v108, v112
	v_div_fixup_f32 v72, v71, v70, 1.0
	v_mul_f32_e32 v69, v69, v98
	v_pk_mul_f32 v[78:79], v[78:79], v[78:79]
	s_waitcnt lgkmcnt(0)
	v_mov_b32_e32 v74, v222
	v_mov_b32_e32 v75, v223
	v_mov_b32_e32 v82, v208
	v_mov_b32_e32 v83, v209
	v_mov_b32_e32 v84, v210
	v_mov_b32_e32 v85, v211
	v_lshlrev_b32_e32 v70, 16, v74
	v_and_b32_e32 v71, 0xffff0000, v74
	v_lshlrev_b32_e32 v74, 16, v75
	v_and_b32_e32 v75, 0xffff0000, v75
	v_pk_fma_f32 v[70:71], v[66:67], v[70:71], v[82:83]
	v_pk_fma_f32 v[72:73], v[72:73], v[74:75], v[84:85]
	global_store_dwordx4 v[88:89], v[70:73], off offset:64
	v_cvt_pk_bf16_f32 v74, v70, v71
	v_cvt_pk_bf16_f32 v75, v72, v73
	s_nop 0
	v_mul_f32_e32 v82, 0xbfb8aa3b, v94
	v_mov_b32_e32 v240, v74
	v_mov_b32_e32 v241, v75
	v_mbcnt_lo_u32_b32 v242, -1, 0
	v_mbcnt_hi_u32_b32 v242, -1, v242
	v_and_b32_e32 v242, 16, v242
	v_lshrrev_b32_e32 v236, 1, v242
	v_add_u32_e32 v242, v242, v236
	v_mov_b32_e32 v243, 0
	v_lshl_add_u64 v[236:237], v[90:91], 0, v[242:243]
	v_permlane16_swap_b32_e32 v238, v240
	v_permlane16_swap_b32_e32 v239, v241
	global_store_dwordx4 v[236:237], v[238:241], off
	s_nop 0
	v_mul_f32_e32 v83, 0xbfb8aa3b, v95
	v_mul_f32_e32 v84, 0xbfb8aa3b, v96
	v_mul_f32_e32 v85, 0xbfb8aa3b, v97
	v_mul_f32_e32 v96, 0xbfb8aa3b, v68
	v_mul_f32_e32 v97, 0xbfb8aa3b, v69
	v_exp_f32_e32 v68, v82
	v_exp_f32_e32 v69, v83
	v_exp_f32_e32 v82, v84
	v_exp_f32_e32 v83, v85
	v_mul_f32_e32 v94, 0xbfb8aa3b, v101
	v_pk_add_f32 v[68:69], v[68:69], 1.0 op_sel_hi:[1,0]
	v_exp_f32_e32 v84, v94
	v_exp_f32_e32 v94, v96
	v_div_scale_f32 v96, s[4:5], v69, v69, 1.0
	v_pk_add_f32 v[82:83], v[82:83], 1.0 op_sel_hi:[1,0]
	v_div_scale_f32 v98, s[4:5], v68, v68, 1.0
	v_rcp_f32_e32 v104, v96
	v_div_scale_f32 v100, s[6:7], v83, v83, 1.0
	v_rcp_f32_e32 v105, v98
	v_div_scale_f32 v102, s[8:9], v82, v82, 1.0
	v_rcp_f32_e32 v106, v100
	v_rcp_f32_e32 v107, v102
	v_mul_f32_e32 v95, 0xbfb8aa3b, v99
	v_fma_f32 v108, -v96, v104, 1.0
	v_exp_f32_e32 v85, v95
	v_exp_f32_e32 v95, v97
	v_div_scale_f32 v97, vcc, 1.0, v69, 1.0
	v_fma_f32 v109, -v98, v105, 1.0
	v_fmac_f32_e32 v104, v108, v104
	v_div_scale_f32 v99, s[4:5], 1.0, v68, 1.0
	v_fma_f32 v110, -v100, v106, 1.0
	v_fmac_f32_e32 v105, v109, v105
	v_mul_f32_e32 v108, v97, v104
	v_div_scale_f32 v101, s[6:7], 1.0, v83, 1.0
	v_fma_f32 v111, -v102, v107, 1.0
	v_fmac_f32_e32 v106, v110, v106
	v_mul_f32_e32 v109, v99, v105
	v_fma_f32 v112, -v96, v108, v97
	v_div_scale_f32 v103, s[8:9], 1.0, v82, 1.0
	v_fmac_f32_e32 v107, v111, v107
	v_mul_f32_e32 v110, v101, v106
	v_fma_f32 v113, -v98, v109, v99
	v_fmac_f32_e32 v108, v112, v104
	v_mul_f32_e32 v111, v103, v107
	v_fma_f32 v114, -v100, v110, v101
	v_fmac_f32_e32 v109, v113, v105
	v_fma_f32 v96, -v96, v108, v97
	v_fma_f32 v115, -v102, v111, v103
	v_fmac_f32_e32 v110, v114, v106
	v_fma_f32 v97, -v98, v109, v99
	v_div_fmas_f32 v96, v96, v104, v108
	s_mov_b64 vcc, s[4:5]
	v_fmac_f32_e32 v111, v115, v107
	v_fma_f32 v98, -v100, v110, v101
	v_div_fixup_f32 v69, v96, v69, 1.0
	v_div_fmas_f32 v96, v97, v105, v109
	s_mov_b64 vcc, s[6:7]
	v_fma_f32 v99, -v102, v111, v103
	v_div_fixup_f32 v68, v96, v68, 1.0
	v_div_fmas_f32 v96, v98, v106, v110
	s_mov_b64 vcc, s[8:9]
	v_div_fixup_f32 v83, v96, v83, 1.0
	v_div_fmas_f32 v96, v99, v107, v111
	v_div_fixup_f32 v82, v96, v82, 1.0
	v_pk_add_f32 v[84:85], v[84:85], 1.0 op_sel_hi:[1,0]
	v_pk_mul_f32 v[70:71], v[70:71], v[70:71]
	v_pk_mul_f32 v[72:73], v[72:73], v[72:73]
	v_add_f32_e32 v70, v70, v71
	s_waitcnt lgkmcnt(0)
	v_mov_b32_e32 v66, v224
	v_mov_b32_e32 v67, v225
	v_mov_b32_e32 v74, v212
	v_mov_b32_e32 v75, v213
	v_mov_b32_e32 v76, v214
	v_mov_b32_e32 v77, v215
	v_lshlrev_b32_e32 v96, 16, v66
	v_and_b32_e32 v97, 0xffff0000, v66
	v_lshlrev_b32_e32 v98, 16, v67
	v_and_b32_e32 v99, 0xffff0000, v67
	v_pk_fma_f32 v[66:67], v[68:69], v[96:97], v[74:75]
	v_pk_fma_f32 v[68:69], v[82:83], v[98:99], v[76:77]
	global_store_dwordx4 v[88:89], v[66:69], off offset:128
	v_cvt_pk_bf16_f32 v74, v66, v67
	v_cvt_pk_bf16_f32 v75, v68, v69
	s_nop 0
	v_pk_add_f32 v[92:93], v[94:95], 1.0 op_sel_hi:[1,0]
	v_mov_b32_e32 v238, v74
	v_mov_b32_e32 v239, v75
	s_nop 0
	v_div_scale_f32 v94, s[4:5], v85, v85, 1.0
	v_div_scale_f32 v96, s[4:5], v84, v84, 1.0
	v_div_scale_f32 v98, s[6:7], v93, v93, 1.0
	v_rcp_f32_e32 v102, v94
	v_rcp_f32_e32 v103, v96
	v_rcp_f32_e32 v104, v98
	v_div_scale_f32 v100, s[8:9], v92, v92, 1.0
	v_rcp_f32_e32 v105, v100
	v_fma_f32 v106, -v94, v102, 1.0
	v_fma_f32 v107, -v96, v103, 1.0
	v_fma_f32 v108, -v98, v104, 1.0
	v_div_scale_f32 v95, vcc, 1.0, v85, 1.0
	v_div_scale_f32 v97, s[4:5], 1.0, v84, 1.0
	v_div_scale_f32 v99, s[6:7], 1.0, v93, 1.0
	v_fmac_f32_e32 v102, v106, v102
	v_fmac_f32_e32 v103, v107, v103
	v_fmac_f32_e32 v104, v108, v104
	v_mul_f32_e32 v106, v95, v102
	v_mul_f32_e32 v107, v97, v103
	v_mul_f32_e32 v108, v99, v104
	v_fma_f32 v110, -v94, v106, v95
	v_fma_f32 v111, -v96, v107, v97
	v_fma_f32 v112, -v98, v108, v99
	v_fma_f32 v109, -v100, v105, 1.0
	v_fmac_f32_e32 v106, v110, v102
	v_fmac_f32_e32 v107, v111, v103
	v_fmac_f32_e32 v108, v112, v104
	v_div_scale_f32 v101, s[8:9], 1.0, v92, 1.0
	v_fmac_f32_e32 v105, v109, v105
	v_fma_f32 v94, -v94, v106, v95
	v_fma_f32 v95, -v96, v107, v97
	v_fma_f32 v96, -v98, v108, v99
	v_add_f32_e32 v98, v78, v79
	v_pk_mul_f32 v[78:79], v[80:81], v[80:81]
	v_mul_f32_e32 v109, v101, v105
	v_add_f32_e32 v78, v78, v98
	v_fma_f32 v113, -v100, v109, v101
	v_add_f32_e32 v98, v79, v78
	v_div_fmas_f32 v78, v94, v102, v106
	s_mov_b64 vcc, s[4:5]
	v_pk_mul_f32 v[66:67], v[66:67], v[66:67]
	v_fmac_f32_e32 v109, v113, v105
	v_div_fixup_f32 v79, v78, v85, 1.0
	v_div_fmas_f32 v78, v95, v103, v107
	s_mov_b64 vcc, s[6:7]
	v_pk_mul_f32 v[68:69], v[68:69], v[68:69]
	v_add_f32_e32 v66, v66, v67
	v_fma_f32 v97, -v100, v109, v101
	v_div_fmas_f32 v80, v96, v104, v108
	s_mov_b64 vcc, s[8:9]
	v_add_f32_e32 v70, v72, v70
	v_add_f32_e32 v66, v68, v66
	v_div_fixup_f32 v78, v78, v84, 1.0
	v_div_fixup_f32 v81, v80, v93, 1.0
	v_div_fmas_f32 v80, v97, v105, v109
	v_add_f32_e32 v70, v73, v70
	v_add_f32_e32 v85, v69, v66
	v_div_fixup_f32 v80, v80, v92, 1.0
	v_add_f32_e32 v84, v98, v70
	s_waitcnt lgkmcnt(0)
	v_mov_b32_e32 v82, v226
	v_mov_b32_e32 v83, v227
	v_mov_b32_e32 v74, v216
	v_mov_b32_e32 v75, v217
	v_mov_b32_e32 v76, v218
	v_mov_b32_e32 v77, v219
	v_lshlrev_b32_e32 v66, 16, v82
	v_and_b32_e32 v67, 0xffff0000, v82
	v_lshlrev_b32_e32 v70, 16, v83
	v_and_b32_e32 v71, 0xffff0000, v83
	v_pk_fma_f32 v[68:69], v[78:79], v[66:67], v[74:75]
	v_pk_fma_f32 v[70:71], v[80:81], v[70:71], v[76:77]
	v_pk_mul_f32 v[66:67], v[68:69], v[68:69]
	v_pk_mul_f32 v[72:73], v[70:71], v[70:71]
	v_add_f32_e32 v66, v66, v67
	v_add_f32_e32 v66, v72, v66
	v_add_f32_e32 v74, v84, v85
	v_add_f32_e32 v66, v73, v66
	v_add_f32_e32 v66, v74, v66
	ds_bpermute_b32 v67, v126, v66
	global_store_dwordx4 v[88:89], v[68:71], off offset:192
	s_waitcnt lgkmcnt(0)
	v_add_f32_e32 v66, v66, v67
	ds_bpermute_b32 v67, v127, v66
	v_cvt_pk_bf16_f32 v68, v68, v69
	v_cvt_pk_bf16_f32 v69, v70, v71
	v_mov_b32_e32 v240, v68
	v_mov_b32_e32 v241, v69
	s_nop 1
	v_lshl_add_u64 v[236:237], v[90:91], 0, v[242:243]
	v_permlane16_swap_b32_e32 v238, v240
	v_permlane16_swap_b32_e32 v239, v241
	global_store_dwordx4 v[236:237], v[238:241], off offset:64
	s_and_saveexec_b64 s[4:5], s[0:1]
	s_cbranch_execz .LBB0_630
	s_waitcnt lgkmcnt(0)
	v_add_f32_e32 v68, v66, v67
	v_lshl_add_u64 v[66:67], v[86:87], 2, s[20:21]
	global_atomic_add_f32 v[66:67], v68, off
.LBB0_630:
	s_or_b64 exec, exec, s[4:5]
	v_or_b32_e32 v70, 64, v140
	v_mov_b32_e32 v71, v141
	s_waitcnt lgkmcnt(0)
	v_lshl_add_u64 v[66:67], v[70:71], 2, s[18:19]
	s_mov_b32 s99, 0
	s_mov_b32 s98, 0x50000
	v_lshl_add_u64 v[236:237], v[230:231], 0, s[98:99]
	global_load_dwordx4 v[204:207], v[236:237], off
	global_load_dwordx4 v[208:211], v[236:237], off offset:64
	global_load_dwordx4 v[212:215], v[236:237], off offset:128
	global_load_dwordx4 v[216:219], v[236:237], off offset:192
	s_mov_b32 s98, 0x28000
	v_lshl_add_u64 v[236:237], v[232:233], 0, s[98:99]
	global_load_dwordx2 v[220:221], v[236:237], off
	global_load_dwordx2 v[222:223], v[236:237], off offset:32
	global_load_dwordx2 v[224:225], v[236:237], off offset:64
	global_load_dwordx2 v[226:227], v[236:237], off offset:96
	s_mov_b32 s98, 0x140
	v_lshl_add_u64 v[236:237], v[234:235], 0, s[98:99]
	global_load_dword v229, v[236:237], off
	v_lshlrev_b64 v[66:67], 11, v[70:71]
	v_lshl_add_u64 v[68:69], s[14:15], 0, v[66:67]
	v_mov_b32_e32 v143, v139
	v_lshl_add_u64 v[76:77], v[68:69], 0, v[142:143]
	v_lshlrev_b64 v[68:69], 12, v[70:71]
	v_lshl_add_u64 v[68:69], v[134:135], 0, v[68:69]
	s_nop 0
	v_lshl_add_u64 v[66:67], s[16:17], 0, v[66:67]
	v_lshl_add_u64 v[72:73], v[68:69], 0, v[138:139]
	v_lshl_add_u64 v[74:75], v[66:67], 0, v[142:143]
	s_nop 0
	s_waitcnt vmcnt(15) lgkmcnt(0)
	v_mov_b32_e32 v80, v228
	v_mov_b32_e32 v78, v196
	v_mov_b32_e32 v79, v197
	v_mov_b32_e32 v66, v180
	v_mov_b32_e32 v67, v181
	v_mov_b32_e32 v68, v182
	v_mov_b32_e32 v69, v183
	v_fmamk_f32 v80, v80, 0x3a800000, v153
	v_mul_f32_e32 v81, 0x4b800000, v80
	v_cmp_gt_f32_e32 vcc, s56, v80
	s_nop 1
	v_cndmask_b32_e32 v81, v80, v81, vcc
	v_rsq_f32_e32 v82, v81
	v_lshlrev_b32_e32 v80, 16, v78
	v_and_b32_e32 v81, 0xffff0000, v78
	v_lshlrev_b32_e32 v78, 16, v79
	v_mul_f32_e32 v83, 0x45800000, v82
	v_cndmask_b32_e32 v82, v82, v83, vcc
	v_mul_f32_e32 v62, v62, v82
	v_mul_f32_e32 v63, v63, v82
	v_mul_f32_e32 v62, 0xbfb8aa3b, v62
	v_mul_f32_e32 v63, 0xbfb8aa3b, v63
	v_mul_f32_e32 v64, v64, v82
	v_mul_f32_e32 v65, v65, v82
	v_exp_f32_e32 v62, v62
	v_exp_f32_e32 v63, v63
	v_mul_f32_e32 v64, 0xbfb8aa3b, v64
	v_mul_f32_e32 v65, 0xbfb8aa3b, v65
	v_exp_f32_e32 v64, v64
	v_exp_f32_e32 v65, v65
	v_mul_f32_e32 v83, v58, v82
	v_mul_f32_e32 v84, v59, v82
	v_pk_add_f32 v[58:59], v[62:63], 1.0 op_sel_hi:[1,0]
	v_pk_add_f32 v[64:65], v[64:65], 1.0 op_sel_hi:[1,0]
	v_div_scale_f32 v62, s[4:5], v59, v59, 1.0
	v_div_scale_f32 v85, s[4:5], v58, v58, 1.0
	v_rcp_f32_e32 v91, v62
	v_div_scale_f32 v87, s[6:7], v65, v65, 1.0
	v_rcp_f32_e32 v92, v85
	v_div_scale_f32 v89, s[8:9], v64, v64, 1.0
	v_rcp_f32_e32 v93, v87
	v_rcp_f32_e32 v94, v89
	v_fma_f32 v95, -v62, v91, 1.0
	v_div_scale_f32 v63, vcc, 1.0, v59, 1.0
	v_fma_f32 v96, -v85, v92, 1.0
	v_fmac_f32_e32 v91, v95, v91
	v_div_scale_f32 v86, s[4:5], 1.0, v58, 1.0
	v_fma_f32 v97, -v87, v93, 1.0
	v_fmac_f32_e32 v92, v96, v92
	v_mul_f32_e32 v95, v63, v91
	v_div_scale_f32 v88, s[6:7], 1.0, v65, 1.0
	v_fma_f32 v98, -v89, v94, 1.0
	v_fmac_f32_e32 v93, v97, v93
	v_mul_f32_e32 v96, v86, v92
	v_fma_f32 v99, -v62, v95, v63
	v_div_scale_f32 v90, s[8:9], 1.0, v64, 1.0
	v_fmac_f32_e32 v94, v98, v94
	v_mul_f32_e32 v97, v88, v93
	v_fma_f32 v100, -v85, v96, v86
	v_fmac_f32_e32 v95, v99, v91
	v_mul_f32_e32 v98, v90, v94
	v_fma_f32 v101, -v87, v97, v88
	v_fmac_f32_e32 v96, v100, v92
	v_fma_f32 v62, -v62, v95, v63
	v_fma_f32 v102, -v89, v98, v90
	v_fmac_f32_e32 v97, v101, v93
	v_fma_f32 v63, -v85, v96, v86
	v_div_fmas_f32 v62, v62, v91, v95
	s_mov_b64 vcc, s[4:5]
	v_fmac_f32_e32 v98, v102, v94
	v_fma_f32 v85, -v87, v97, v88
	v_div_fixup_f32 v59, v62, v59, 1.0
	v_div_fmas_f32 v62, v63, v92, v96
	s_mov_b64 vcc, s[6:7]
	v_fma_f32 v86, -v89, v98, v90
	v_div_fixup_f32 v58, v62, v58, 1.0
	v_div_fmas_f32 v85, v85, v93, v97
	s_mov_b64 vcc, s[8:9]
	v_pk_fma_f32 v[62:63], v[58:59], v[80:81], v[66:67]
	v_div_fmas_f32 v58, v86, v94, v98
	v_and_b32_e32 v79, 0xffff0000, v79
	v_div_fixup_f32 v59, v85, v65, 1.0
	v_div_fixup_f32 v58, v58, v64, 1.0
	v_pk_fma_f32 v[64:65], v[58:59], v[78:79], v[68:69]
	global_store_dwordx4 v[72:73], v[62:65], off
	v_cvt_pk_bf16_f32 v66, v62, v63
	v_cvt_pk_bf16_f32 v67, v64, v65
	s_nop 0
	v_mul_f32_e32 v60, v60, v82
	v_mov_b32_e32 v238, v66
	v_mov_b32_e32 v239, v67
	s_nop 0
	v_mul_f32_e32 v61, v61, v82
	v_mul_f32_e32 v79, v55, v82
	v_mul_f32_e32 v85, v50, v82
	v_mul_f32_e32 v50, 0xbfb8aa3b, v83
	v_mul_f32_e32 v55, 0xbfb8aa3b, v84
	v_mul_f32_e32 v78, v54, v82
	v_mul_f32_e32 v80, v56, v82
	v_mul_f32_e32 v81, v57, v82
	v_mul_f32_e32 v56, 0xbfb8aa3b, v60
	v_mul_f32_e32 v57, 0xbfb8aa3b, v61
	v_exp_f32_e32 v54, v50
	v_exp_f32_e32 v55, v55
	v_exp_f32_e32 v56, v56
	v_exp_f32_e32 v57, v57
	v_mul_f32_e32 v83, v51, v82
	v_pk_add_f32 v[50:51], v[54:55], 1.0 op_sel_hi:[1,0]
	v_mul_f32_e32 v52, v52, v82
	v_pk_add_f32 v[54:55], v[56:57], 1.0 op_sel_hi:[1,0]
	v_div_scale_f32 v56, s[4:5], v51, v51, 1.0
	v_div_scale_f32 v60, s[4:5], v50, v50, 1.0
	v_rcp_f32_e32 v89, v56
	v_div_scale_f32 v84, s[6:7], v55, v55, 1.0
	v_rcp_f32_e32 v90, v60
	v_div_scale_f32 v87, s[8:9], v54, v54, 1.0
	v_rcp_f32_e32 v91, v84
	v_rcp_f32_e32 v92, v87
	v_fma_f32 v93, -v56, v89, 1.0
	v_div_scale_f32 v57, vcc, 1.0, v51, 1.0
	v_fma_f32 v94, -v60, v90, 1.0
	v_fmac_f32_e32 v89, v93, v89
	v_div_scale_f32 v61, s[4:5], 1.0, v50, 1.0
	v_fma_f32 v95, -v84, v91, 1.0
	v_fmac_f32_e32 v90, v94, v90
	v_mul_f32_e32 v93, v57, v89
	v_div_scale_f32 v86, s[6:7], 1.0, v55, 1.0
	v_fma_f32 v96, -v87, v92, 1.0
	v_fmac_f32_e32 v91, v95, v91
	v_mul_f32_e32 v94, v61, v90
	v_fma_f32 v97, -v56, v93, v57
	v_div_scale_f32 v88, s[8:9], 1.0, v54, 1.0
	v_fmac_f32_e32 v92, v96, v92
	v_mul_f32_e32 v95, v86, v91
	v_fma_f32 v98, -v60, v94, v61
	v_fmac_f32_e32 v93, v97, v89
	v_mul_f32_e32 v96, v88, v92
	v_fma_f32 v99, -v84, v95, v86
	v_fmac_f32_e32 v94, v98, v90
	v_fma_f32 v56, -v56, v93, v57
	v_fma_f32 v100, -v87, v96, v88
	v_fmac_f32_e32 v95, v99, v91
	v_fma_f32 v57, -v60, v94, v61
	v_div_fmas_f32 v56, v56, v89, v93
	s_mov_b64 vcc, s[4:5]
	v_fmac_f32_e32 v96, v100, v92
	v_fma_f32 v60, -v84, v95, v86
	v_div_fixup_f32 v51, v56, v51, 1.0
	v_div_fmas_f32 v56, v57, v90, v94
	s_mov_b64 vcc, s[6:7]
	v_fma_f32 v61, -v87, v96, v88
	v_div_fixup_f32 v50, v56, v50, 1.0
	v_div_fmas_f32 v56, v60, v91, v95
	s_mov_b64 vcc, s[8:9]
	v_div_fixup_f32 v57, v56, v55, 1.0
	v_div_fmas_f32 v55, v61, v92, v96
	v_div_fixup_f32 v56, v55, v54, 1.0
	v_mul_f32_e32 v53, v53, v82
	v_pk_mul_f32 v[62:63], v[62:63], v[62:63]
	s_waitcnt lgkmcnt(0)
	v_mov_b32_e32 v58, v198
	v_mov_b32_e32 v59, v199
	v_mov_b32_e32 v66, v184
	v_mov_b32_e32 v67, v185
	v_mov_b32_e32 v68, v186
	v_mov_b32_e32 v69, v187
	v_lshlrev_b32_e32 v54, 16, v58
	v_and_b32_e32 v55, 0xffff0000, v58
	v_lshlrev_b32_e32 v58, 16, v59
	v_and_b32_e32 v59, 0xffff0000, v59
	v_pk_fma_f32 v[54:55], v[50:51], v[54:55], v[66:67]
	v_pk_fma_f32 v[56:57], v[56:57], v[58:59], v[68:69]
	global_store_dwordx4 v[72:73], v[54:57], off offset:64
	v_cvt_pk_bf16_f32 v58, v54, v55
	v_cvt_pk_bf16_f32 v59, v56, v57
	s_nop 0
	v_mul_f32_e32 v66, 0xbfb8aa3b, v78
	v_mov_b32_e32 v240, v58
	v_mov_b32_e32 v241, v59
	v_mbcnt_lo_u32_b32 v242, -1, 0
	v_mbcnt_hi_u32_b32 v242, -1, v242
	v_and_b32_e32 v242, 16, v242
	v_lshrrev_b32_e32 v236, 1, v242
	v_add_u32_e32 v242, v242, v236
	v_mov_b32_e32 v243, 0
	v_lshl_add_u64 v[236:237], v[74:75], 0, v[242:243]
	v_permlane16_swap_b32_e32 v238, v240
	v_permlane16_swap_b32_e32 v239, v241
	global_store_dwordx4 v[236:237], v[238:241], off
	s_nop 0
	v_mul_f32_e32 v67, 0xbfb8aa3b, v79
	v_mul_f32_e32 v68, 0xbfb8aa3b, v80
	v_mul_f32_e32 v69, 0xbfb8aa3b, v81
	v_mul_f32_e32 v80, 0xbfb8aa3b, v52
	v_mul_f32_e32 v81, 0xbfb8aa3b, v53
	v_exp_f32_e32 v52, v66
	v_exp_f32_e32 v53, v67
	v_exp_f32_e32 v66, v68
	v_exp_f32_e32 v67, v69
	v_mul_f32_e32 v78, 0xbfb8aa3b, v85
	v_pk_add_f32 v[52:53], v[52:53], 1.0 op_sel_hi:[1,0]
	v_exp_f32_e32 v68, v78
	v_exp_f32_e32 v78, v80
	v_div_scale_f32 v80, s[4:5], v53, v53, 1.0
	v_pk_add_f32 v[66:67], v[66:67], 1.0 op_sel_hi:[1,0]
	v_div_scale_f32 v82, s[4:5], v52, v52, 1.0
	v_rcp_f32_e32 v88, v80
	v_div_scale_f32 v84, s[6:7], v67, v67, 1.0
	v_rcp_f32_e32 v89, v82
	v_div_scale_f32 v86, s[8:9], v66, v66, 1.0
	v_rcp_f32_e32 v90, v84
	v_rcp_f32_e32 v91, v86
	v_mul_f32_e32 v79, 0xbfb8aa3b, v83
	v_fma_f32 v92, -v80, v88, 1.0
	v_exp_f32_e32 v69, v79
	v_exp_f32_e32 v79, v81
	v_div_scale_f32 v81, vcc, 1.0, v53, 1.0
	v_fma_f32 v93, -v82, v89, 1.0
	v_fmac_f32_e32 v88, v92, v88
	v_div_scale_f32 v83, s[4:5], 1.0, v52, 1.0
	v_fma_f32 v94, -v84, v90, 1.0
	v_fmac_f32_e32 v89, v93, v89
	v_mul_f32_e32 v92, v81, v88
	v_div_scale_f32 v85, s[6:7], 1.0, v67, 1.0
	v_fma_f32 v95, -v86, v91, 1.0
	v_fmac_f32_e32 v90, v94, v90
	v_mul_f32_e32 v93, v83, v89
	v_fma_f32 v96, -v80, v92, v81
	v_div_scale_f32 v87, s[8:9], 1.0, v66, 1.0
	v_fmac_f32_e32 v91, v95, v91
	v_mul_f32_e32 v94, v85, v90
	v_fma_f32 v97, -v82, v93, v83
	v_fmac_f32_e32 v92, v96, v88
	v_mul_f32_e32 v95, v87, v91
	v_fma_f32 v98, -v84, v94, v85
	v_fmac_f32_e32 v93, v97, v89
	v_fma_f32 v80, -v80, v92, v81
	v_fma_f32 v99, -v86, v95, v87
	v_fmac_f32_e32 v94, v98, v90
	v_fma_f32 v81, -v82, v93, v83
	v_div_fmas_f32 v80, v80, v88, v92
	s_mov_b64 vcc, s[4:5]
	v_fmac_f32_e32 v95, v99, v91
	v_fma_f32 v82, -v84, v94, v85
	v_div_fixup_f32 v53, v80, v53, 1.0
	v_div_fmas_f32 v80, v81, v89, v93
	s_mov_b64 vcc, s[6:7]
	v_fma_f32 v83, -v86, v95, v87
	v_div_fixup_f32 v52, v80, v52, 1.0
	v_div_fmas_f32 v80, v82, v90, v94
	s_mov_b64 vcc, s[8:9]
	v_div_fixup_f32 v67, v80, v67, 1.0
	v_div_fmas_f32 v80, v83, v91, v95
	v_div_fixup_f32 v66, v80, v66, 1.0
	v_pk_add_f32 v[68:69], v[68:69], 1.0 op_sel_hi:[1,0]
	v_pk_mul_f32 v[54:55], v[54:55], v[54:55]
	v_pk_mul_f32 v[56:57], v[56:57], v[56:57]
	v_add_f32_e32 v54, v54, v55
	s_waitcnt lgkmcnt(0)
	v_mov_b32_e32 v50, v200
	v_mov_b32_e32 v51, v201
	v_mov_b32_e32 v58, v188
	v_mov_b32_e32 v59, v189
	v_mov_b32_e32 v60, v190
	v_mov_b32_e32 v61, v191
	v_lshlrev_b32_e32 v80, 16, v50
	v_and_b32_e32 v81, 0xffff0000, v50
	v_lshlrev_b32_e32 v82, 16, v51
	v_and_b32_e32 v83, 0xffff0000, v51
	v_pk_fma_f32 v[50:51], v[52:53], v[80:81], v[58:59]
	v_pk_fma_f32 v[52:53], v[66:67], v[82:83], v[60:61]
	global_store_dwordx4 v[72:73], v[50:53], off offset:128
	v_cvt_pk_bf16_f32 v58, v50, v51
	v_cvt_pk_bf16_f32 v59, v52, v53
	s_nop 0
	v_pk_add_f32 v[76:77], v[78:79], 1.0 op_sel_hi:[1,0]
	v_mov_b32_e32 v238, v58
	v_mov_b32_e32 v239, v59
	s_nop 0
	v_div_scale_f32 v78, s[4:5], v69, v69, 1.0
	v_div_scale_f32 v80, s[4:5], v68, v68, 1.0
	v_div_scale_f32 v82, s[6:7], v77, v77, 1.0
	v_rcp_f32_e32 v86, v78
	v_rcp_f32_e32 v87, v80
	v_rcp_f32_e32 v88, v82
	v_div_scale_f32 v84, s[8:9], v76, v76, 1.0
	v_rcp_f32_e32 v89, v84
	v_fma_f32 v90, -v78, v86, 1.0
	v_fma_f32 v91, -v80, v87, 1.0
	v_fma_f32 v92, -v82, v88, 1.0
	v_div_scale_f32 v79, vcc, 1.0, v69, 1.0
	v_div_scale_f32 v81, s[4:5], 1.0, v68, 1.0
	v_div_scale_f32 v83, s[6:7], 1.0, v77, 1.0
	v_fmac_f32_e32 v86, v90, v86
	v_fmac_f32_e32 v87, v91, v87
	v_fmac_f32_e32 v88, v92, v88
	v_mul_f32_e32 v90, v79, v86
	v_mul_f32_e32 v91, v81, v87
	v_mul_f32_e32 v92, v83, v88
	v_fma_f32 v94, -v78, v90, v79
	v_fma_f32 v95, -v80, v91, v81
	v_fma_f32 v96, -v82, v92, v83
	v_fma_f32 v93, -v84, v89, 1.0
	v_fmac_f32_e32 v90, v94, v86
	v_fmac_f32_e32 v91, v95, v87
	v_fmac_f32_e32 v92, v96, v88
	v_div_scale_f32 v85, s[8:9], 1.0, v76, 1.0
	v_fmac_f32_e32 v89, v93, v89
	v_fma_f32 v78, -v78, v90, v79
	v_fma_f32 v79, -v80, v91, v81
	v_fma_f32 v80, -v82, v92, v83
	v_add_f32_e32 v82, v62, v63
	v_pk_mul_f32 v[62:63], v[64:65], v[64:65]
	v_mul_f32_e32 v93, v85, v89
	v_add_f32_e32 v62, v62, v82
	v_fma_f32 v97, -v84, v93, v85
	v_add_f32_e32 v82, v63, v62
	v_div_fmas_f32 v62, v78, v86, v90
	s_mov_b64 vcc, s[4:5]
	v_pk_mul_f32 v[50:51], v[50:51], v[50:51]
	v_fmac_f32_e32 v93, v97, v89
	v_div_fixup_f32 v63, v62, v69, 1.0
	v_div_fmas_f32 v62, v79, v87, v91
	s_mov_b64 vcc, s[6:7]
	v_pk_mul_f32 v[52:53], v[52:53], v[52:53]
	v_add_f32_e32 v50, v50, v51
	v_fma_f32 v81, -v84, v93, v85
	v_div_fmas_f32 v64, v80, v88, v92
	s_mov_b64 vcc, s[8:9]
	v_add_f32_e32 v54, v56, v54
	v_add_f32_e32 v50, v52, v50
	v_div_fixup_f32 v62, v62, v68, 1.0
	v_div_fixup_f32 v65, v64, v77, 1.0
	v_div_fmas_f32 v64, v81, v89, v93
	v_add_f32_e32 v54, v57, v54
	v_add_f32_e32 v69, v53, v50
	v_div_fixup_f32 v64, v64, v76, 1.0
	v_add_f32_e32 v68, v82, v54
	s_waitcnt lgkmcnt(0)
	v_mov_b32_e32 v66, v202
	v_mov_b32_e32 v67, v203
	v_mov_b32_e32 v58, v192
	v_mov_b32_e32 v59, v193
	v_mov_b32_e32 v60, v194
	v_mov_b32_e32 v61, v195
	v_lshlrev_b32_e32 v50, 16, v66
	v_and_b32_e32 v51, 0xffff0000, v66
	v_lshlrev_b32_e32 v54, 16, v67
	v_and_b32_e32 v55, 0xffff0000, v67
	v_pk_fma_f32 v[52:53], v[62:63], v[50:51], v[58:59]
	v_pk_fma_f32 v[54:55], v[64:65], v[54:55], v[60:61]
	v_pk_mul_f32 v[50:51], v[52:53], v[52:53]
	v_pk_mul_f32 v[56:57], v[54:55], v[54:55]
	v_add_f32_e32 v50, v50, v51
	v_add_f32_e32 v50, v56, v50
	v_add_f32_e32 v58, v68, v69
	v_add_f32_e32 v50, v57, v50
	v_add_f32_e32 v50, v58, v50
	ds_bpermute_b32 v51, v126, v50
	global_store_dwordx4 v[72:73], v[52:55], off offset:192
	s_waitcnt lgkmcnt(0)
	v_add_f32_e32 v50, v50, v51
	ds_bpermute_b32 v51, v127, v50
	v_cvt_pk_bf16_f32 v52, v52, v53
	v_cvt_pk_bf16_f32 v53, v54, v55
	v_mov_b32_e32 v240, v52
	v_mov_b32_e32 v241, v53
	s_nop 1
	v_lshl_add_u64 v[236:237], v[74:75], 0, v[242:243]
	v_permlane16_swap_b32_e32 v238, v240
	v_permlane16_swap_b32_e32 v239, v241
	global_store_dwordx4 v[236:237], v[238:241], off offset:64
	s_and_saveexec_b64 s[4:5], s[0:1]
	s_cbranch_execz .LBB0_632
	s_waitcnt lgkmcnt(0)
	v_add_f32_e32 v52, v50, v51
	v_lshl_add_u64 v[50:51], v[70:71], 2, s[20:21]
	global_atomic_add_f32 v[50:51], v52, off
.LBB0_632:
	s_or_b64 exec, exec, s[4:5]
	v_or_b32_e32 v54, 0x50, v140
	v_mov_b32_e32 v55, v141
	s_waitcnt lgkmcnt(0)
	v_lshl_add_u64 v[50:51], v[54:55], 2, s[18:19]
	s_mov_b32 s99, 0
	s_mov_b32 s98, 0x60000
	v_lshl_add_u64 v[236:237], v[230:231], 0, s[98:99]
	global_load_dwordx4 v[180:183], v[236:237], off
	global_load_dwordx4 v[184:187], v[236:237], off offset:64
	global_load_dwordx4 v[188:191], v[236:237], off offset:128
	global_load_dwordx4 v[192:195], v[236:237], off offset:192
	s_mov_b32 s98, 0x30000
	v_lshl_add_u64 v[236:237], v[232:233], 0, s[98:99]
	global_load_dwordx2 v[196:197], v[236:237], off
	global_load_dwordx2 v[198:199], v[236:237], off offset:32
	global_load_dwordx2 v[200:201], v[236:237], off offset:64
	global_load_dwordx2 v[202:203], v[236:237], off offset:96
	s_mov_b32 s98, 0x180
	v_lshl_add_u64 v[236:237], v[234:235], 0, s[98:99]
	global_load_dword v228, v[236:237], off
	v_lshlrev_b64 v[50:51], 11, v[54:55]
	v_lshl_add_u64 v[52:53], s[14:15], 0, v[50:51]
	v_lshl_add_u64 v[60:61], v[52:53], 0, v[142:143]
	v_lshlrev_b64 v[52:53], 12, v[54:55]
	v_lshl_add_u64 v[52:53], v[134:135], 0, v[52:53]
	s_nop 0
	v_lshl_add_u64 v[50:51], s[16:17], 0, v[50:51]
	v_lshl_add_u64 v[56:57], v[52:53], 0, v[138:139]
	v_lshl_add_u64 v[58:59], v[50:51], 0, v[142:143]
	s_nop 0
	s_waitcnt vmcnt(15) lgkmcnt(0)
	v_mov_b32_e32 v64, v229
	v_mov_b32_e32 v62, v220
	v_mov_b32_e32 v63, v221
	v_mov_b32_e32 v50, v204
	v_mov_b32_e32 v51, v205
	v_mov_b32_e32 v52, v206
	v_mov_b32_e32 v53, v207
	v_fmamk_f32 v64, v64, 0x3a800000, v153
	v_mul_f32_e32 v65, 0x4b800000, v64
	v_cmp_gt_f32_e32 vcc, s56, v64
	s_nop 1
	v_cndmask_b32_e32 v65, v64, v65, vcc
	v_rsq_f32_e32 v66, v65
	v_lshlrev_b32_e32 v64, 16, v62
	v_and_b32_e32 v65, 0xffff0000, v62
	v_lshlrev_b32_e32 v62, 16, v63
	v_mul_f32_e32 v67, 0x45800000, v66
	v_cndmask_b32_e32 v66, v66, v67, vcc
	v_mul_f32_e32 v46, v46, v66
	v_mul_f32_e32 v47, v47, v66
	v_mul_f32_e32 v46, 0xbfb8aa3b, v46
	v_mul_f32_e32 v47, 0xbfb8aa3b, v47
	v_mul_f32_e32 v48, v48, v66
	v_mul_f32_e32 v49, v49, v66
	v_exp_f32_e32 v46, v46
	v_exp_f32_e32 v47, v47
	v_mul_f32_e32 v48, 0xbfb8aa3b, v48
	v_mul_f32_e32 v49, 0xbfb8aa3b, v49
	v_exp_f32_e32 v48, v48
	v_exp_f32_e32 v49, v49
	v_mul_f32_e32 v67, v42, v66
	v_mul_f32_e32 v68, v43, v66
	v_pk_add_f32 v[42:43], v[46:47], 1.0 op_sel_hi:[1,0]
	v_pk_add_f32 v[48:49], v[48:49], 1.0 op_sel_hi:[1,0]
	v_div_scale_f32 v46, s[4:5], v43, v43, 1.0
	v_div_scale_f32 v69, s[4:5], v42, v42, 1.0
	v_rcp_f32_e32 v75, v46
	v_div_scale_f32 v71, s[6:7], v49, v49, 1.0
	v_rcp_f32_e32 v76, v69
	v_div_scale_f32 v73, s[8:9], v48, v48, 1.0
	v_rcp_f32_e32 v77, v71
	v_rcp_f32_e32 v78, v73
	v_fma_f32 v79, -v46, v75, 1.0
	v_div_scale_f32 v47, vcc, 1.0, v43, 1.0
	v_fma_f32 v80, -v69, v76, 1.0
	v_fmac_f32_e32 v75, v79, v75
	v_div_scale_f32 v70, s[4:5], 1.0, v42, 1.0
	v_fma_f32 v81, -v71, v77, 1.0
	v_fmac_f32_e32 v76, v80, v76
	v_mul_f32_e32 v79, v47, v75
	v_div_scale_f32 v72, s[6:7], 1.0, v49, 1.0
	v_fma_f32 v82, -v73, v78, 1.0
	v_fmac_f32_e32 v77, v81, v77
	v_mul_f32_e32 v80, v70, v76
	v_fma_f32 v83, -v46, v79, v47
	v_div_scale_f32 v74, s[8:9], 1.0, v48, 1.0
	v_fmac_f32_e32 v78, v82, v78
	v_mul_f32_e32 v81, v72, v77
	v_fma_f32 v84, -v69, v80, v70
	v_fmac_f32_e32 v79, v83, v75
	v_mul_f32_e32 v82, v74, v78
	v_fma_f32 v85, -v71, v81, v72
	v_fmac_f32_e32 v80, v84, v76
	v_fma_f32 v46, -v46, v79, v47
	v_fma_f32 v86, -v73, v82, v74
	v_fmac_f32_e32 v81, v85, v77
	v_fma_f32 v47, -v69, v80, v70
	v_div_fmas_f32 v46, v46, v75, v79
	s_mov_b64 vcc, s[4:5]
	v_fmac_f32_e32 v82, v86, v78
	v_fma_f32 v69, -v71, v81, v72
	v_div_fixup_f32 v43, v46, v43, 1.0
	v_div_fmas_f32 v46, v47, v76, v80
	s_mov_b64 vcc, s[6:7]
	v_fma_f32 v70, -v73, v82, v74
	v_div_fixup_f32 v42, v46, v42, 1.0
	v_div_fmas_f32 v69, v69, v77, v81
	s_mov_b64 vcc, s[8:9]
	v_pk_fma_f32 v[46:47], v[42:43], v[64:65], v[50:51]
	v_div_fmas_f32 v42, v70, v78, v82
	v_and_b32_e32 v63, 0xffff0000, v63
	v_div_fixup_f32 v43, v69, v49, 1.0
	v_div_fixup_f32 v42, v42, v48, 1.0
	v_pk_fma_f32 v[48:49], v[42:43], v[62:63], v[52:53]
	global_store_dwordx4 v[56:57], v[46:49], off
	v_cvt_pk_bf16_f32 v50, v46, v47
	v_cvt_pk_bf16_f32 v51, v48, v49
	s_nop 0
	v_mul_f32_e32 v44, v44, v66
	v_mov_b32_e32 v238, v50
	v_mov_b32_e32 v239, v51
	s_nop 0
	v_mul_f32_e32 v45, v45, v66
	v_mul_f32_e32 v63, v39, v66
	v_mul_f32_e32 v69, v34, v66
	v_mul_f32_e32 v34, 0xbfb8aa3b, v67
	v_mul_f32_e32 v39, 0xbfb8aa3b, v68
	v_mul_f32_e32 v62, v38, v66
	v_mul_f32_e32 v64, v40, v66
	v_mul_f32_e32 v65, v41, v66
	v_mul_f32_e32 v40, 0xbfb8aa3b, v44
	v_mul_f32_e32 v41, 0xbfb8aa3b, v45
	v_exp_f32_e32 v38, v34
	v_exp_f32_e32 v39, v39
	v_exp_f32_e32 v40, v40
	v_exp_f32_e32 v41, v41
	v_mul_f32_e32 v67, v35, v66
	v_pk_add_f32 v[34:35], v[38:39], 1.0 op_sel_hi:[1,0]
	v_mul_f32_e32 v36, v36, v66
	v_pk_add_f32 v[38:39], v[40:41], 1.0 op_sel_hi:[1,0]
	v_div_scale_f32 v40, s[4:5], v35, v35, 1.0
	v_div_scale_f32 v44, s[4:5], v34, v34, 1.0
	v_rcp_f32_e32 v73, v40
	v_div_scale_f32 v68, s[6:7], v39, v39, 1.0
	v_rcp_f32_e32 v74, v44
	v_div_scale_f32 v71, s[8:9], v38, v38, 1.0
	v_rcp_f32_e32 v75, v68
	v_rcp_f32_e32 v76, v71
	v_fma_f32 v77, -v40, v73, 1.0
	v_div_scale_f32 v41, vcc, 1.0, v35, 1.0
	v_fma_f32 v78, -v44, v74, 1.0
	v_fmac_f32_e32 v73, v77, v73
	v_div_scale_f32 v45, s[4:5], 1.0, v34, 1.0
	v_fma_f32 v79, -v68, v75, 1.0
	v_fmac_f32_e32 v74, v78, v74
	v_mul_f32_e32 v77, v41, v73
	v_div_scale_f32 v70, s[6:7], 1.0, v39, 1.0
	v_fma_f32 v80, -v71, v76, 1.0
	v_fmac_f32_e32 v75, v79, v75
	v_mul_f32_e32 v78, v45, v74
	v_fma_f32 v81, -v40, v77, v41
	v_div_scale_f32 v72, s[8:9], 1.0, v38, 1.0
	v_fmac_f32_e32 v76, v80, v76
	v_mul_f32_e32 v79, v70, v75
	v_fma_f32 v82, -v44, v78, v45
	v_fmac_f32_e32 v77, v81, v73
	v_mul_f32_e32 v80, v72, v76
	v_fma_f32 v83, -v68, v79, v70
	v_fmac_f32_e32 v78, v82, v74
	v_fma_f32 v40, -v40, v77, v41
	v_fma_f32 v84, -v71, v80, v72
	v_fmac_f32_e32 v79, v83, v75
	v_fma_f32 v41, -v44, v78, v45
	v_div_fmas_f32 v40, v40, v73, v77
	s_mov_b64 vcc, s[4:5]
	v_fmac_f32_e32 v80, v84, v76
	v_fma_f32 v44, -v68, v79, v70
	v_div_fixup_f32 v35, v40, v35, 1.0
	v_div_fmas_f32 v40, v41, v74, v78
	s_mov_b64 vcc, s[6:7]
	v_fma_f32 v45, -v71, v80, v72
	v_div_fixup_f32 v34, v40, v34, 1.0
	v_div_fmas_f32 v40, v44, v75, v79
	s_mov_b64 vcc, s[8:9]
	v_div_fixup_f32 v41, v40, v39, 1.0
	v_div_fmas_f32 v39, v45, v76, v80
	v_div_fixup_f32 v40, v39, v38, 1.0
	v_mul_f32_e32 v37, v37, v66
	v_pk_mul_f32 v[46:47], v[46:47], v[46:47]
	s_waitcnt lgkmcnt(0)
	v_mov_b32_e32 v42, v222
	v_mov_b32_e32 v43, v223
	v_mov_b32_e32 v50, v208
	v_mov_b32_e32 v51, v209
	v_mov_b32_e32 v52, v210
	v_mov_b32_e32 v53, v211
	v_lshlrev_b32_e32 v38, 16, v42
	v_and_b32_e32 v39, 0xffff0000, v42
	v_lshlrev_b32_e32 v42, 16, v43
	v_and_b32_e32 v43, 0xffff0000, v43
	v_pk_fma_f32 v[38:39], v[34:35], v[38:39], v[50:51]
	v_pk_fma_f32 v[40:41], v[40:41], v[42:43], v[52:53]
	global_store_dwordx4 v[56:57], v[38:41], off offset:64
	v_cvt_pk_bf16_f32 v42, v38, v39
	v_cvt_pk_bf16_f32 v43, v40, v41
	s_nop 0
	v_mul_f32_e32 v50, 0xbfb8aa3b, v62
	v_mov_b32_e32 v240, v42
	v_mov_b32_e32 v241, v43
	v_mbcnt_lo_u32_b32 v242, -1, 0
	v_mbcnt_hi_u32_b32 v242, -1, v242
	v_and_b32_e32 v242, 16, v242
	v_lshrrev_b32_e32 v236, 1, v242
	v_add_u32_e32 v242, v242, v236
	v_mov_b32_e32 v243, 0
	v_lshl_add_u64 v[236:237], v[58:59], 0, v[242:243]
	v_permlane16_swap_b32_e32 v238, v240
	v_permlane16_swap_b32_e32 v239, v241
	global_store_dwordx4 v[236:237], v[238:241], off
	s_nop 0
	v_mul_f32_e32 v51, 0xbfb8aa3b, v63
	v_mul_f32_e32 v52, 0xbfb8aa3b, v64
	v_mul_f32_e32 v53, 0xbfb8aa3b, v65
	v_mul_f32_e32 v64, 0xbfb8aa3b, v36
	v_mul_f32_e32 v65, 0xbfb8aa3b, v37
	v_exp_f32_e32 v36, v50
	v_exp_f32_e32 v37, v51
	v_exp_f32_e32 v50, v52
	v_exp_f32_e32 v51, v53
	v_mul_f32_e32 v62, 0xbfb8aa3b, v69
	v_pk_add_f32 v[36:37], v[36:37], 1.0 op_sel_hi:[1,0]
	v_exp_f32_e32 v52, v62
	v_exp_f32_e32 v62, v64
	v_div_scale_f32 v64, s[4:5], v37, v37, 1.0
	v_pk_add_f32 v[50:51], v[50:51], 1.0 op_sel_hi:[1,0]
	v_div_scale_f32 v66, s[4:5], v36, v36, 1.0
	v_rcp_f32_e32 v72, v64
	v_div_scale_f32 v68, s[6:7], v51, v51, 1.0
	v_rcp_f32_e32 v73, v66
	v_div_scale_f32 v70, s[8:9], v50, v50, 1.0
	v_rcp_f32_e32 v74, v68
	v_rcp_f32_e32 v75, v70
	v_mul_f32_e32 v63, 0xbfb8aa3b, v67
	v_fma_f32 v76, -v64, v72, 1.0
	v_exp_f32_e32 v53, v63
	v_exp_f32_e32 v63, v65
	v_div_scale_f32 v65, vcc, 1.0, v37, 1.0
	v_fma_f32 v77, -v66, v73, 1.0
	v_fmac_f32_e32 v72, v76, v72
	v_div_scale_f32 v67, s[4:5], 1.0, v36, 1.0
	v_fma_f32 v78, -v68, v74, 1.0
	v_fmac_f32_e32 v73, v77, v73
	v_mul_f32_e32 v76, v65, v72
	v_div_scale_f32 v69, s[6:7], 1.0, v51, 1.0
	v_fma_f32 v79, -v70, v75, 1.0
	v_fmac_f32_e32 v74, v78, v74
	v_mul_f32_e32 v77, v67, v73
	v_fma_f32 v80, -v64, v76, v65
	v_div_scale_f32 v71, s[8:9], 1.0, v50, 1.0
	v_fmac_f32_e32 v75, v79, v75
	v_mul_f32_e32 v78, v69, v74
	v_fma_f32 v81, -v66, v77, v67
	v_fmac_f32_e32 v76, v80, v72
	v_mul_f32_e32 v79, v71, v75
	v_fma_f32 v82, -v68, v78, v69
	v_fmac_f32_e32 v77, v81, v73
	v_fma_f32 v64, -v64, v76, v65
	v_fma_f32 v83, -v70, v79, v71
	v_fmac_f32_e32 v78, v82, v74
	v_fma_f32 v65, -v66, v77, v67
	v_div_fmas_f32 v64, v64, v72, v76
	s_mov_b64 vcc, s[4:5]
	v_fmac_f32_e32 v79, v83, v75
	v_fma_f32 v66, -v68, v78, v69
	v_div_fixup_f32 v37, v64, v37, 1.0
	v_div_fmas_f32 v64, v65, v73, v77
	s_mov_b64 vcc, s[6:7]
	v_fma_f32 v67, -v70, v79, v71
	v_div_fixup_f32 v36, v64, v36, 1.0
	v_div_fmas_f32 v64, v66, v74, v78
	s_mov_b64 vcc, s[8:9]
	v_div_fixup_f32 v51, v64, v51, 1.0
	v_div_fmas_f32 v64, v67, v75, v79
	v_div_fixup_f32 v50, v64, v50, 1.0
	v_pk_add_f32 v[52:53], v[52:53], 1.0 op_sel_hi:[1,0]
	v_pk_mul_f32 v[38:39], v[38:39], v[38:39]
	v_pk_mul_f32 v[40:41], v[40:41], v[40:41]
	v_add_f32_e32 v38, v38, v39
	s_waitcnt lgkmcnt(0)
	v_mov_b32_e32 v34, v224
	v_mov_b32_e32 v35, v225
	v_mov_b32_e32 v42, v212
	v_mov_b32_e32 v43, v213
	v_mov_b32_e32 v44, v214
	v_mov_b32_e32 v45, v215
	v_lshlrev_b32_e32 v64, 16, v34
	v_and_b32_e32 v65, 0xffff0000, v34
	v_lshlrev_b32_e32 v66, 16, v35
	v_and_b32_e32 v67, 0xffff0000, v35
	v_pk_fma_f32 v[34:35], v[36:37], v[64:65], v[42:43]
	v_pk_fma_f32 v[36:37], v[50:51], v[66:67], v[44:45]
	global_store_dwordx4 v[56:57], v[34:37], off offset:128
	v_cvt_pk_bf16_f32 v42, v34, v35
	v_cvt_pk_bf16_f32 v43, v36, v37
	s_nop 0
	v_pk_add_f32 v[60:61], v[62:63], 1.0 op_sel_hi:[1,0]
	v_mov_b32_e32 v238, v42
	v_mov_b32_e32 v239, v43
	s_nop 0
	v_div_scale_f32 v62, s[4:5], v53, v53, 1.0
	v_div_scale_f32 v64, s[4:5], v52, v52, 1.0
	v_div_scale_f32 v66, s[6:7], v61, v61, 1.0
	v_rcp_f32_e32 v70, v62
	v_rcp_f32_e32 v71, v64
	v_rcp_f32_e32 v72, v66
	v_div_scale_f32 v68, s[8:9], v60, v60, 1.0
	v_rcp_f32_e32 v73, v68
	v_fma_f32 v74, -v62, v70, 1.0
	v_fma_f32 v75, -v64, v71, 1.0
	v_fma_f32 v76, -v66, v72, 1.0
	v_div_scale_f32 v63, vcc, 1.0, v53, 1.0
	v_div_scale_f32 v65, s[4:5], 1.0, v52, 1.0
	v_div_scale_f32 v67, s[6:7], 1.0, v61, 1.0
	v_fmac_f32_e32 v70, v74, v70
	v_fmac_f32_e32 v71, v75, v71
	v_fmac_f32_e32 v72, v76, v72
	v_mul_f32_e32 v74, v63, v70
	v_mul_f32_e32 v75, v65, v71
	v_mul_f32_e32 v76, v67, v72
	v_fma_f32 v78, -v62, v74, v63
	v_fma_f32 v79, -v64, v75, v65
	v_fma_f32 v80, -v66, v76, v67
	v_fma_f32 v77, -v68, v73, 1.0
	v_fmac_f32_e32 v74, v78, v70
	v_fmac_f32_e32 v75, v79, v71
	v_fmac_f32_e32 v76, v80, v72
	v_div_scale_f32 v69, s[8:9], 1.0, v60, 1.0
	v_fmac_f32_e32 v73, v77, v73
	v_fma_f32 v62, -v62, v74, v63
	v_fma_f32 v63, -v64, v75, v65
	v_fma_f32 v64, -v66, v76, v67
	v_add_f32_e32 v66, v46, v47
	v_pk_mul_f32 v[46:47], v[48:49], v[48:49]
	v_mul_f32_e32 v77, v69, v73
	v_add_f32_e32 v46, v46, v66
	v_fma_f32 v81, -v68, v77, v69
	v_add_f32_e32 v66, v47, v46
	v_div_fmas_f32 v46, v62, v70, v74
	s_mov_b64 vcc, s[4:5]
	v_pk_mul_f32 v[34:35], v[34:35], v[34:35]
	v_fmac_f32_e32 v77, v81, v73
	v_div_fixup_f32 v47, v46, v53, 1.0
	v_div_fmas_f32 v46, v63, v71, v75
	s_mov_b64 vcc, s[6:7]
	v_pk_mul_f32 v[36:37], v[36:37], v[36:37]
	v_add_f32_e32 v34, v34, v35
	v_fma_f32 v65, -v68, v77, v69
	v_div_fmas_f32 v48, v64, v72, v76
	s_mov_b64 vcc, s[8:9]
	v_add_f32_e32 v38, v40, v38
	v_add_f32_e32 v34, v36, v34
	v_div_fixup_f32 v46, v46, v52, 1.0
	v_div_fixup_f32 v49, v48, v61, 1.0
	v_div_fmas_f32 v48, v65, v73, v77
	v_add_f32_e32 v38, v41, v38
	v_add_f32_e32 v53, v37, v34
	v_div_fixup_f32 v48, v48, v60, 1.0
	v_add_f32_e32 v52, v66, v38
	s_waitcnt lgkmcnt(0)
	v_mov_b32_e32 v50, v226
	v_mov_b32_e32 v51, v227
	v_mov_b32_e32 v42, v216
	v_mov_b32_e32 v43, v217
	v_mov_b32_e32 v44, v218
	v_mov_b32_e32 v45, v219
	v_lshlrev_b32_e32 v34, 16, v50
	v_and_b32_e32 v35, 0xffff0000, v50
	v_lshlrev_b32_e32 v38, 16, v51
	v_and_b32_e32 v39, 0xffff0000, v51
	v_pk_fma_f32 v[36:37], v[46:47], v[34:35], v[42:43]
	v_pk_fma_f32 v[38:39], v[48:49], v[38:39], v[44:45]
	v_pk_mul_f32 v[34:35], v[36:37], v[36:37]
	v_pk_mul_f32 v[40:41], v[38:39], v[38:39]
	v_add_f32_e32 v34, v34, v35
	v_add_f32_e32 v34, v40, v34
	v_add_f32_e32 v42, v52, v53
	v_add_f32_e32 v34, v41, v34
	v_add_f32_e32 v34, v42, v34
	ds_bpermute_b32 v35, v126, v34
	global_store_dwordx4 v[56:57], v[36:39], off offset:192
	s_waitcnt lgkmcnt(0)
	v_add_f32_e32 v34, v34, v35
	ds_bpermute_b32 v35, v127, v34
	v_cvt_pk_bf16_f32 v36, v36, v37
	v_cvt_pk_bf16_f32 v37, v38, v39
	v_mov_b32_e32 v240, v36
	v_mov_b32_e32 v241, v37
	s_nop 1
	v_lshl_add_u64 v[236:237], v[58:59], 0, v[242:243]
	v_permlane16_swap_b32_e32 v238, v240
	v_permlane16_swap_b32_e32 v239, v241
	global_store_dwordx4 v[236:237], v[238:241], off offset:64
	s_and_saveexec_b64 s[4:5], s[0:1]
	s_cbranch_execz .LBB0_634
	s_waitcnt lgkmcnt(0)
	v_add_f32_e32 v36, v34, v35
	v_lshl_add_u64 v[34:35], v[54:55], 2, s[20:21]
	global_atomic_add_f32 v[34:35], v36, off
.LBB0_634:
	s_or_b64 exec, exec, s[4:5]
	v_or_b32_e32 v38, 0x60, v140
	v_mov_b32_e32 v39, v141
	s_waitcnt lgkmcnt(0)
	v_lshl_add_u64 v[34:35], v[38:39], 2, s[18:19]
	s_mov_b32 s99, 0
	s_mov_b32 s98, 0x70000
	v_lshl_add_u64 v[236:237], v[230:231], 0, s[98:99]
	global_load_dwordx4 v[204:207], v[236:237], off
	global_load_dwordx4 v[208:211], v[236:237], off offset:64
	global_load_dwordx4 v[212:215], v[236:237], off offset:128
	global_load_dwordx4 v[216:219], v[236:237], off offset:192
	s_mov_b32 s98, 0x38000
	v_lshl_add_u64 v[236:237], v[232:233], 0, s[98:99]
	global_load_dwordx2 v[220:221], v[236:237], off
	global_load_dwordx2 v[222:223], v[236:237], off offset:32
	global_load_dwordx2 v[224:225], v[236:237], off offset:64
	global_load_dwordx2 v[226:227], v[236:237], off offset:96
	s_mov_b32 s98, 0x1c0
	v_lshl_add_u64 v[236:237], v[234:235], 0, s[98:99]
	global_load_dword v229, v[236:237], off
	v_lshlrev_b64 v[34:35], 11, v[38:39]
	v_lshl_add_u64 v[36:37], s[14:15], 0, v[34:35]
	v_mov_b32_e32 v143, v139
	v_lshl_add_u64 v[44:45], v[36:37], 0, v[142:143]
	v_lshlrev_b64 v[36:37], 12, v[38:39]
	v_lshl_add_u64 v[36:37], v[134:135], 0, v[36:37]
	s_nop 0
	v_lshl_add_u64 v[34:35], s[16:17], 0, v[34:35]
	v_lshl_add_u64 v[40:41], v[36:37], 0, v[138:139]
	v_lshl_add_u64 v[42:43], v[34:35], 0, v[142:143]
	s_nop 0
	s_waitcnt vmcnt(15) lgkmcnt(0)
	v_mov_b32_e32 v48, v228
	v_mov_b32_e32 v46, v196
	v_mov_b32_e32 v47, v197
	v_mov_b32_e32 v34, v180
	v_mov_b32_e32 v35, v181
	v_mov_b32_e32 v36, v182
	v_mov_b32_e32 v37, v183
	v_fmamk_f32 v48, v48, 0x3a800000, v153
	v_mul_f32_e32 v49, 0x4b800000, v48
	v_cmp_gt_f32_e32 vcc, s56, v48
	s_nop 1
	v_cndmask_b32_e32 v49, v48, v49, vcc
	v_rsq_f32_e32 v50, v49
	v_lshlrev_b32_e32 v48, 16, v46
	v_and_b32_e32 v49, 0xffff0000, v46
	v_lshlrev_b32_e32 v46, 16, v47
	v_mul_f32_e32 v51, 0x45800000, v50
	v_cndmask_b32_e32 v50, v50, v51, vcc
	v_mul_f32_e32 v30, v30, v50
	v_mul_f32_e32 v31, v31, v50
	v_mul_f32_e32 v30, 0xbfb8aa3b, v30
	v_mul_f32_e32 v31, 0xbfb8aa3b, v31
	v_mul_f32_e32 v32, v32, v50
	v_mul_f32_e32 v33, v33, v50
	v_exp_f32_e32 v30, v30
	v_exp_f32_e32 v31, v31
	v_mul_f32_e32 v32, 0xbfb8aa3b, v32
	v_mul_f32_e32 v33, 0xbfb8aa3b, v33
	v_exp_f32_e32 v32, v32
	v_exp_f32_e32 v33, v33
	v_mul_f32_e32 v51, v26, v50
	v_mul_f32_e32 v52, v27, v50
	v_pk_add_f32 v[26:27], v[30:31], 1.0 op_sel_hi:[1,0]
	v_pk_add_f32 v[32:33], v[32:33], 1.0 op_sel_hi:[1,0]
	v_div_scale_f32 v30, s[4:5], v27, v27, 1.0
	v_div_scale_f32 v53, s[4:5], v26, v26, 1.0
	v_rcp_f32_e32 v59, v30
	v_div_scale_f32 v55, s[6:7], v33, v33, 1.0
	v_rcp_f32_e32 v60, v53
	v_div_scale_f32 v57, s[8:9], v32, v32, 1.0
	v_rcp_f32_e32 v61, v55
	v_rcp_f32_e32 v62, v57
	v_fma_f32 v63, -v30, v59, 1.0
	v_div_scale_f32 v31, vcc, 1.0, v27, 1.0
	v_fma_f32 v64, -v53, v60, 1.0
	v_fmac_f32_e32 v59, v63, v59
	v_div_scale_f32 v54, s[4:5], 1.0, v26, 1.0
	v_fma_f32 v65, -v55, v61, 1.0
	v_fmac_f32_e32 v60, v64, v60
	v_mul_f32_e32 v63, v31, v59
	v_div_scale_f32 v56, s[6:7], 1.0, v33, 1.0
	v_fma_f32 v66, -v57, v62, 1.0
	v_fmac_f32_e32 v61, v65, v61
	v_mul_f32_e32 v64, v54, v60
	v_fma_f32 v67, -v30, v63, v31
	v_div_scale_f32 v58, s[8:9], 1.0, v32, 1.0
	v_fmac_f32_e32 v62, v66, v62
	v_mul_f32_e32 v65, v56, v61
	v_fma_f32 v68, -v53, v64, v54
	v_fmac_f32_e32 v63, v67, v59
	v_mul_f32_e32 v66, v58, v62
	v_fma_f32 v69, -v55, v65, v56
	v_fmac_f32_e32 v64, v68, v60
	v_fma_f32 v30, -v30, v63, v31
	v_fma_f32 v70, -v57, v66, v58
	v_fmac_f32_e32 v65, v69, v61
	v_fma_f32 v31, -v53, v64, v54
	v_div_fmas_f32 v30, v30, v59, v63
	s_mov_b64 vcc, s[4:5]
	v_fmac_f32_e32 v66, v70, v62
	v_fma_f32 v53, -v55, v65, v56
	v_div_fixup_f32 v27, v30, v27, 1.0
	v_div_fmas_f32 v30, v31, v60, v64
	s_mov_b64 vcc, s[6:7]
	v_fma_f32 v54, -v57, v66, v58
	v_div_fixup_f32 v26, v30, v26, 1.0
	v_div_fmas_f32 v53, v53, v61, v65
	s_mov_b64 vcc, s[8:9]
	v_pk_fma_f32 v[30:31], v[26:27], v[48:49], v[34:35]
	v_div_fmas_f32 v26, v54, v62, v66
	v_and_b32_e32 v47, 0xffff0000, v47
	v_div_fixup_f32 v27, v53, v33, 1.0
	v_div_fixup_f32 v26, v26, v32, 1.0
	v_pk_fma_f32 v[32:33], v[26:27], v[46:47], v[36:37]
	global_store_dwordx4 v[40:41], v[30:33], off
	v_cvt_pk_bf16_f32 v34, v30, v31
	v_cvt_pk_bf16_f32 v35, v32, v33
	s_nop 0
	v_mul_f32_e32 v28, v28, v50
	v_mov_b32_e32 v238, v34
	v_mov_b32_e32 v239, v35
	s_nop 0
	v_mul_f32_e32 v29, v29, v50
	v_mul_f32_e32 v47, v23, v50
	v_mul_f32_e32 v53, v18, v50
	v_mul_f32_e32 v18, 0xbfb8aa3b, v51
	v_mul_f32_e32 v23, 0xbfb8aa3b, v52
	v_mul_f32_e32 v46, v22, v50
	v_mul_f32_e32 v48, v24, v50
	v_mul_f32_e32 v49, v25, v50
	v_mul_f32_e32 v24, 0xbfb8aa3b, v28
	v_mul_f32_e32 v25, 0xbfb8aa3b, v29
	v_exp_f32_e32 v22, v18
	v_exp_f32_e32 v23, v23
	v_exp_f32_e32 v24, v24
	v_exp_f32_e32 v25, v25
	v_mul_f32_e32 v51, v19, v50
	v_pk_add_f32 v[18:19], v[22:23], 1.0 op_sel_hi:[1,0]
	v_mul_f32_e32 v20, v20, v50
	v_pk_add_f32 v[22:23], v[24:25], 1.0 op_sel_hi:[1,0]
	v_div_scale_f32 v24, s[4:5], v19, v19, 1.0
	v_div_scale_f32 v28, s[4:5], v18, v18, 1.0
	v_rcp_f32_e32 v57, v24
	v_div_scale_f32 v52, s[6:7], v23, v23, 1.0
	v_rcp_f32_e32 v58, v28
	v_div_scale_f32 v55, s[8:9], v22, v22, 1.0
	v_rcp_f32_e32 v59, v52
	v_rcp_f32_e32 v60, v55
	v_fma_f32 v61, -v24, v57, 1.0
	v_div_scale_f32 v25, vcc, 1.0, v19, 1.0
	v_fma_f32 v62, -v28, v58, 1.0
	v_fmac_f32_e32 v57, v61, v57
	v_div_scale_f32 v29, s[4:5], 1.0, v18, 1.0
	v_fma_f32 v63, -v52, v59, 1.0
	v_fmac_f32_e32 v58, v62, v58
	v_mul_f32_e32 v61, v25, v57
	v_div_scale_f32 v54, s[6:7], 1.0, v23, 1.0
	v_fma_f32 v64, -v55, v60, 1.0
	v_fmac_f32_e32 v59, v63, v59
	v_mul_f32_e32 v62, v29, v58
	v_fma_f32 v65, -v24, v61, v25
	v_div_scale_f32 v56, s[8:9], 1.0, v22, 1.0
	v_fmac_f32_e32 v60, v64, v60
	v_mul_f32_e32 v63, v54, v59
	v_fma_f32 v66, -v28, v62, v29
	v_fmac_f32_e32 v61, v65, v57
	v_mul_f32_e32 v64, v56, v60
	v_fma_f32 v67, -v52, v63, v54
	v_fmac_f32_e32 v62, v66, v58
	v_fma_f32 v24, -v24, v61, v25
	v_fma_f32 v68, -v55, v64, v56
	v_fmac_f32_e32 v63, v67, v59
	v_fma_f32 v25, -v28, v62, v29
	v_div_fmas_f32 v24, v24, v57, v61
	s_mov_b64 vcc, s[4:5]
	v_fmac_f32_e32 v64, v68, v60
	v_fma_f32 v28, -v52, v63, v54
	v_div_fixup_f32 v19, v24, v19, 1.0
	v_div_fmas_f32 v24, v25, v58, v62
	s_mov_b64 vcc, s[6:7]
	v_fma_f32 v29, -v55, v64, v56
	v_div_fixup_f32 v18, v24, v18, 1.0
	v_div_fmas_f32 v24, v28, v59, v63
	s_mov_b64 vcc, s[8:9]
	v_div_fixup_f32 v25, v24, v23, 1.0
	v_div_fmas_f32 v23, v29, v60, v64
	v_div_fixup_f32 v24, v23, v22, 1.0
	v_mul_f32_e32 v21, v21, v50
	v_pk_mul_f32 v[30:31], v[30:31], v[30:31]
	s_waitcnt lgkmcnt(0)
	v_mov_b32_e32 v26, v198
	v_mov_b32_e32 v27, v199
	v_mov_b32_e32 v34, v184
	v_mov_b32_e32 v35, v185
	v_mov_b32_e32 v36, v186
	v_mov_b32_e32 v37, v187
	v_lshlrev_b32_e32 v22, 16, v26
	v_and_b32_e32 v23, 0xffff0000, v26
	v_lshlrev_b32_e32 v26, 16, v27
	v_and_b32_e32 v27, 0xffff0000, v27
	v_pk_fma_f32 v[22:23], v[18:19], v[22:23], v[34:35]
	v_pk_fma_f32 v[24:25], v[24:25], v[26:27], v[36:37]
	global_store_dwordx4 v[40:41], v[22:25], off offset:64
	v_cvt_pk_bf16_f32 v26, v22, v23
	v_cvt_pk_bf16_f32 v27, v24, v25
	s_nop 0
	v_mul_f32_e32 v34, 0xbfb8aa3b, v46
	v_mov_b32_e32 v240, v26
	v_mov_b32_e32 v241, v27
	v_mbcnt_lo_u32_b32 v242, -1, 0
	v_mbcnt_hi_u32_b32 v242, -1, v242
	v_and_b32_e32 v242, 16, v242
	v_lshrrev_b32_e32 v236, 1, v242
	v_add_u32_e32 v242, v242, v236
	v_mov_b32_e32 v243, 0
	v_lshl_add_u64 v[236:237], v[42:43], 0, v[242:243]
	v_permlane16_swap_b32_e32 v238, v240
	v_permlane16_swap_b32_e32 v239, v241
	global_store_dwordx4 v[236:237], v[238:241], off
	s_nop 0
	v_mul_f32_e32 v35, 0xbfb8aa3b, v47
	v_mul_f32_e32 v36, 0xbfb8aa3b, v48
	v_mul_f32_e32 v37, 0xbfb8aa3b, v49
	v_mul_f32_e32 v48, 0xbfb8aa3b, v20
	v_mul_f32_e32 v49, 0xbfb8aa3b, v21
	v_exp_f32_e32 v20, v34
	v_exp_f32_e32 v21, v35
	v_exp_f32_e32 v34, v36
	v_exp_f32_e32 v35, v37
	v_mul_f32_e32 v46, 0xbfb8aa3b, v53
	v_pk_add_f32 v[20:21], v[20:21], 1.0 op_sel_hi:[1,0]
	v_exp_f32_e32 v36, v46
	v_exp_f32_e32 v46, v48
	v_div_scale_f32 v48, s[4:5], v21, v21, 1.0
	v_pk_add_f32 v[34:35], v[34:35], 1.0 op_sel_hi:[1,0]
	v_div_scale_f32 v50, s[4:5], v20, v20, 1.0
	v_rcp_f32_e32 v56, v48
	v_div_scale_f32 v52, s[6:7], v35, v35, 1.0
	v_rcp_f32_e32 v57, v50
	v_div_scale_f32 v54, s[8:9], v34, v34, 1.0
	v_rcp_f32_e32 v58, v52
	v_rcp_f32_e32 v59, v54
	v_mul_f32_e32 v47, 0xbfb8aa3b, v51
	v_fma_f32 v60, -v48, v56, 1.0
	v_exp_f32_e32 v37, v47
	v_exp_f32_e32 v47, v49
	v_div_scale_f32 v49, vcc, 1.0, v21, 1.0
	v_fma_f32 v61, -v50, v57, 1.0
	v_fmac_f32_e32 v56, v60, v56
	v_div_scale_f32 v51, s[4:5], 1.0, v20, 1.0
	v_fma_f32 v62, -v52, v58, 1.0
	v_fmac_f32_e32 v57, v61, v57
	v_mul_f32_e32 v60, v49, v56
	v_div_scale_f32 v53, s[6:7], 1.0, v35, 1.0
	v_fma_f32 v63, -v54, v59, 1.0
	v_fmac_f32_e32 v58, v62, v58
	v_mul_f32_e32 v61, v51, v57
	v_fma_f32 v64, -v48, v60, v49
	v_div_scale_f32 v55, s[8:9], 1.0, v34, 1.0
	v_fmac_f32_e32 v59, v63, v59
	v_mul_f32_e32 v62, v53, v58
	v_fma_f32 v65, -v50, v61, v51
	v_fmac_f32_e32 v60, v64, v56
	v_mul_f32_e32 v63, v55, v59
	v_fma_f32 v66, -v52, v62, v53
	v_fmac_f32_e32 v61, v65, v57
	v_fma_f32 v48, -v48, v60, v49
	v_fma_f32 v67, -v54, v63, v55
	v_fmac_f32_e32 v62, v66, v58
	v_fma_f32 v49, -v50, v61, v51
	v_div_fmas_f32 v48, v48, v56, v60
	s_mov_b64 vcc, s[4:5]
	v_fmac_f32_e32 v63, v67, v59
	v_fma_f32 v50, -v52, v62, v53
	v_div_fixup_f32 v21, v48, v21, 1.0
	v_div_fmas_f32 v48, v49, v57, v61
	s_mov_b64 vcc, s[6:7]
	v_fma_f32 v51, -v54, v63, v55
	v_div_fixup_f32 v20, v48, v20, 1.0
	v_div_fmas_f32 v48, v50, v58, v62
	s_mov_b64 vcc, s[8:9]
	v_div_fixup_f32 v35, v48, v35, 1.0
	v_div_fmas_f32 v48, v51, v59, v63
	v_div_fixup_f32 v34, v48, v34, 1.0
	v_pk_add_f32 v[36:37], v[36:37], 1.0 op_sel_hi:[1,0]
	v_pk_mul_f32 v[22:23], v[22:23], v[22:23]
	v_pk_mul_f32 v[24:25], v[24:25], v[24:25]
	v_add_f32_e32 v22, v22, v23
	s_waitcnt lgkmcnt(0)
	v_mov_b32_e32 v18, v200
	v_mov_b32_e32 v19, v201
	v_mov_b32_e32 v26, v188
	v_mov_b32_e32 v27, v189
	v_mov_b32_e32 v28, v190
	v_mov_b32_e32 v29, v191
	v_lshlrev_b32_e32 v48, 16, v18
	v_and_b32_e32 v49, 0xffff0000, v18
	v_lshlrev_b32_e32 v50, 16, v19
	v_and_b32_e32 v51, 0xffff0000, v19
	v_pk_fma_f32 v[18:19], v[20:21], v[48:49], v[26:27]
	v_pk_fma_f32 v[20:21], v[34:35], v[50:51], v[28:29]
	global_store_dwordx4 v[40:41], v[18:21], off offset:128
	v_cvt_pk_bf16_f32 v26, v18, v19
	v_cvt_pk_bf16_f32 v27, v20, v21
	s_nop 0
	v_pk_add_f32 v[44:45], v[46:47], 1.0 op_sel_hi:[1,0]
	v_mov_b32_e32 v238, v26
	v_mov_b32_e32 v239, v27
	s_nop 0
	v_div_scale_f32 v46, s[4:5], v37, v37, 1.0
	v_div_scale_f32 v48, s[4:5], v36, v36, 1.0
	v_div_scale_f32 v50, s[6:7], v45, v45, 1.0
	v_rcp_f32_e32 v54, v46
	v_rcp_f32_e32 v55, v48
	v_rcp_f32_e32 v56, v50
	v_div_scale_f32 v52, s[8:9], v44, v44, 1.0
	v_rcp_f32_e32 v57, v52
	v_fma_f32 v58, -v46, v54, 1.0
	v_fma_f32 v59, -v48, v55, 1.0
	v_fma_f32 v60, -v50, v56, 1.0
	v_div_scale_f32 v47, vcc, 1.0, v37, 1.0
	v_div_scale_f32 v49, s[4:5], 1.0, v36, 1.0
	v_div_scale_f32 v51, s[6:7], 1.0, v45, 1.0
	v_fmac_f32_e32 v54, v58, v54
	v_fmac_f32_e32 v55, v59, v55
	v_fmac_f32_e32 v56, v60, v56
	v_mul_f32_e32 v58, v47, v54
	v_mul_f32_e32 v59, v49, v55
	v_mul_f32_e32 v60, v51, v56
	v_fma_f32 v62, -v46, v58, v47
	v_fma_f32 v63, -v48, v59, v49
	v_fma_f32 v64, -v50, v60, v51
	v_fma_f32 v61, -v52, v57, 1.0
	v_fmac_f32_e32 v58, v62, v54
	v_fmac_f32_e32 v59, v63, v55
	v_fmac_f32_e32 v60, v64, v56
	v_div_scale_f32 v53, s[8:9], 1.0, v44, 1.0
	v_fmac_f32_e32 v57, v61, v57
	v_fma_f32 v46, -v46, v58, v47
	v_fma_f32 v47, -v48, v59, v49
	v_fma_f32 v48, -v50, v60, v51
	v_add_f32_e32 v50, v30, v31
	v_pk_mul_f32 v[30:31], v[32:33], v[32:33]
	v_mul_f32_e32 v61, v53, v57
	v_add_f32_e32 v30, v30, v50
	v_fma_f32 v65, -v52, v61, v53
	v_add_f32_e32 v50, v31, v30
	v_div_fmas_f32 v30, v46, v54, v58
	s_mov_b64 vcc, s[4:5]
	v_pk_mul_f32 v[18:19], v[18:19], v[18:19]
	v_fmac_f32_e32 v61, v65, v57
	v_div_fixup_f32 v31, v30, v37, 1.0
	v_div_fmas_f32 v30, v47, v55, v59
	s_mov_b64 vcc, s[6:7]
	v_pk_mul_f32 v[20:21], v[20:21], v[20:21]
	v_add_f32_e32 v18, v18, v19
	v_fma_f32 v49, -v52, v61, v53
	v_div_fmas_f32 v32, v48, v56, v60
	s_mov_b64 vcc, s[8:9]
	v_add_f32_e32 v22, v24, v22
	v_add_f32_e32 v18, v20, v18
	v_div_fixup_f32 v30, v30, v36, 1.0
	v_div_fixup_f32 v33, v32, v45, 1.0
	v_div_fmas_f32 v32, v49, v57, v61
	v_add_f32_e32 v22, v25, v22
	v_add_f32_e32 v37, v21, v18
	v_div_fixup_f32 v32, v32, v44, 1.0
	v_add_f32_e32 v36, v50, v22
	s_waitcnt lgkmcnt(0)
	v_mov_b32_e32 v34, v202
	v_mov_b32_e32 v35, v203
	v_mov_b32_e32 v26, v192
	v_mov_b32_e32 v27, v193
	v_mov_b32_e32 v28, v194
	v_mov_b32_e32 v29, v195
	v_lshlrev_b32_e32 v18, 16, v34
	v_and_b32_e32 v19, 0xffff0000, v34
	v_lshlrev_b32_e32 v22, 16, v35
	v_and_b32_e32 v23, 0xffff0000, v35
	v_pk_fma_f32 v[20:21], v[30:31], v[18:19], v[26:27]
	v_pk_fma_f32 v[22:23], v[32:33], v[22:23], v[28:29]
	v_pk_mul_f32 v[18:19], v[20:21], v[20:21]
	v_pk_mul_f32 v[24:25], v[22:23], v[22:23]
	v_add_f32_e32 v18, v18, v19
	v_add_f32_e32 v18, v24, v18
	v_add_f32_e32 v26, v36, v37
	v_add_f32_e32 v18, v25, v18
	v_add_f32_e32 v18, v26, v18
	ds_bpermute_b32 v19, v126, v18
	global_store_dwordx4 v[40:41], v[20:23], off offset:192
	s_waitcnt lgkmcnt(0)
	v_add_f32_e32 v18, v18, v19
	ds_bpermute_b32 v19, v127, v18
	v_cvt_pk_bf16_f32 v20, v20, v21
	v_cvt_pk_bf16_f32 v21, v22, v23
	v_mov_b32_e32 v240, v20
	v_mov_b32_e32 v241, v21
	s_nop 1
	v_lshl_add_u64 v[236:237], v[42:43], 0, v[242:243]
	v_permlane16_swap_b32_e32 v238, v240
	v_permlane16_swap_b32_e32 v239, v241
	global_store_dwordx4 v[236:237], v[238:241], off offset:64
	s_and_saveexec_b64 s[4:5], s[0:1]
	s_cbranch_execz .LBB0_636
	s_waitcnt lgkmcnt(0)
	v_add_f32_e32 v20, v18, v19
	v_lshl_add_u64 v[18:19], v[38:39], 2, s[20:21]
	global_atomic_add_f32 v[18:19], v20, off
.LBB0_636:
	s_or_b64 exec, exec, s[4:5]
	v_or_b32_e32 v140, 0x70, v140
	s_waitcnt lgkmcnt(0)
	v_lshl_add_u64 v[18:19], v[140:141], 2, s[18:19]
	s_nop 0
	v_lshlrev_b64 v[18:19], 11, v[140:141]
	v_lshl_add_u64 v[20:21], s[14:15], 0, v[18:19]
	v_lshl_add_u64 v[26:27], v[20:21], 0, v[142:143]
	v_lshlrev_b64 v[20:21], 12, v[140:141]
	v_lshl_add_u64 v[20:21], v[134:135], 0, v[20:21]
	s_nop 0
	v_lshl_add_u64 v[18:19], s[16:17], 0, v[18:19]
	v_lshl_add_u64 v[22:23], v[20:21], 0, v[138:139]
	v_lshl_add_u64 v[24:25], v[18:19], 0, v[142:143]
	s_nop 0
	s_waitcnt vmcnt(6) lgkmcnt(0)
	v_mov_b32_e32 v30, v229
	v_mov_b32_e32 v28, v220
	v_mov_b32_e32 v29, v221
	v_mov_b32_e32 v18, v204
	v_mov_b32_e32 v19, v205
	v_mov_b32_e32 v20, v206
	v_mov_b32_e32 v21, v207
	v_fmamk_f32 v30, v30, 0x3a800000, v153
	v_mul_f32_e32 v31, 0x4b800000, v30
	v_cmp_gt_f32_e32 vcc, s56, v30
	s_nop 1
	v_cndmask_b32_e32 v31, v30, v31, vcc
	v_rsq_f32_e32 v32, v31
	v_lshlrev_b32_e32 v30, 16, v28
	v_and_b32_e32 v31, 0xffff0000, v28
	v_lshlrev_b32_e32 v28, 16, v29
	v_mul_f32_e32 v33, 0x45800000, v32
	v_cndmask_b32_e32 v32, v32, v33, vcc
	v_mul_f32_e32 v14, v14, v32
	v_mul_f32_e32 v15, v15, v32
	v_mul_f32_e32 v14, 0xbfb8aa3b, v14
	v_mul_f32_e32 v15, 0xbfb8aa3b, v15
	v_mul_f32_e32 v16, v16, v32
	v_mul_f32_e32 v17, v17, v32
	v_exp_f32_e32 v14, v14
	v_exp_f32_e32 v15, v15
	v_mul_f32_e32 v16, 0xbfb8aa3b, v16
	v_mul_f32_e32 v17, 0xbfb8aa3b, v17
	v_exp_f32_e32 v16, v16
	v_exp_f32_e32 v17, v17
	v_mul_f32_e32 v33, v10, v32
	v_mul_f32_e32 v34, v11, v32
	v_pk_add_f32 v[10:11], v[14:15], 1.0 op_sel_hi:[1,0]
	v_pk_add_f32 v[16:17], v[16:17], 1.0 op_sel_hi:[1,0]
	v_div_scale_f32 v14, s[4:5], v11, v11, 1.0
	v_div_scale_f32 v35, s[4:5], v10, v10, 1.0
	v_rcp_f32_e32 v41, v14
	v_div_scale_f32 v37, s[6:7], v17, v17, 1.0
	v_rcp_f32_e32 v42, v35
	v_div_scale_f32 v39, s[8:9], v16, v16, 1.0
	v_rcp_f32_e32 v43, v37
	v_rcp_f32_e32 v44, v39
	v_fma_f32 v45, -v14, v41, 1.0
	v_div_scale_f32 v15, vcc, 1.0, v11, 1.0
	v_fma_f32 v46, -v35, v42, 1.0
	v_fmac_f32_e32 v41, v45, v41
	v_div_scale_f32 v36, s[4:5], 1.0, v10, 1.0
	v_fma_f32 v47, -v37, v43, 1.0
	v_fmac_f32_e32 v42, v46, v42
	v_mul_f32_e32 v45, v15, v41
	v_div_scale_f32 v38, s[6:7], 1.0, v17, 1.0
	v_fma_f32 v48, -v39, v44, 1.0
	v_fmac_f32_e32 v43, v47, v43
	v_mul_f32_e32 v46, v36, v42
	v_fma_f32 v49, -v14, v45, v15
	v_div_scale_f32 v40, s[8:9], 1.0, v16, 1.0
	v_fmac_f32_e32 v44, v48, v44
	v_mul_f32_e32 v47, v38, v43
	v_fma_f32 v50, -v35, v46, v36
	v_fmac_f32_e32 v45, v49, v41
	v_mul_f32_e32 v48, v40, v44
	v_fma_f32 v51, -v37, v47, v38
	v_fmac_f32_e32 v46, v50, v42
	v_fma_f32 v14, -v14, v45, v15
	v_fma_f32 v52, -v39, v48, v40
	v_fmac_f32_e32 v47, v51, v43
	v_fma_f32 v15, -v35, v46, v36
	v_div_fmas_f32 v14, v14, v41, v45
	s_mov_b64 vcc, s[4:5]
	v_fmac_f32_e32 v48, v52, v44
	v_fma_f32 v35, -v37, v47, v38
	v_div_fixup_f32 v11, v14, v11, 1.0
	v_div_fmas_f32 v14, v15, v42, v46
	s_mov_b64 vcc, s[6:7]
	v_fma_f32 v36, -v39, v48, v40
	v_div_fixup_f32 v10, v14, v10, 1.0
	v_div_fmas_f32 v35, v35, v43, v47
	s_mov_b64 vcc, s[8:9]
	v_pk_fma_f32 v[14:15], v[10:11], v[30:31], v[18:19]
	v_div_fmas_f32 v10, v36, v44, v48
	v_and_b32_e32 v29, 0xffff0000, v29
	v_div_fixup_f32 v11, v35, v17, 1.0
	v_div_fixup_f32 v10, v10, v16, 1.0
	v_pk_fma_f32 v[16:17], v[10:11], v[28:29], v[20:21]
	global_store_dwordx4 v[22:23], v[14:17], off
	v_cvt_pk_bf16_f32 v18, v14, v15
	v_cvt_pk_bf16_f32 v19, v16, v17
	s_nop 0
	v_mul_f32_e32 v12, v12, v32
	v_mov_b32_e32 v238, v18
	v_mov_b32_e32 v239, v19
	s_nop 0
	v_mul_f32_e32 v13, v13, v32
	v_mul_f32_e32 v29, v7, v32
	v_mul_f32_e32 v35, v2, v32
	v_mul_f32_e32 v2, 0xbfb8aa3b, v33
	v_mul_f32_e32 v7, 0xbfb8aa3b, v34
	v_mul_f32_e32 v28, v6, v32
	v_mul_f32_e32 v30, v8, v32
	v_mul_f32_e32 v31, v9, v32
	v_mul_f32_e32 v8, 0xbfb8aa3b, v12
	v_mul_f32_e32 v9, 0xbfb8aa3b, v13
	v_exp_f32_e32 v6, v2
	v_exp_f32_e32 v7, v7
	v_exp_f32_e32 v8, v8
	v_exp_f32_e32 v9, v9
	v_mul_f32_e32 v33, v3, v32
	v_pk_add_f32 v[2:3], v[6:7], 1.0 op_sel_hi:[1,0]
	v_mul_f32_e32 v4, v4, v32
	v_pk_add_f32 v[6:7], v[8:9], 1.0 op_sel_hi:[1,0]
	v_div_scale_f32 v8, s[4:5], v3, v3, 1.0
	v_div_scale_f32 v12, s[4:5], v2, v2, 1.0
	v_rcp_f32_e32 v39, v8
	v_div_scale_f32 v34, s[6:7], v7, v7, 1.0
	v_rcp_f32_e32 v40, v12
	v_div_scale_f32 v37, s[8:9], v6, v6, 1.0
	v_rcp_f32_e32 v41, v34
	v_rcp_f32_e32 v42, v37
	v_fma_f32 v43, -v8, v39, 1.0
	v_div_scale_f32 v9, vcc, 1.0, v3, 1.0
	v_fma_f32 v44, -v12, v40, 1.0
	v_fmac_f32_e32 v39, v43, v39
	v_div_scale_f32 v13, s[4:5], 1.0, v2, 1.0
	v_fma_f32 v45, -v34, v41, 1.0
	v_fmac_f32_e32 v40, v44, v40
	v_mul_f32_e32 v43, v9, v39
	v_div_scale_f32 v36, s[6:7], 1.0, v7, 1.0
	v_fma_f32 v46, -v37, v42, 1.0
	v_fmac_f32_e32 v41, v45, v41
	v_mul_f32_e32 v44, v13, v40
	v_fma_f32 v47, -v8, v43, v9
	v_div_scale_f32 v38, s[8:9], 1.0, v6, 1.0
	v_fmac_f32_e32 v42, v46, v42
	v_mul_f32_e32 v45, v36, v41
	v_fma_f32 v48, -v12, v44, v13
	v_fmac_f32_e32 v43, v47, v39
	v_mul_f32_e32 v46, v38, v42
	v_fma_f32 v49, -v34, v45, v36
	v_fmac_f32_e32 v44, v48, v40
	v_fma_f32 v8, -v8, v43, v9
	v_fma_f32 v50, -v37, v46, v38
	v_fmac_f32_e32 v45, v49, v41
	v_fma_f32 v9, -v12, v44, v13
	v_div_fmas_f32 v8, v8, v39, v43
	s_mov_b64 vcc, s[4:5]
	v_fmac_f32_e32 v46, v50, v42
	v_fma_f32 v12, -v34, v45, v36
	v_div_fixup_f32 v3, v8, v3, 1.0
	v_div_fmas_f32 v8, v9, v40, v44
	s_mov_b64 vcc, s[6:7]
	v_fma_f32 v13, -v37, v46, v38
	v_div_fixup_f32 v2, v8, v2, 1.0
	v_div_fmas_f32 v8, v12, v41, v45
	s_mov_b64 vcc, s[8:9]
	v_div_fixup_f32 v9, v8, v7, 1.0
	v_div_fmas_f32 v7, v13, v42, v46
	v_div_fixup_f32 v8, v7, v6, 1.0
	v_mul_f32_e32 v5, v5, v32
	v_pk_mul_f32 v[14:15], v[14:15], v[14:15]
	s_waitcnt lgkmcnt(0)
	v_mov_b32_e32 v10, v222
	v_mov_b32_e32 v11, v223
	v_mov_b32_e32 v18, v208
	v_mov_b32_e32 v19, v209
	v_mov_b32_e32 v20, v210
	v_mov_b32_e32 v21, v211
	v_lshlrev_b32_e32 v6, 16, v10
	v_and_b32_e32 v7, 0xffff0000, v10
	v_lshlrev_b32_e32 v10, 16, v11
	v_and_b32_e32 v11, 0xffff0000, v11
	v_pk_fma_f32 v[6:7], v[2:3], v[6:7], v[18:19]
	v_pk_fma_f32 v[8:9], v[8:9], v[10:11], v[20:21]
	global_store_dwordx4 v[22:23], v[6:9], off offset:64
	v_cvt_pk_bf16_f32 v10, v6, v7
	v_cvt_pk_bf16_f32 v11, v8, v9
	s_nop 0
	v_mul_f32_e32 v18, 0xbfb8aa3b, v28
	v_mov_b32_e32 v240, v10
	v_mov_b32_e32 v241, v11
	v_mbcnt_lo_u32_b32 v242, -1, 0
	v_mbcnt_hi_u32_b32 v242, -1, v242
	v_and_b32_e32 v242, 16, v242
	v_lshrrev_b32_e32 v236, 1, v242
	v_add_u32_e32 v242, v242, v236
	v_mov_b32_e32 v243, 0
	v_lshl_add_u64 v[236:237], v[24:25], 0, v[242:243]
	v_permlane16_swap_b32_e32 v238, v240
	v_permlane16_swap_b32_e32 v239, v241
	global_store_dwordx4 v[236:237], v[238:241], off
	s_nop 0
	v_mul_f32_e32 v19, 0xbfb8aa3b, v29
	v_mul_f32_e32 v20, 0xbfb8aa3b, v30
	v_mul_f32_e32 v21, 0xbfb8aa3b, v31
	v_mul_f32_e32 v30, 0xbfb8aa3b, v4
	v_mul_f32_e32 v31, 0xbfb8aa3b, v5
	v_exp_f32_e32 v4, v18
	v_exp_f32_e32 v5, v19
	v_exp_f32_e32 v18, v20
	v_exp_f32_e32 v19, v21
	v_mul_f32_e32 v28, 0xbfb8aa3b, v35
	v_pk_add_f32 v[4:5], v[4:5], 1.0 op_sel_hi:[1,0]
	v_exp_f32_e32 v20, v28
	v_exp_f32_e32 v28, v30
	v_div_scale_f32 v30, s[4:5], v5, v5, 1.0
	v_pk_add_f32 v[18:19], v[18:19], 1.0 op_sel_hi:[1,0]
	v_div_scale_f32 v32, s[4:5], v4, v4, 1.0
	v_rcp_f32_e32 v38, v30
	v_div_scale_f32 v34, s[6:7], v19, v19, 1.0
	v_rcp_f32_e32 v39, v32
	v_div_scale_f32 v36, s[8:9], v18, v18, 1.0
	v_rcp_f32_e32 v40, v34
	v_rcp_f32_e32 v41, v36
	v_mul_f32_e32 v29, 0xbfb8aa3b, v33
	v_fma_f32 v42, -v30, v38, 1.0
	v_exp_f32_e32 v21, v29
	v_exp_f32_e32 v29, v31
	v_div_scale_f32 v31, vcc, 1.0, v5, 1.0
	v_fma_f32 v43, -v32, v39, 1.0
	v_fmac_f32_e32 v38, v42, v38
	v_div_scale_f32 v33, s[4:5], 1.0, v4, 1.0
	v_fma_f32 v44, -v34, v40, 1.0
	v_fmac_f32_e32 v39, v43, v39
	v_mul_f32_e32 v42, v31, v38
	v_div_scale_f32 v35, s[6:7], 1.0, v19, 1.0
	v_fma_f32 v45, -v36, v41, 1.0
	v_fmac_f32_e32 v40, v44, v40
	v_mul_f32_e32 v43, v33, v39
	v_fma_f32 v46, -v30, v42, v31
	v_div_scale_f32 v37, s[8:9], 1.0, v18, 1.0
	v_fmac_f32_e32 v41, v45, v41
	v_mul_f32_e32 v44, v35, v40
	v_fma_f32 v47, -v32, v43, v33
	v_fmac_f32_e32 v42, v46, v38
	v_mul_f32_e32 v45, v37, v41
	v_fma_f32 v48, -v34, v44, v35
	v_fmac_f32_e32 v43, v47, v39
	v_fma_f32 v30, -v30, v42, v31
	v_fma_f32 v49, -v36, v45, v37
	v_fmac_f32_e32 v44, v48, v40
	v_fma_f32 v31, -v32, v43, v33
	v_div_fmas_f32 v30, v30, v38, v42
	s_mov_b64 vcc, s[4:5]
	v_fmac_f32_e32 v45, v49, v41
	v_fma_f32 v32, -v34, v44, v35
	v_div_fixup_f32 v5, v30, v5, 1.0
	v_div_fmas_f32 v30, v31, v39, v43
	s_mov_b64 vcc, s[6:7]
	v_fma_f32 v33, -v36, v45, v37
	v_div_fixup_f32 v4, v30, v4, 1.0
	v_div_fmas_f32 v30, v32, v40, v44
	s_mov_b64 vcc, s[8:9]
	v_div_fixup_f32 v19, v30, v19, 1.0
	v_div_fmas_f32 v30, v33, v41, v45
	v_div_fixup_f32 v18, v30, v18, 1.0
	v_pk_add_f32 v[20:21], v[20:21], 1.0 op_sel_hi:[1,0]
	v_pk_mul_f32 v[6:7], v[6:7], v[6:7]
	v_pk_mul_f32 v[8:9], v[8:9], v[8:9]
	v_add_f32_e32 v6, v6, v7
	s_waitcnt lgkmcnt(0)
	v_mov_b32_e32 v2, v224
	v_mov_b32_e32 v3, v225
	v_mov_b32_e32 v10, v212
	v_mov_b32_e32 v11, v213
	v_mov_b32_e32 v12, v214
	v_mov_b32_e32 v13, v215
	v_lshlrev_b32_e32 v30, 16, v2
	v_and_b32_e32 v31, 0xffff0000, v2
	v_lshlrev_b32_e32 v32, 16, v3
	v_and_b32_e32 v33, 0xffff0000, v3
	v_pk_fma_f32 v[2:3], v[4:5], v[30:31], v[10:11]
	v_pk_fma_f32 v[4:5], v[18:19], v[32:33], v[12:13]
	global_store_dwordx4 v[22:23], v[2:5], off offset:128
	v_cvt_pk_bf16_f32 v10, v2, v3
	v_cvt_pk_bf16_f32 v11, v4, v5
	s_nop 0
	v_pk_add_f32 v[26:27], v[28:29], 1.0 op_sel_hi:[1,0]
	v_mov_b32_e32 v238, v10
	v_mov_b32_e32 v239, v11
	s_nop 0
	v_div_scale_f32 v28, s[4:5], v21, v21, 1.0
	v_div_scale_f32 v30, s[4:5], v20, v20, 1.0
	v_div_scale_f32 v32, s[6:7], v27, v27, 1.0
	v_rcp_f32_e32 v36, v28
	v_rcp_f32_e32 v37, v30
	v_rcp_f32_e32 v38, v32
	v_div_scale_f32 v34, s[8:9], v26, v26, 1.0
	v_rcp_f32_e32 v39, v34
	v_fma_f32 v40, -v28, v36, 1.0
	v_fma_f32 v41, -v30, v37, 1.0
	v_fma_f32 v42, -v32, v38, 1.0
	v_div_scale_f32 v29, vcc, 1.0, v21, 1.0
	v_div_scale_f32 v31, s[4:5], 1.0, v20, 1.0
	v_div_scale_f32 v33, s[6:7], 1.0, v27, 1.0
	v_fmac_f32_e32 v36, v40, v36
	v_fmac_f32_e32 v37, v41, v37
	v_fmac_f32_e32 v38, v42, v38
	v_mul_f32_e32 v40, v29, v36
	v_mul_f32_e32 v41, v31, v37
	v_mul_f32_e32 v42, v33, v38
	v_fma_f32 v44, -v28, v40, v29
	v_fma_f32 v45, -v30, v41, v31
	v_fma_f32 v46, -v32, v42, v33
	v_fma_f32 v43, -v34, v39, 1.0
	v_fmac_f32_e32 v40, v44, v36
	v_fmac_f32_e32 v41, v45, v37
	v_fmac_f32_e32 v42, v46, v38
	v_div_scale_f32 v35, s[8:9], 1.0, v26, 1.0
	v_fmac_f32_e32 v39, v43, v39
	v_fma_f32 v28, -v28, v40, v29
	v_fma_f32 v29, -v30, v41, v31
	v_fma_f32 v30, -v32, v42, v33
	v_add_f32_e32 v32, v14, v15
	v_pk_mul_f32 v[14:15], v[16:17], v[16:17]
	v_mul_f32_e32 v43, v35, v39
	v_add_f32_e32 v14, v14, v32
	v_fma_f32 v47, -v34, v43, v35
	v_add_f32_e32 v32, v15, v14
	v_div_fmas_f32 v14, v28, v36, v40
	s_mov_b64 vcc, s[4:5]
	v_pk_mul_f32 v[2:3], v[2:3], v[2:3]
	v_fmac_f32_e32 v43, v47, v39
	v_div_fixup_f32 v15, v14, v21, 1.0
	v_div_fmas_f32 v14, v29, v37, v41
	s_mov_b64 vcc, s[6:7]
	v_pk_mul_f32 v[4:5], v[4:5], v[4:5]
	v_add_f32_e32 v2, v2, v3
	v_fma_f32 v31, -v34, v43, v35
	v_div_fmas_f32 v16, v30, v38, v42
	s_mov_b64 vcc, s[8:9]
	v_add_f32_e32 v6, v8, v6
	v_add_f32_e32 v2, v4, v2
	v_div_fixup_f32 v14, v14, v20, 1.0
	v_div_fixup_f32 v17, v16, v27, 1.0
	v_div_fmas_f32 v16, v31, v39, v43
	v_add_f32_e32 v6, v9, v6
	v_add_f32_e32 v21, v5, v2
	v_div_fixup_f32 v16, v16, v26, 1.0
	v_add_f32_e32 v20, v32, v6
	s_waitcnt lgkmcnt(0)
	v_mov_b32_e32 v18, v226
	v_mov_b32_e32 v19, v227
	v_mov_b32_e32 v10, v216
	v_mov_b32_e32 v11, v217
	v_mov_b32_e32 v12, v218
	v_mov_b32_e32 v13, v219
	v_lshlrev_b32_e32 v2, 16, v18
	v_and_b32_e32 v3, 0xffff0000, v18
	v_lshlrev_b32_e32 v6, 16, v19
	v_and_b32_e32 v7, 0xffff0000, v19
	v_pk_fma_f32 v[4:5], v[14:15], v[2:3], v[10:11]
	v_pk_fma_f32 v[6:7], v[16:17], v[6:7], v[12:13]
	v_pk_mul_f32 v[2:3], v[4:5], v[4:5]
	v_pk_mul_f32 v[8:9], v[6:7], v[6:7]
	v_add_f32_e32 v2, v2, v3
	v_add_f32_e32 v2, v8, v2
	v_add_f32_e32 v10, v20, v21
	v_add_f32_e32 v2, v9, v2
	v_add_f32_e32 v2, v10, v2
	ds_bpermute_b32 v3, v126, v2
	global_store_dwordx4 v[22:23], v[4:7], off offset:192
	s_waitcnt lgkmcnt(0)
	v_add_f32_e32 v2, v2, v3
	ds_bpermute_b32 v3, v127, v2
	v_cvt_pk_bf16_f32 v4, v4, v5
	v_cvt_pk_bf16_f32 v5, v6, v7
	v_mov_b32_e32 v240, v4
	v_mov_b32_e32 v241, v5
	s_nop 1
	v_lshl_add_u64 v[236:237], v[24:25], 0, v[242:243]
	v_permlane16_swap_b32_e32 v238, v240
	v_permlane16_swap_b32_e32 v239, v241
	global_store_dwordx4 v[236:237], v[238:241], off offset:64
	s_and_saveexec_b64 s[4:5], s[0:1]
	s_cbranch_execz .LBB0_619
	s_waitcnt lgkmcnt(0)
	v_add_f32_e32 v4, v2, v3
	v_lshl_add_u64 v[2:3], v[140:141], 2, s[20:21]
	global_atomic_add_f32 v[2:3], v4, off
	s_branch .LBB0_619
